# V pass sweeps with four row buffers (three row groups in flight behind the one being consumed); residual rows loaded after each sweep
# speedup vs baseline: 1.0274x; 1.0041x over previous
; DI void peer_item_v(const Params& p, int item) {
;     ...
; #pragma unroll 1
;   for (int ti = 0; ti < 8; ++ti) {
;     const size_t tok = (size_t)item * 32 + wave * 8 + ti;
;     const int e_lo = EG[tok * 128 + lane], e_hi = EG[tok * 128 + 64 + lane];
;     const int a_lo = __float_as_int(AG[tok * 128 + lane]), a_hi = __float_as_int(AG[tok * 128 + 64 + lane]);
;     float out[16];
; #pragma unroll
;     for (int i = 0; i < 16; ++i) out[i] = 0.f;
;     u32x4 vqa[8], vqb[8];
;     ...
;     V_ISSUE(vqa, 0)
.Lvq_item:
	s_lshl_b32 s14, s10, 5
	s_add_u32 s14, s14, s56
	s_lshl_b32 s13, s14, 9
	s_add_u32 s58, s2, s13
	s_addc_u32 s59, s3, 0
	s_add_u32 s60, s4, s13
	s_addc_u32 s61, s5, 0
	v_lshrrev_b32_e32 v250, 3, v249
	v_and_b32_e32 v251, 7, v249
	v_lshlrev_b32_e32 v250, 6, v250
	v_lshl_add_u32 v250, v251, 2, v250
	s_lshr_b32 s13, s68, 8
	s_mul_i32 s13, s13, 0x13f00
	s_lshl_b32 s15, s56, 9
	s_add_u32 s13, s13, s15
	s_add_u32 s13, s13, 32
	v_add_u32_e32 v250, s13, v250
	ds_read_b32 v128, v250 offset:0
	ds_read_b32 v129, v250 offset:32
	ds_read_b32 v130, v250 offset:32768
	ds_read_b32 v131, v250 offset:32800
	ds_read_b32 v132, v250 offset:512
	ds_read_b32 v133, v250 offset:544
	ds_read_b32 v134, v250 offset:33280
	ds_read_b32 v135, v250 offset:33312
	ds_read_b32 v136, v250 offset:1024
	ds_read_b32 v137, v250 offset:1056
	ds_read_b32 v138, v250 offset:33792
	ds_read_b32 v139, v250 offset:33824
	ds_read_b32 v140, v250 offset:1536
	ds_read_b32 v141, v250 offset:1568
	ds_read_b32 v142, v250 offset:34304
	ds_read_b32 v143, v250 offset:34336
	ds_read_b32 v144, v250 offset:2048
	ds_read_b32 v145, v250 offset:2080
	ds_read_b32 v146, v250 offset:34816
	ds_read_b32 v147, v250 offset:34848
	ds_read_b32 v148, v250 offset:2560
	ds_read_b32 v149, v250 offset:2592
	ds_read_b32 v150, v250 offset:35328
	ds_read_b32 v151, v250 offset:35360
	ds_read_b32 v152, v250 offset:3072
	ds_read_b32 v153, v250 offset:3104
	ds_read_b32 v154, v250 offset:35840
	ds_read_b32 v155, v250 offset:35872
	ds_read_b32 v156, v250 offset:3584
	ds_read_b32 v157, v250 offset:3616
	ds_read_b32 v158, v250 offset:36352
	ds_read_b32 v159, v250 offset:36384
	v_add_u32_e32 v160, s57, v241
	v_mov_b32_e32 v161, 0
	v_mov_b32_e32 v162, 1
	v_lshrrev_b32_e32 v163, 3, v249
	v_and_b32_e32 v164, 7, v249
	v_lshlrev_b32_e32 v163, 6, v163
	v_lshl_add_u32 v163, v164, 2, v163
	v_add_u32_e32 v163, s57, v163
	v_add_u32_e32 v164, 32, v163
	v_subrev_u32_e32 v165, 1, v249
	v_subrev_u32_e32 v166, 2, v249
	v_subrev_u32_e32 v167, 4, v249
	v_subrev_u32_e32 v168, 8, v249
	v_subrev_u32_e32 v169, 16, v249
	v_subrev_u32_e32 v170, 32, v249
	v_lshlrev_b32_e32 v165, 2, v165
	v_lshlrev_b32_e32 v166, 2, v166
	v_lshlrev_b32_e32 v167, 2, v167
	v_lshlrev_b32_e32 v168, 2, v168
	v_lshlrev_b32_e32 v169, 2, v169
	v_lshlrev_b32_e32 v170, 2, v170
	v_mov_b32_e32 v0, 0
	v_mov_b32_e32 v1, 0
	v_mov_b32_e32 v2, 0
	v_mov_b32_e32 v3, 0
	v_mov_b32_e32 v4, 0
	v_mov_b32_e32 v5, 0
	v_mov_b32_e32 v6, 0
	v_mov_b32_e32 v7, 0
	v_mov_b32_e32 v8, 0
	v_mov_b32_e32 v9, 0
	v_mov_b32_e32 v10, 0
	v_mov_b32_e32 v11, 0
	v_mov_b32_e32 v12, 0
	v_mov_b32_e32 v13, 0
	v_mov_b32_e32 v14, 0
	v_mov_b32_e32 v15, 0
	v_mov_b32_e32 v16, 0
	v_mov_b32_e32 v17, 0
	v_mov_b32_e32 v18, 0
	v_mov_b32_e32 v19, 0
	v_mov_b32_e32 v20, 0
	v_mov_b32_e32 v21, 0
	v_mov_b32_e32 v22, 0
	v_mov_b32_e32 v23, 0
	v_mov_b32_e32 v24, 0
	v_mov_b32_e32 v25, 0
	v_mov_b32_e32 v26, 0
	v_mov_b32_e32 v27, 0
	v_mov_b32_e32 v28, 0
	v_mov_b32_e32 v29, 0
	v_mov_b32_e32 v30, 0
	v_mov_b32_e32 v31, 0
	v_mov_b32_e32 v32, 0
	v_mov_b32_e32 v33, 0
	v_mov_b32_e32 v34, 0
	v_mov_b32_e32 v35, 0
	v_mov_b32_e32 v36, 0
	v_mov_b32_e32 v37, 0
	v_mov_b32_e32 v38, 0
	v_mov_b32_e32 v39, 0
	v_mov_b32_e32 v40, 0
	v_mov_b32_e32 v41, 0
	v_mov_b32_e32 v42, 0
	v_mov_b32_e32 v43, 0
	v_mov_b32_e32 v44, 0
	v_mov_b32_e32 v45, 0
	v_mov_b32_e32 v46, 0
	v_mov_b32_e32 v47, 0
	v_mov_b32_e32 v48, 0
	v_mov_b32_e32 v49, 0
	v_mov_b32_e32 v50, 0
	v_mov_b32_e32 v51, 0
	v_mov_b32_e32 v52, 0
	v_mov_b32_e32 v53, 0
	v_mov_b32_e32 v54, 0
	v_mov_b32_e32 v55, 0
	v_mov_b32_e32 v56, 0
	v_mov_b32_e32 v57, 0
	v_mov_b32_e32 v58, 0
	v_mov_b32_e32 v59, 0
	v_mov_b32_e32 v60, 0
	v_mov_b32_e32 v61, 0
	v_mov_b32_e32 v62, 0
	v_mov_b32_e32 v63, 0
	s_waitcnt vmcnt(0) lgkmcnt(0)
	v_lshlrev_b32_e32 v128, 10, v128
	v_lshlrev_b32_e32 v129, 10, v129
	v_lshlrev_b32_e32 v132, 10, v132
	v_lshlrev_b32_e32 v133, 10, v133
	v_lshlrev_b32_e32 v136, 10, v136
	v_lshlrev_b32_e32 v137, 10, v137
	v_lshlrev_b32_e32 v140, 10, v140
	v_lshlrev_b32_e32 v141, 10, v141
	v_lshlrev_b32_e32 v144, 10, v144
	v_lshlrev_b32_e32 v145, 10, v145
	v_lshlrev_b32_e32 v148, 10, v148
	v_lshlrev_b32_e32 v149, 10, v149
	v_lshlrev_b32_e32 v152, 10, v152
	v_lshlrev_b32_e32 v153, 10, v153
	v_lshlrev_b32_e32 v156, 10, v156
	v_lshlrev_b32_e32 v157, 10, v157
	s_lshl_b32 s15, s14, 12
	s_add_u32 s62, s6, s15
	s_addc_u32 s63, s7, 0
	s_mov_b32 s72, 0
	s_mov_b32 s73, 1
	s_mov_b32 s74, 2
	s_mov_b32 s75, 3
	s_mov_b32 s76, 4
	s_mov_b32 s77, 5
	s_mov_b32 s78, 6
	s_mov_b32 s79, 7
	s_mov_b32 s80, 8
	s_mov_b32 s81, 9
	s_mov_b32 s82, 10
	s_mov_b32 s83, 11
	s_mov_b32 s84, 12
	s_mov_b32 s85, 13
	s_mov_b32 s86, 14
	s_mov_b32 s87, 15
	s_nop 0
	v_readlane_b32 s48, v128, s72
	v_readlane_b32 s49, v128, s73
	v_readlane_b32 s50, v128, s74
	v_readlane_b32 s51, v128, s75
	v_readlane_b32 s52, v128, s76
	v_readlane_b32 s53, v128, s77
	v_readlane_b32 s54, v128, s78
	v_readlane_b32 s55, v128, s79
	s_add_u32 s32, s0, s48
	s_addc_u32 s33, s1, 0
	s_add_u32 s34, s0, s49
	s_addc_u32 s35, s1, 0
	s_add_u32 s36, s0, s50
	s_addc_u32 s37, s1, 0
	s_add_u32 s38, s0, s51
	s_addc_u32 s39, s1, 0
	s_add_u32 s40, s0, s52
	s_addc_u32 s41, s1, 0
	s_add_u32 s42, s0, s53
	s_addc_u32 s43, s1, 0
	s_add_u32 s44, s0, s54
	s_addc_u32 s45, s1, 0
	s_add_u32 s46, s0, s55
	s_addc_u32 s47, s1, 0
	global_load_dwordx4 v[160:163], v240, s[32:33]
	global_load_dwordx4 v[164:167], v240, s[34:35]
	global_load_dwordx4 v[168:171], v240, s[36:37]
	global_load_dwordx4 v[172:175], v240, s[38:39]
	global_load_dwordx4 v[176:179], v240, s[40:41]
	global_load_dwordx4 v[180:183], v240, s[42:43]
	global_load_dwordx4 v[184:187], v240, s[44:45]
	global_load_dwordx4 v[188:191], v240, s[46:47]
; DI void peer_item_v(const Params& p, int item) {
;     ...
;     V_ISSUE(vqa, 0)
; #pragma unroll 1
;     for (int g = 0; g < 16; g += 2) {
;       V_ISSUE(vqb, g + 1)
;       V_CONSUME(vqa, g)
;       if (g + 2 < 16) V_ISSUE(vqa, g + 2)
;       V_CONSUME(vqb, g + 1)
	v_readlane_b32 s48, v132, s72
	v_readlane_b32 s49, v132, s73
	v_readlane_b32 s50, v132, s74
	v_readlane_b32 s51, v132, s75
	v_readlane_b32 s52, v132, s76
	v_readlane_b32 s53, v132, s77
	v_readlane_b32 s54, v132, s78
	v_readlane_b32 s55, v132, s79
	s_add_u32 s32, s0, s48
	s_addc_u32 s33, s1, 0
	s_add_u32 s34, s0, s49
	s_addc_u32 s35, s1, 0
	s_add_u32 s36, s0, s50
	s_addc_u32 s37, s1, 0
	s_add_u32 s38, s0, s51
	s_addc_u32 s39, s1, 0
	s_add_u32 s40, s0, s52
	s_addc_u32 s41, s1, 0
	s_add_u32 s42, s0, s53
	s_addc_u32 s43, s1, 0
	s_add_u32 s44, s0, s54
	s_addc_u32 s45, s1, 0
	s_add_u32 s46, s0, s55
	s_addc_u32 s47, s1, 0
	global_load_dwordx4 v[192:195], v240, s[32:33]
	global_load_dwordx4 v[196:199], v240, s[34:35]
	global_load_dwordx4 v[200:203], v240, s[36:37]
	global_load_dwordx4 v[204:207], v240, s[38:39]
	global_load_dwordx4 v[208:211], v240, s[40:41]
	global_load_dwordx4 v[212:215], v240, s[42:43]
	global_load_dwordx4 v[216:219], v240, s[44:45]
	global_load_dwordx4 v[220:223], v240, s[46:47]
	v_readlane_b32 s48, v136, s72
	v_readlane_b32 s49, v136, s73
	v_readlane_b32 s50, v136, s74
	v_readlane_b32 s51, v136, s75
	v_readlane_b32 s52, v136, s76
	v_readlane_b32 s53, v136, s77
	v_readlane_b32 s54, v136, s78
	v_readlane_b32 s55, v136, s79
	s_add_u32 s32, s0, s48
	s_addc_u32 s33, s1, 0
	s_add_u32 s34, s0, s49
	s_addc_u32 s35, s1, 0
	s_add_u32 s36, s0, s50
	s_addc_u32 s37, s1, 0
	s_add_u32 s38, s0, s51
	s_addc_u32 s39, s1, 0
	s_add_u32 s40, s0, s52
	s_addc_u32 s41, s1, 0
	s_add_u32 s42, s0, s53
	s_addc_u32 s43, s1, 0
	s_add_u32 s44, s0, s54
	s_addc_u32 s45, s1, 0
	s_add_u32 s46, s0, s55
	s_addc_u32 s47, s1, 0
	global_load_dwordx4 v[64:67], v240, s[32:33]
	global_load_dwordx4 v[68:71], v240, s[34:35]
	global_load_dwordx4 v[72:75], v240, s[36:37]
	global_load_dwordx4 v[76:79], v240, s[38:39]
	global_load_dwordx4 v[80:83], v240, s[40:41]
	global_load_dwordx4 v[84:87], v240, s[42:43]
	global_load_dwordx4 v[88:91], v240, s[44:45]
	global_load_dwordx4 v[92:95], v240, s[46:47]
	s_mov_b32 s12, 0
.Lvq_kA:
	v_readlane_b32 s16, v130, s72
	v_readlane_b32 s18, v130, s73
	v_readlane_b32 s20, v130, s74
	v_readlane_b32 s22, v130, s75
	v_readlane_b32 s24, v130, s76
	v_readlane_b32 s26, v130, s77
	v_readlane_b32 s28, v130, s78
	v_readlane_b32 s30, v130, s79
	v_readlane_b32 s48, v140, s72
	v_readlane_b32 s49, v140, s73
	v_readlane_b32 s50, v140, s74
	v_readlane_b32 s51, v140, s75
	v_readlane_b32 s52, v140, s76
	v_readlane_b32 s53, v140, s77
	v_readlane_b32 s54, v140, s78
	v_readlane_b32 s55, v140, s79
	s_add_u32 s32, s0, s48
	s_addc_u32 s33, s1, 0
	s_add_u32 s34, s0, s49
	s_addc_u32 s35, s1, 0
	s_add_u32 s36, s0, s50
	s_addc_u32 s37, s1, 0
	s_add_u32 s38, s0, s51
	s_addc_u32 s39, s1, 0
	s_add_u32 s40, s0, s52
	s_addc_u32 s41, s1, 0
	s_add_u32 s42, s0, s53
	s_addc_u32 s43, s1, 0
	s_add_u32 s44, s0, s54
	s_addc_u32 s45, s1, 0
	s_add_u32 s46, s0, s55
	s_addc_u32 s47, s1, 0
	global_load_dwordx4 v[96:99], v240, s[32:33]
	global_load_dwordx4 v[100:103], v240, s[34:35]
	global_load_dwordx4 v[104:107], v240, s[36:37]
	global_load_dwordx4 v[108:111], v240, s[38:39]
	global_load_dwordx4 v[112:115], v240, s[40:41]
	global_load_dwordx4 v[116:119], v240, s[42:43]
	global_load_dwordx4 v[120:123], v240, s[44:45]
	global_load_dwordx4 v[124:127], v240, s[46:47]
	s_waitcnt vmcnt(24)
	v_cvt_pk_f32_fp8_e32 v[224:225], v160
	v_cvt_pk_f32_fp8_sdwa v[226:227], v160 src0_sel:WORD_1
	v_cvt_pk_f32_fp8_e32 v[228:229], v161
	v_cvt_pk_f32_fp8_sdwa v[230:231], v161 src0_sel:WORD_1
	v_cvt_pk_f32_fp8_e32 v[232:233], v162
	v_cvt_pk_f32_fp8_sdwa v[234:235], v162 src0_sel:WORD_1
	v_cvt_pk_f32_fp8_e32 v[236:237], v163
	v_cvt_pk_f32_fp8_sdwa v[238:239], v163 src0_sel:WORD_1
	v_pk_fma_f32 v[0:1], v[224:225], s[16:17], v[0:1] op_sel_hi:[1,0,1]
	v_pk_fma_f32 v[2:3], v[226:227], s[16:17], v[2:3] op_sel_hi:[1,0,1]
	v_pk_fma_f32 v[4:5], v[228:229], s[16:17], v[4:5] op_sel_hi:[1,0,1]
	v_pk_fma_f32 v[6:7], v[230:231], s[16:17], v[6:7] op_sel_hi:[1,0,1]
	v_pk_fma_f32 v[8:9], v[232:233], s[16:17], v[8:9] op_sel_hi:[1,0,1]
	v_pk_fma_f32 v[10:11], v[234:235], s[16:17], v[10:11] op_sel_hi:[1,0,1]
	v_pk_fma_f32 v[12:13], v[236:237], s[16:17], v[12:13] op_sel_hi:[1,0,1]
	v_pk_fma_f32 v[14:15], v[238:239], s[16:17], v[14:15] op_sel_hi:[1,0,1]
	v_cvt_pk_f32_fp8_e32 v[224:225], v164
	v_cvt_pk_f32_fp8_sdwa v[226:227], v164 src0_sel:WORD_1
	v_cvt_pk_f32_fp8_e32 v[228:229], v165
	v_cvt_pk_f32_fp8_sdwa v[230:231], v165 src0_sel:WORD_1
	v_cvt_pk_f32_fp8_e32 v[232:233], v166
	v_cvt_pk_f32_fp8_sdwa v[234:235], v166 src0_sel:WORD_1
	v_cvt_pk_f32_fp8_e32 v[236:237], v167
	v_cvt_pk_f32_fp8_sdwa v[238:239], v167 src0_sel:WORD_1
	v_pk_fma_f32 v[0:1], v[224:225], s[18:19], v[0:1] op_sel_hi:[1,0,1]
	v_pk_fma_f32 v[2:3], v[226:227], s[18:19], v[2:3] op_sel_hi:[1,0,1]
	v_pk_fma_f32 v[4:5], v[228:229], s[18:19], v[4:5] op_sel_hi:[1,0,1]
	v_pk_fma_f32 v[6:7], v[230:231], s[18:19], v[6:7] op_sel_hi:[1,0,1]
	v_pk_fma_f32 v[8:9], v[232:233], s[18:19], v[8:9] op_sel_hi:[1,0,1]
	v_pk_fma_f32 v[10:11], v[234:235], s[18:19], v[10:11] op_sel_hi:[1,0,1]
	v_pk_fma_f32 v[12:13], v[236:237], s[18:19], v[12:13] op_sel_hi:[1,0,1]
	v_pk_fma_f32 v[14:15], v[238:239], s[18:19], v[14:15] op_sel_hi:[1,0,1]
	v_cvt_pk_f32_fp8_e32 v[224:225], v168
	v_cvt_pk_f32_fp8_sdwa v[226:227], v168 src0_sel:WORD_1
	v_cvt_pk_f32_fp8_e32 v[228:229], v169
	v_cvt_pk_f32_fp8_sdwa v[230:231], v169 src0_sel:WORD_1
	v_cvt_pk_f32_fp8_e32 v[232:233], v170
	v_cvt_pk_f32_fp8_sdwa v[234:235], v170 src0_sel:WORD_1
	v_cvt_pk_f32_fp8_e32 v[236:237], v171
	v_cvt_pk_f32_fp8_sdwa v[238:239], v171 src0_sel:WORD_1
	v_pk_fma_f32 v[0:1], v[224:225], s[20:21], v[0:1] op_sel_hi:[1,0,1]
; DI void peer_item_v(const Params& p, int item) {
;     ...
;     V_ISSUE(vqa, 0)
; #pragma unroll 1
;     for (int g = 0; g < 16; g += 2) {
;       V_ISSUE(vqb, g + 1)
;       V_CONSUME(vqa, g)
;       if (g + 2 < 16) V_ISSUE(vqa, g + 2)
;       V_CONSUME(vqb, g + 1)
;     }
	v_pk_fma_f32 v[2:3], v[226:227], s[20:21], v[2:3] op_sel_hi:[1,0,1]
	v_pk_fma_f32 v[4:5], v[228:229], s[20:21], v[4:5] op_sel_hi:[1,0,1]
	v_pk_fma_f32 v[6:7], v[230:231], s[20:21], v[6:7] op_sel_hi:[1,0,1]
	v_pk_fma_f32 v[8:9], v[232:233], s[20:21], v[8:9] op_sel_hi:[1,0,1]
	v_pk_fma_f32 v[10:11], v[234:235], s[20:21], v[10:11] op_sel_hi:[1,0,1]
	v_pk_fma_f32 v[12:13], v[236:237], s[20:21], v[12:13] op_sel_hi:[1,0,1]
	v_pk_fma_f32 v[14:15], v[238:239], s[20:21], v[14:15] op_sel_hi:[1,0,1]
	v_cvt_pk_f32_fp8_e32 v[224:225], v172
	v_cvt_pk_f32_fp8_sdwa v[226:227], v172 src0_sel:WORD_1
	v_cvt_pk_f32_fp8_e32 v[228:229], v173
	v_cvt_pk_f32_fp8_sdwa v[230:231], v173 src0_sel:WORD_1
	v_cvt_pk_f32_fp8_e32 v[232:233], v174
	v_cvt_pk_f32_fp8_sdwa v[234:235], v174 src0_sel:WORD_1
	v_cvt_pk_f32_fp8_e32 v[236:237], v175
	v_cvt_pk_f32_fp8_sdwa v[238:239], v175 src0_sel:WORD_1
	v_pk_fma_f32 v[0:1], v[224:225], s[22:23], v[0:1] op_sel_hi:[1,0,1]
	v_pk_fma_f32 v[2:3], v[226:227], s[22:23], v[2:3] op_sel_hi:[1,0,1]
	v_pk_fma_f32 v[4:5], v[228:229], s[22:23], v[4:5] op_sel_hi:[1,0,1]
	v_pk_fma_f32 v[6:7], v[230:231], s[22:23], v[6:7] op_sel_hi:[1,0,1]
	v_pk_fma_f32 v[8:9], v[232:233], s[22:23], v[8:9] op_sel_hi:[1,0,1]
	v_pk_fma_f32 v[10:11], v[234:235], s[22:23], v[10:11] op_sel_hi:[1,0,1]
	v_pk_fma_f32 v[12:13], v[236:237], s[22:23], v[12:13] op_sel_hi:[1,0,1]
	v_pk_fma_f32 v[14:15], v[238:239], s[22:23], v[14:15] op_sel_hi:[1,0,1]
	v_cvt_pk_f32_fp8_e32 v[224:225], v176
	v_cvt_pk_f32_fp8_sdwa v[226:227], v176 src0_sel:WORD_1
	v_cvt_pk_f32_fp8_e32 v[228:229], v177
	v_cvt_pk_f32_fp8_sdwa v[230:231], v177 src0_sel:WORD_1
	v_cvt_pk_f32_fp8_e32 v[232:233], v178
	v_cvt_pk_f32_fp8_sdwa v[234:235], v178 src0_sel:WORD_1
	v_cvt_pk_f32_fp8_e32 v[236:237], v179
	v_cvt_pk_f32_fp8_sdwa v[238:239], v179 src0_sel:WORD_1
	v_pk_fma_f32 v[0:1], v[224:225], s[24:25], v[0:1] op_sel_hi:[1,0,1]
	v_pk_fma_f32 v[2:3], v[226:227], s[24:25], v[2:3] op_sel_hi:[1,0,1]
	v_pk_fma_f32 v[4:5], v[228:229], s[24:25], v[4:5] op_sel_hi:[1,0,1]
	v_pk_fma_f32 v[6:7], v[230:231], s[24:25], v[6:7] op_sel_hi:[1,0,1]
	v_pk_fma_f32 v[8:9], v[232:233], s[24:25], v[8:9] op_sel_hi:[1,0,1]
	v_pk_fma_f32 v[10:11], v[234:235], s[24:25], v[10:11] op_sel_hi:[1,0,1]
	v_pk_fma_f32 v[12:13], v[236:237], s[24:25], v[12:13] op_sel_hi:[1,0,1]
	v_pk_fma_f32 v[14:15], v[238:239], s[24:25], v[14:15] op_sel_hi:[1,0,1]
	v_cvt_pk_f32_fp8_e32 v[224:225], v180
	v_cvt_pk_f32_fp8_sdwa v[226:227], v180 src0_sel:WORD_1
	v_cvt_pk_f32_fp8_e32 v[228:229], v181
	v_cvt_pk_f32_fp8_sdwa v[230:231], v181 src0_sel:WORD_1
	v_cvt_pk_f32_fp8_e32 v[232:233], v182
	v_cvt_pk_f32_fp8_sdwa v[234:235], v182 src0_sel:WORD_1
	v_cvt_pk_f32_fp8_e32 v[236:237], v183
	v_cvt_pk_f32_fp8_sdwa v[238:239], v183 src0_sel:WORD_1
	v_pk_fma_f32 v[0:1], v[224:225], s[26:27], v[0:1] op_sel_hi:[1,0,1]
	v_pk_fma_f32 v[2:3], v[226:227], s[26:27], v[2:3] op_sel_hi:[1,0,1]
	v_pk_fma_f32 v[4:5], v[228:229], s[26:27], v[4:5] op_sel_hi:[1,0,1]
	v_pk_fma_f32 v[6:7], v[230:231], s[26:27], v[6:7] op_sel_hi:[1,0,1]
	v_pk_fma_f32 v[8:9], v[232:233], s[26:27], v[8:9] op_sel_hi:[1,0,1]
	v_pk_fma_f32 v[10:11], v[234:235], s[26:27], v[10:11] op_sel_hi:[1,0,1]
	v_pk_fma_f32 v[12:13], v[236:237], s[26:27], v[12:13] op_sel_hi:[1,0,1]
	v_pk_fma_f32 v[14:15], v[238:239], s[26:27], v[14:15] op_sel_hi:[1,0,1]
	v_cvt_pk_f32_fp8_e32 v[224:225], v184
	v_cvt_pk_f32_fp8_sdwa v[226:227], v184 src0_sel:WORD_1
	v_cvt_pk_f32_fp8_e32 v[228:229], v185
	v_cvt_pk_f32_fp8_sdwa v[230:231], v185 src0_sel:WORD_1
	v_cvt_pk_f32_fp8_e32 v[232:233], v186
	v_cvt_pk_f32_fp8_sdwa v[234:235], v186 src0_sel:WORD_1
	v_cvt_pk_f32_fp8_e32 v[236:237], v187
	v_cvt_pk_f32_fp8_sdwa v[238:239], v187 src0_sel:WORD_1
	v_pk_fma_f32 v[0:1], v[224:225], s[28:29], v[0:1] op_sel_hi:[1,0,1]
	v_pk_fma_f32 v[2:3], v[226:227], s[28:29], v[2:3] op_sel_hi:[1,0,1]
	v_pk_fma_f32 v[4:5], v[228:229], s[28:29], v[4:5] op_sel_hi:[1,0,1]
	v_pk_fma_f32 v[6:7], v[230:231], s[28:29], v[6:7] op_sel_hi:[1,0,1]
	v_pk_fma_f32 v[8:9], v[232:233], s[28:29], v[8:9] op_sel_hi:[1,0,1]
	v_pk_fma_f32 v[10:11], v[234:235], s[28:29], v[10:11] op_sel_hi:[1,0,1]
	v_pk_fma_f32 v[12:13], v[236:237], s[28:29], v[12:13] op_sel_hi:[1,0,1]
	v_pk_fma_f32 v[14:15], v[238:239], s[28:29], v[14:15] op_sel_hi:[1,0,1]
	v_cvt_pk_f32_fp8_e32 v[224:225], v188
	v_cvt_pk_f32_fp8_sdwa v[226:227], v188 src0_sel:WORD_1
	v_cvt_pk_f32_fp8_e32 v[228:229], v189
	v_cvt_pk_f32_fp8_sdwa v[230:231], v189 src0_sel:WORD_1
	v_cvt_pk_f32_fp8_e32 v[232:233], v190
	v_cvt_pk_f32_fp8_sdwa v[234:235], v190 src0_sel:WORD_1
	v_cvt_pk_f32_fp8_e32 v[236:237], v191
	v_cvt_pk_f32_fp8_sdwa v[238:239], v191 src0_sel:WORD_1
	v_pk_fma_f32 v[0:1], v[224:225], s[30:31], v[0:1] op_sel_hi:[1,0,1]
	v_pk_fma_f32 v[2:3], v[226:227], s[30:31], v[2:3] op_sel_hi:[1,0,1]
	v_pk_fma_f32 v[4:5], v[228:229], s[30:31], v[4:5] op_sel_hi:[1,0,1]
	v_pk_fma_f32 v[6:7], v[230:231], s[30:31], v[6:7] op_sel_hi:[1,0,1]
	v_pk_fma_f32 v[8:9], v[232:233], s[30:31], v[8:9] op_sel_hi:[1,0,1]
	v_pk_fma_f32 v[10:11], v[234:235], s[30:31], v[10:11] op_sel_hi:[1,0,1]
	v_pk_fma_f32 v[12:13], v[236:237], s[30:31], v[12:13] op_sel_hi:[1,0,1]
	v_pk_fma_f32 v[14:15], v[238:239], s[30:31], v[14:15] op_sel_hi:[1,0,1]
	v_readlane_b32 s16, v134, s72
	v_readlane_b32 s18, v134, s73
	v_readlane_b32 s20, v134, s74
	v_readlane_b32 s22, v134, s75
	v_readlane_b32 s24, v134, s76
	v_readlane_b32 s26, v134, s77
	v_readlane_b32 s28, v134, s78
	v_readlane_b32 s30, v134, s79
	v_readlane_b32 s48, v129, s72
	v_readlane_b32 s49, v129, s73
	v_readlane_b32 s50, v129, s74
	v_readlane_b32 s51, v129, s75
	v_readlane_b32 s52, v129, s76
	v_readlane_b32 s53, v129, s77
	v_readlane_b32 s54, v129, s78
	v_readlane_b32 s55, v129, s79
	s_add_u32 s32, s0, s48
	s_addc_u32 s33, s1, 0
	s_add_u32 s34, s0, s49
	s_addc_u32 s35, s1, 0
	s_add_u32 s36, s0, s50
	s_addc_u32 s37, s1, 0
	s_add_u32 s38, s0, s51
	s_addc_u32 s39, s1, 0
	s_add_u32 s40, s0, s52
	s_addc_u32 s41, s1, 0
	s_add_u32 s42, s0, s53
	s_addc_u32 s43, s1, 0
	s_add_u32 s44, s0, s54
	s_addc_u32 s45, s1, 0
	s_add_u32 s46, s0, s55
	s_addc_u32 s47, s1, 0
	global_load_dwordx4 v[160:163], v240, s[32:33]
	global_load_dwordx4 v[164:167], v240, s[34:35]
	global_load_dwordx4 v[168:171], v240, s[36:37]
	global_load_dwordx4 v[172:175], v240, s[38:39]
	global_load_dwordx4 v[176:179], v240, s[40:41]
	global_load_dwordx4 v[180:183], v240, s[42:43]
	global_load_dwordx4 v[184:187], v240, s[44:45]
	global_load_dwordx4 v[188:191], v240, s[46:47]
	s_waitcnt vmcnt(24)
	v_cvt_pk_f32_fp8_e32 v[224:225], v192
	v_cvt_pk_f32_fp8_sdwa v[226:227], v192 src0_sel:WORD_1
	v_cvt_pk_f32_fp8_e32 v[228:229], v193
	v_cvt_pk_f32_fp8_sdwa v[230:231], v193 src0_sel:WORD_1
	v_cvt_pk_f32_fp8_e32 v[232:233], v194
	v_cvt_pk_f32_fp8_sdwa v[234:235], v194 src0_sel:WORD_1
	v_cvt_pk_f32_fp8_e32 v[236:237], v195
	v_cvt_pk_f32_fp8_sdwa v[238:239], v195 src0_sel:WORD_1
	v_pk_fma_f32 v[16:17], v[224:225], s[16:17], v[16:17] op_sel_hi:[1,0,1]
	v_pk_fma_f32 v[18:19], v[226:227], s[16:17], v[18:19] op_sel_hi:[1,0,1]
	v_pk_fma_f32 v[20:21], v[228:229], s[16:17], v[20:21] op_sel_hi:[1,0,1]
	v_pk_fma_f32 v[22:23], v[230:231], s[16:17], v[22:23] op_sel_hi:[1,0,1]
	v_pk_fma_f32 v[24:25], v[232:233], s[16:17], v[24:25] op_sel_hi:[1,0,1]
	v_pk_fma_f32 v[26:27], v[234:235], s[16:17], v[26:27] op_sel_hi:[1,0,1]
	v_pk_fma_f32 v[28:29], v[236:237], s[16:17], v[28:29] op_sel_hi:[1,0,1]
	v_pk_fma_f32 v[30:31], v[238:239], s[16:17], v[30:31] op_sel_hi:[1,0,1]
	v_cvt_pk_f32_fp8_e32 v[224:225], v196
	v_cvt_pk_f32_fp8_sdwa v[226:227], v196 src0_sel:WORD_1
	v_cvt_pk_f32_fp8_e32 v[228:229], v197
	v_cvt_pk_f32_fp8_sdwa v[230:231], v197 src0_sel:WORD_1
	v_cvt_pk_f32_fp8_e32 v[232:233], v198
	v_cvt_pk_f32_fp8_sdwa v[234:235], v198 src0_sel:WORD_1
	v_cvt_pk_f32_fp8_e32 v[236:237], v199
	v_cvt_pk_f32_fp8_sdwa v[238:239], v199 src0_sel:WORD_1
	v_pk_fma_f32 v[16:17], v[224:225], s[18:19], v[16:17] op_sel_hi:[1,0,1]
	v_pk_fma_f32 v[18:19], v[226:227], s[18:19], v[18:19] op_sel_hi:[1,0,1]
	v_pk_fma_f32 v[20:21], v[228:229], s[18:19], v[20:21] op_sel_hi:[1,0,1]
	v_pk_fma_f32 v[22:23], v[230:231], s[18:19], v[22:23] op_sel_hi:[1,0,1]
	v_pk_fma_f32 v[24:25], v[232:233], s[18:19], v[24:25] op_sel_hi:[1,0,1]
	v_pk_fma_f32 v[26:27], v[234:235], s[18:19], v[26:27] op_sel_hi:[1,0,1]
	v_pk_fma_f32 v[28:29], v[236:237], s[18:19], v[28:29] op_sel_hi:[1,0,1]
	v_pk_fma_f32 v[30:31], v[238:239], s[18:19], v[30:31] op_sel_hi:[1,0,1]
	v_cvt_pk_f32_fp8_e32 v[224:225], v200
	v_cvt_pk_f32_fp8_sdwa v[226:227], v200 src0_sel:WORD_1
	v_cvt_pk_f32_fp8_e32 v[228:229], v201
	v_cvt_pk_f32_fp8_sdwa v[230:231], v201 src0_sel:WORD_1
	v_cvt_pk_f32_fp8_e32 v[232:233], v202
	v_cvt_pk_f32_fp8_sdwa v[234:235], v202 src0_sel:WORD_1
	v_cvt_pk_f32_fp8_e32 v[236:237], v203
	v_cvt_pk_f32_fp8_sdwa v[238:239], v203 src0_sel:WORD_1
	v_pk_fma_f32 v[16:17], v[224:225], s[20:21], v[16:17] op_sel_hi:[1,0,1]
	v_pk_fma_f32 v[18:19], v[226:227], s[20:21], v[18:19] op_sel_hi:[1,0,1]
	v_pk_fma_f32 v[20:21], v[228:229], s[20:21], v[20:21] op_sel_hi:[1,0,1]
	v_pk_fma_f32 v[22:23], v[230:231], s[20:21], v[22:23] op_sel_hi:[1,0,1]
	v_pk_fma_f32 v[24:25], v[232:233], s[20:21], v[24:25] op_sel_hi:[1,0,1]
	v_pk_fma_f32 v[26:27], v[234:235], s[20:21], v[26:27] op_sel_hi:[1,0,1]
	v_pk_fma_f32 v[28:29], v[236:237], s[20:21], v[28:29] op_sel_hi:[1,0,1]
	v_pk_fma_f32 v[30:31], v[238:239], s[20:21], v[30:31] op_sel_hi:[1,0,1]
	v_cvt_pk_f32_fp8_e32 v[224:225], v204
	v_cvt_pk_f32_fp8_sdwa v[226:227], v204 src0_sel:WORD_1
	v_cvt_pk_f32_fp8_e32 v[228:229], v205
	v_cvt_pk_f32_fp8_sdwa v[230:231], v205 src0_sel:WORD_1
	v_cvt_pk_f32_fp8_e32 v[232:233], v206
	v_cvt_pk_f32_fp8_sdwa v[234:235], v206 src0_sel:WORD_1
	v_cvt_pk_f32_fp8_e32 v[236:237], v207
	v_cvt_pk_f32_fp8_sdwa v[238:239], v207 src0_sel:WORD_1
	v_pk_fma_f32 v[16:17], v[224:225], s[22:23], v[16:17] op_sel_hi:[1,0,1]
	v_pk_fma_f32 v[18:19], v[226:227], s[22:23], v[18:19] op_sel_hi:[1,0,1]
	v_pk_fma_f32 v[20:21], v[228:229], s[22:23], v[20:21] op_sel_hi:[1,0,1]
	v_pk_fma_f32 v[22:23], v[230:231], s[22:23], v[22:23] op_sel_hi:[1,0,1]
	v_pk_fma_f32 v[24:25], v[232:233], s[22:23], v[24:25] op_sel_hi:[1,0,1]
	v_pk_fma_f32 v[26:27], v[234:235], s[22:23], v[26:27] op_sel_hi:[1,0,1]
	v_pk_fma_f32 v[28:29], v[236:237], s[22:23], v[28:29] op_sel_hi:[1,0,1]
	v_pk_fma_f32 v[30:31], v[238:239], s[22:23], v[30:31] op_sel_hi:[1,0,1]
	v_cvt_pk_f32_fp8_e32 v[224:225], v208
	v_cvt_pk_f32_fp8_sdwa v[226:227], v208 src0_sel:WORD_1
	v_cvt_pk_f32_fp8_e32 v[228:229], v209
	v_cvt_pk_f32_fp8_sdwa v[230:231], v209 src0_sel:WORD_1
	v_cvt_pk_f32_fp8_e32 v[232:233], v210
	v_cvt_pk_f32_fp8_sdwa v[234:235], v210 src0_sel:WORD_1
	v_cvt_pk_f32_fp8_e32 v[236:237], v211
	v_cvt_pk_f32_fp8_sdwa v[238:239], v211 src0_sel:WORD_1
	v_pk_fma_f32 v[16:17], v[224:225], s[24:25], v[16:17] op_sel_hi:[1,0,1]
	v_pk_fma_f32 v[18:19], v[226:227], s[24:25], v[18:19] op_sel_hi:[1,0,1]
	v_pk_fma_f32 v[20:21], v[228:229], s[24:25], v[20:21] op_sel_hi:[1,0,1]
	v_pk_fma_f32 v[22:23], v[230:231], s[24:25], v[22:23] op_sel_hi:[1,0,1]
	v_pk_fma_f32 v[24:25], v[232:233], s[24:25], v[24:25] op_sel_hi:[1,0,1]
	v_pk_fma_f32 v[26:27], v[234:235], s[24:25], v[26:27] op_sel_hi:[1,0,1]
	v_pk_fma_f32 v[28:29], v[236:237], s[24:25], v[28:29] op_sel_hi:[1,0,1]
	v_pk_fma_f32 v[30:31], v[238:239], s[24:25], v[30:31] op_sel_hi:[1,0,1]
	v_cvt_pk_f32_fp8_e32 v[224:225], v212
	v_cvt_pk_f32_fp8_sdwa v[226:227], v212 src0_sel:WORD_1
	v_cvt_pk_f32_fp8_e32 v[228:229], v213
	v_cvt_pk_f32_fp8_sdwa v[230:231], v213 src0_sel:WORD_1
	v_cvt_pk_f32_fp8_e32 v[232:233], v214
	v_cvt_pk_f32_fp8_sdwa v[234:235], v214 src0_sel:WORD_1
	v_cvt_pk_f32_fp8_e32 v[236:237], v215
	v_cvt_pk_f32_fp8_sdwa v[238:239], v215 src0_sel:WORD_1
	v_pk_fma_f32 v[16:17], v[224:225], s[26:27], v[16:17] op_sel_hi:[1,0,1]
	v_pk_fma_f32 v[18:19], v[226:227], s[26:27], v[18:19] op_sel_hi:[1,0,1]
	v_pk_fma_f32 v[20:21], v[228:229], s[26:27], v[20:21] op_sel_hi:[1,0,1]
	v_pk_fma_f32 v[22:23], v[230:231], s[26:27], v[22:23] op_sel_hi:[1,0,1]
	v_pk_fma_f32 v[24:25], v[232:233], s[26:27], v[24:25] op_sel_hi:[1,0,1]
	v_pk_fma_f32 v[26:27], v[234:235], s[26:27], v[26:27] op_sel_hi:[1,0,1]
; DI void peer_item_v(const Params& p, int item) {
;     ...
;     V_ISSUE(vqa, 0)
; #pragma unroll 1
;     for (int g = 0; g < 16; g += 2) {
;       V_ISSUE(vqb, g + 1)
;       V_CONSUME(vqa, g)
;       if (g + 2 < 16) V_ISSUE(vqa, g + 2)
;       V_CONSUME(vqb, g + 1)
;     }
	v_pk_fma_f32 v[28:29], v[236:237], s[26:27], v[28:29] op_sel_hi:[1,0,1]
	v_pk_fma_f32 v[30:31], v[238:239], s[26:27], v[30:31] op_sel_hi:[1,0,1]
	v_cvt_pk_f32_fp8_e32 v[224:225], v216
	v_cvt_pk_f32_fp8_sdwa v[226:227], v216 src0_sel:WORD_1
	v_cvt_pk_f32_fp8_e32 v[228:229], v217
	v_cvt_pk_f32_fp8_sdwa v[230:231], v217 src0_sel:WORD_1
	v_cvt_pk_f32_fp8_e32 v[232:233], v218
	v_cvt_pk_f32_fp8_sdwa v[234:235], v218 src0_sel:WORD_1
	v_cvt_pk_f32_fp8_e32 v[236:237], v219
	v_cvt_pk_f32_fp8_sdwa v[238:239], v219 src0_sel:WORD_1
	v_pk_fma_f32 v[16:17], v[224:225], s[28:29], v[16:17] op_sel_hi:[1,0,1]
	v_pk_fma_f32 v[18:19], v[226:227], s[28:29], v[18:19] op_sel_hi:[1,0,1]
	v_pk_fma_f32 v[20:21], v[228:229], s[28:29], v[20:21] op_sel_hi:[1,0,1]
	v_pk_fma_f32 v[22:23], v[230:231], s[28:29], v[22:23] op_sel_hi:[1,0,1]
	v_pk_fma_f32 v[24:25], v[232:233], s[28:29], v[24:25] op_sel_hi:[1,0,1]
	v_pk_fma_f32 v[26:27], v[234:235], s[28:29], v[26:27] op_sel_hi:[1,0,1]
	v_pk_fma_f32 v[28:29], v[236:237], s[28:29], v[28:29] op_sel_hi:[1,0,1]
	v_pk_fma_f32 v[30:31], v[238:239], s[28:29], v[30:31] op_sel_hi:[1,0,1]
	v_cvt_pk_f32_fp8_e32 v[224:225], v220
	v_cvt_pk_f32_fp8_sdwa v[226:227], v220 src0_sel:WORD_1
	v_cvt_pk_f32_fp8_e32 v[228:229], v221
	v_cvt_pk_f32_fp8_sdwa v[230:231], v221 src0_sel:WORD_1
	v_cvt_pk_f32_fp8_e32 v[232:233], v222
	v_cvt_pk_f32_fp8_sdwa v[234:235], v222 src0_sel:WORD_1
	v_cvt_pk_f32_fp8_e32 v[236:237], v223
	v_cvt_pk_f32_fp8_sdwa v[238:239], v223 src0_sel:WORD_1
	v_pk_fma_f32 v[16:17], v[224:225], s[30:31], v[16:17] op_sel_hi:[1,0,1]
	v_pk_fma_f32 v[18:19], v[226:227], s[30:31], v[18:19] op_sel_hi:[1,0,1]
	v_pk_fma_f32 v[20:21], v[228:229], s[30:31], v[20:21] op_sel_hi:[1,0,1]
	v_pk_fma_f32 v[22:23], v[230:231], s[30:31], v[22:23] op_sel_hi:[1,0,1]
	v_pk_fma_f32 v[24:25], v[232:233], s[30:31], v[24:25] op_sel_hi:[1,0,1]
	v_pk_fma_f32 v[26:27], v[234:235], s[30:31], v[26:27] op_sel_hi:[1,0,1]
	v_pk_fma_f32 v[28:29], v[236:237], s[30:31], v[28:29] op_sel_hi:[1,0,1]
	v_pk_fma_f32 v[30:31], v[238:239], s[30:31], v[30:31] op_sel_hi:[1,0,1]
	v_readlane_b32 s16, v138, s72
	v_readlane_b32 s18, v138, s73
	v_readlane_b32 s20, v138, s74
	v_readlane_b32 s22, v138, s75
	v_readlane_b32 s24, v138, s76
	v_readlane_b32 s26, v138, s77
	v_readlane_b32 s28, v138, s78
	v_readlane_b32 s30, v138, s79
	v_readlane_b32 s48, v133, s72
	v_readlane_b32 s49, v133, s73
	v_readlane_b32 s50, v133, s74
	v_readlane_b32 s51, v133, s75
	v_readlane_b32 s52, v133, s76
	v_readlane_b32 s53, v133, s77
	v_readlane_b32 s54, v133, s78
	v_readlane_b32 s55, v133, s79
	s_add_u32 s32, s0, s48
	s_addc_u32 s33, s1, 0
	s_add_u32 s34, s0, s49
	s_addc_u32 s35, s1, 0
	s_add_u32 s36, s0, s50
	s_addc_u32 s37, s1, 0
	s_add_u32 s38, s0, s51
	s_addc_u32 s39, s1, 0
	s_add_u32 s40, s0, s52
	s_addc_u32 s41, s1, 0
	s_add_u32 s42, s0, s53
	s_addc_u32 s43, s1, 0
	s_add_u32 s44, s0, s54
	s_addc_u32 s45, s1, 0
	s_add_u32 s46, s0, s55
	s_addc_u32 s47, s1, 0
	global_load_dwordx4 v[192:195], v240, s[32:33]
	global_load_dwordx4 v[196:199], v240, s[34:35]
	global_load_dwordx4 v[200:203], v240, s[36:37]
	global_load_dwordx4 v[204:207], v240, s[38:39]
	global_load_dwordx4 v[208:211], v240, s[40:41]
	global_load_dwordx4 v[212:215], v240, s[42:43]
	global_load_dwordx4 v[216:219], v240, s[44:45]
	global_load_dwordx4 v[220:223], v240, s[46:47]
	s_waitcnt vmcnt(24)
	v_cvt_pk_f32_fp8_e32 v[224:225], v64
	v_cvt_pk_f32_fp8_sdwa v[226:227], v64 src0_sel:WORD_1
	v_cvt_pk_f32_fp8_e32 v[228:229], v65
	v_cvt_pk_f32_fp8_sdwa v[230:231], v65 src0_sel:WORD_1
	v_cvt_pk_f32_fp8_e32 v[232:233], v66
	v_cvt_pk_f32_fp8_sdwa v[234:235], v66 src0_sel:WORD_1
	v_cvt_pk_f32_fp8_e32 v[236:237], v67
	v_cvt_pk_f32_fp8_sdwa v[238:239], v67 src0_sel:WORD_1
	v_pk_fma_f32 v[32:33], v[224:225], s[16:17], v[32:33] op_sel_hi:[1,0,1]
	v_pk_fma_f32 v[34:35], v[226:227], s[16:17], v[34:35] op_sel_hi:[1,0,1]
	v_pk_fma_f32 v[36:37], v[228:229], s[16:17], v[36:37] op_sel_hi:[1,0,1]
	v_pk_fma_f32 v[38:39], v[230:231], s[16:17], v[38:39] op_sel_hi:[1,0,1]
	v_pk_fma_f32 v[40:41], v[232:233], s[16:17], v[40:41] op_sel_hi:[1,0,1]
	v_pk_fma_f32 v[42:43], v[234:235], s[16:17], v[42:43] op_sel_hi:[1,0,1]
	v_pk_fma_f32 v[44:45], v[236:237], s[16:17], v[44:45] op_sel_hi:[1,0,1]
	v_pk_fma_f32 v[46:47], v[238:239], s[16:17], v[46:47] op_sel_hi:[1,0,1]
	v_cvt_pk_f32_fp8_e32 v[224:225], v68
	v_cvt_pk_f32_fp8_sdwa v[226:227], v68 src0_sel:WORD_1
	v_cvt_pk_f32_fp8_e32 v[228:229], v69
	v_cvt_pk_f32_fp8_sdwa v[230:231], v69 src0_sel:WORD_1
	v_cvt_pk_f32_fp8_e32 v[232:233], v70
	v_cvt_pk_f32_fp8_sdwa v[234:235], v70 src0_sel:WORD_1
	v_cvt_pk_f32_fp8_e32 v[236:237], v71
	v_cvt_pk_f32_fp8_sdwa v[238:239], v71 src0_sel:WORD_1
	v_pk_fma_f32 v[32:33], v[224:225], s[18:19], v[32:33] op_sel_hi:[1,0,1]
	v_pk_fma_f32 v[34:35], v[226:227], s[18:19], v[34:35] op_sel_hi:[1,0,1]
	v_pk_fma_f32 v[36:37], v[228:229], s[18:19], v[36:37] op_sel_hi:[1,0,1]
	v_pk_fma_f32 v[38:39], v[230:231], s[18:19], v[38:39] op_sel_hi:[1,0,1]
	v_pk_fma_f32 v[40:41], v[232:233], s[18:19], v[40:41] op_sel_hi:[1,0,1]
	v_pk_fma_f32 v[42:43], v[234:235], s[18:19], v[42:43] op_sel_hi:[1,0,1]
	v_pk_fma_f32 v[44:45], v[236:237], s[18:19], v[44:45] op_sel_hi:[1,0,1]
	v_pk_fma_f32 v[46:47], v[238:239], s[18:19], v[46:47] op_sel_hi:[1,0,1]
	v_cvt_pk_f32_fp8_e32 v[224:225], v72
	v_cvt_pk_f32_fp8_sdwa v[226:227], v72 src0_sel:WORD_1
	v_cvt_pk_f32_fp8_e32 v[228:229], v73
	v_cvt_pk_f32_fp8_sdwa v[230:231], v73 src0_sel:WORD_1
	v_cvt_pk_f32_fp8_e32 v[232:233], v74
	v_cvt_pk_f32_fp8_sdwa v[234:235], v74 src0_sel:WORD_1
	v_cvt_pk_f32_fp8_e32 v[236:237], v75
	v_cvt_pk_f32_fp8_sdwa v[238:239], v75 src0_sel:WORD_1
; DI void peer_item_v(const Params& p, int item) {
;     ...
;     V_ISSUE(vqa, 0)
; #pragma unroll 1
;     for (int g = 0; g < 16; g += 2) {
;       V_ISSUE(vqb, g + 1)
;       V_CONSUME(vqa, g)
;       if (g + 2 < 16) V_ISSUE(vqa, g + 2)
;       V_CONSUME(vqb, g + 1)
;     }
	v_pk_fma_f32 v[32:33], v[224:225], s[20:21], v[32:33] op_sel_hi:[1,0,1]
	v_pk_fma_f32 v[34:35], v[226:227], s[20:21], v[34:35] op_sel_hi:[1,0,1]
	v_pk_fma_f32 v[36:37], v[228:229], s[20:21], v[36:37] op_sel_hi:[1,0,1]
	v_pk_fma_f32 v[38:39], v[230:231], s[20:21], v[38:39] op_sel_hi:[1,0,1]
	v_pk_fma_f32 v[40:41], v[232:233], s[20:21], v[40:41] op_sel_hi:[1,0,1]
	v_pk_fma_f32 v[42:43], v[234:235], s[20:21], v[42:43] op_sel_hi:[1,0,1]
	v_pk_fma_f32 v[44:45], v[236:237], s[20:21], v[44:45] op_sel_hi:[1,0,1]
	v_pk_fma_f32 v[46:47], v[238:239], s[20:21], v[46:47] op_sel_hi:[1,0,1]
	v_cvt_pk_f32_fp8_e32 v[224:225], v76
	v_cvt_pk_f32_fp8_sdwa v[226:227], v76 src0_sel:WORD_1
	v_cvt_pk_f32_fp8_e32 v[228:229], v77
	v_cvt_pk_f32_fp8_sdwa v[230:231], v77 src0_sel:WORD_1
	v_cvt_pk_f32_fp8_e32 v[232:233], v78
	v_cvt_pk_f32_fp8_sdwa v[234:235], v78 src0_sel:WORD_1
	v_cvt_pk_f32_fp8_e32 v[236:237], v79
	v_cvt_pk_f32_fp8_sdwa v[238:239], v79 src0_sel:WORD_1
	v_pk_fma_f32 v[32:33], v[224:225], s[22:23], v[32:33] op_sel_hi:[1,0,1]
	v_pk_fma_f32 v[34:35], v[226:227], s[22:23], v[34:35] op_sel_hi:[1,0,1]
	v_pk_fma_f32 v[36:37], v[228:229], s[22:23], v[36:37] op_sel_hi:[1,0,1]
	v_pk_fma_f32 v[38:39], v[230:231], s[22:23], v[38:39] op_sel_hi:[1,0,1]
	v_pk_fma_f32 v[40:41], v[232:233], s[22:23], v[40:41] op_sel_hi:[1,0,1]
	v_pk_fma_f32 v[42:43], v[234:235], s[22:23], v[42:43] op_sel_hi:[1,0,1]
	v_pk_fma_f32 v[44:45], v[236:237], s[22:23], v[44:45] op_sel_hi:[1,0,1]
	v_pk_fma_f32 v[46:47], v[238:239], s[22:23], v[46:47] op_sel_hi:[1,0,1]
	v_cvt_pk_f32_fp8_e32 v[224:225], v80
	v_cvt_pk_f32_fp8_sdwa v[226:227], v80 src0_sel:WORD_1
	v_cvt_pk_f32_fp8_e32 v[228:229], v81
	v_cvt_pk_f32_fp8_sdwa v[230:231], v81 src0_sel:WORD_1
	v_cvt_pk_f32_fp8_e32 v[232:233], v82
	v_cvt_pk_f32_fp8_sdwa v[234:235], v82 src0_sel:WORD_1
	v_cvt_pk_f32_fp8_e32 v[236:237], v83
	v_cvt_pk_f32_fp8_sdwa v[238:239], v83 src0_sel:WORD_1
	v_pk_fma_f32 v[32:33], v[224:225], s[24:25], v[32:33] op_sel_hi:[1,0,1]
	v_pk_fma_f32 v[34:35], v[226:227], s[24:25], v[34:35] op_sel_hi:[1,0,1]
	v_pk_fma_f32 v[36:37], v[228:229], s[24:25], v[36:37] op_sel_hi:[1,0,1]
	v_pk_fma_f32 v[38:39], v[230:231], s[24:25], v[38:39] op_sel_hi:[1,0,1]
	v_pk_fma_f32 v[40:41], v[232:233], s[24:25], v[40:41] op_sel_hi:[1,0,1]
	v_pk_fma_f32 v[42:43], v[234:235], s[24:25], v[42:43] op_sel_hi:[1,0,1]
	v_pk_fma_f32 v[44:45], v[236:237], s[24:25], v[44:45] op_sel_hi:[1,0,1]
	v_pk_fma_f32 v[46:47], v[238:239], s[24:25], v[46:47] op_sel_hi:[1,0,1]
	v_cvt_pk_f32_fp8_e32 v[224:225], v84
	v_cvt_pk_f32_fp8_sdwa v[226:227], v84 src0_sel:WORD_1
	v_cvt_pk_f32_fp8_e32 v[228:229], v85
	v_cvt_pk_f32_fp8_sdwa v[230:231], v85 src0_sel:WORD_1
	v_cvt_pk_f32_fp8_e32 v[232:233], v86
	v_cvt_pk_f32_fp8_sdwa v[234:235], v86 src0_sel:WORD_1
	v_cvt_pk_f32_fp8_e32 v[236:237], v87
	v_cvt_pk_f32_fp8_sdwa v[238:239], v87 src0_sel:WORD_1
	v_pk_fma_f32 v[32:33], v[224:225], s[26:27], v[32:33] op_sel_hi:[1,0,1]
	v_pk_fma_f32 v[34:35], v[226:227], s[26:27], v[34:35] op_sel_hi:[1,0,1]
	v_pk_fma_f32 v[36:37], v[228:229], s[26:27], v[36:37] op_sel_hi:[1,0,1]
	v_pk_fma_f32 v[38:39], v[230:231], s[26:27], v[38:39] op_sel_hi:[1,0,1]
	v_pk_fma_f32 v[40:41], v[232:233], s[26:27], v[40:41] op_sel_hi:[1,0,1]
	v_pk_fma_f32 v[42:43], v[234:235], s[26:27], v[42:43] op_sel_hi:[1,0,1]
	v_pk_fma_f32 v[44:45], v[236:237], s[26:27], v[44:45] op_sel_hi:[1,0,1]
	v_pk_fma_f32 v[46:47], v[238:239], s[26:27], v[46:47] op_sel_hi:[1,0,1]
	v_cvt_pk_f32_fp8_e32 v[224:225], v88
	v_cvt_pk_f32_fp8_sdwa v[226:227], v88 src0_sel:WORD_1
	v_cvt_pk_f32_fp8_e32 v[228:229], v89
	v_cvt_pk_f32_fp8_sdwa v[230:231], v89 src0_sel:WORD_1
	v_cvt_pk_f32_fp8_e32 v[232:233], v90
	v_cvt_pk_f32_fp8_sdwa v[234:235], v90 src0_sel:WORD_1
	v_cvt_pk_f32_fp8_e32 v[236:237], v91
	v_cvt_pk_f32_fp8_sdwa v[238:239], v91 src0_sel:WORD_1
	v_pk_fma_f32 v[32:33], v[224:225], s[28:29], v[32:33] op_sel_hi:[1,0,1]
	v_pk_fma_f32 v[34:35], v[226:227], s[28:29], v[34:35] op_sel_hi:[1,0,1]
	v_pk_fma_f32 v[36:37], v[228:229], s[28:29], v[36:37] op_sel_hi:[1,0,1]
	v_pk_fma_f32 v[38:39], v[230:231], s[28:29], v[38:39] op_sel_hi:[1,0,1]
	v_pk_fma_f32 v[40:41], v[232:233], s[28:29], v[40:41] op_sel_hi:[1,0,1]
	v_pk_fma_f32 v[42:43], v[234:235], s[28:29], v[42:43] op_sel_hi:[1,0,1]
	v_pk_fma_f32 v[44:45], v[236:237], s[28:29], v[44:45] op_sel_hi:[1,0,1]
	v_pk_fma_f32 v[46:47], v[238:239], s[28:29], v[46:47] op_sel_hi:[1,0,1]
	v_cvt_pk_f32_fp8_e32 v[224:225], v92
	v_cvt_pk_f32_fp8_sdwa v[226:227], v92 src0_sel:WORD_1
	v_cvt_pk_f32_fp8_e32 v[228:229], v93
	v_cvt_pk_f32_fp8_sdwa v[230:231], v93 src0_sel:WORD_1
	v_cvt_pk_f32_fp8_e32 v[232:233], v94
	v_cvt_pk_f32_fp8_sdwa v[234:235], v94 src0_sel:WORD_1
	v_cvt_pk_f32_fp8_e32 v[236:237], v95
	v_cvt_pk_f32_fp8_sdwa v[238:239], v95 src0_sel:WORD_1
	v_pk_fma_f32 v[32:33], v[224:225], s[30:31], v[32:33] op_sel_hi:[1,0,1]
	v_pk_fma_f32 v[34:35], v[226:227], s[30:31], v[34:35] op_sel_hi:[1,0,1]
	v_pk_fma_f32 v[36:37], v[228:229], s[30:31], v[36:37] op_sel_hi:[1,0,1]
	v_pk_fma_f32 v[38:39], v[230:231], s[30:31], v[38:39] op_sel_hi:[1,0,1]
	v_pk_fma_f32 v[40:41], v[232:233], s[30:31], v[40:41] op_sel_hi:[1,0,1]
	v_pk_fma_f32 v[42:43], v[234:235], s[30:31], v[42:43] op_sel_hi:[1,0,1]
	v_pk_fma_f32 v[44:45], v[236:237], s[30:31], v[44:45] op_sel_hi:[1,0,1]
	v_pk_fma_f32 v[46:47], v[238:239], s[30:31], v[46:47] op_sel_hi:[1,0,1]
	v_readlane_b32 s16, v142, s72
	v_readlane_b32 s18, v142, s73
	v_readlane_b32 s20, v142, s74
	v_readlane_b32 s22, v142, s75
	v_readlane_b32 s24, v142, s76
	v_readlane_b32 s26, v142, s77
	v_readlane_b32 s28, v142, s78
	v_readlane_b32 s30, v142, s79
	v_readlane_b32 s48, v137, s72
	v_readlane_b32 s49, v137, s73
	v_readlane_b32 s50, v137, s74
	v_readlane_b32 s51, v137, s75
	v_readlane_b32 s52, v137, s76
	v_readlane_b32 s53, v137, s77
	v_readlane_b32 s54, v137, s78
	v_readlane_b32 s55, v137, s79
	s_add_u32 s32, s0, s48
	s_addc_u32 s33, s1, 0
	s_add_u32 s34, s0, s49
	s_addc_u32 s35, s1, 0
	s_add_u32 s36, s0, s50
	s_addc_u32 s37, s1, 0
	s_add_u32 s38, s0, s51
	s_addc_u32 s39, s1, 0
	s_add_u32 s40, s0, s52
	s_addc_u32 s41, s1, 0
	s_add_u32 s42, s0, s53
	s_addc_u32 s43, s1, 0
	s_add_u32 s44, s0, s54
	s_addc_u32 s45, s1, 0
	s_add_u32 s46, s0, s55
	s_addc_u32 s47, s1, 0
	global_load_dwordx4 v[64:67], v240, s[32:33]
	global_load_dwordx4 v[68:71], v240, s[34:35]
	global_load_dwordx4 v[72:75], v240, s[36:37]
	global_load_dwordx4 v[76:79], v240, s[38:39]
	global_load_dwordx4 v[80:83], v240, s[40:41]
	global_load_dwordx4 v[84:87], v240, s[42:43]
	global_load_dwordx4 v[88:91], v240, s[44:45]
	global_load_dwordx4 v[92:95], v240, s[46:47]
	s_waitcnt vmcnt(24)
	v_cvt_pk_f32_fp8_e32 v[224:225], v96
	v_cvt_pk_f32_fp8_sdwa v[226:227], v96 src0_sel:WORD_1
	v_cvt_pk_f32_fp8_e32 v[228:229], v97
	v_cvt_pk_f32_fp8_sdwa v[230:231], v97 src0_sel:WORD_1
	v_cvt_pk_f32_fp8_e32 v[232:233], v98
	v_cvt_pk_f32_fp8_sdwa v[234:235], v98 src0_sel:WORD_1
	v_cvt_pk_f32_fp8_e32 v[236:237], v99
	v_cvt_pk_f32_fp8_sdwa v[238:239], v99 src0_sel:WORD_1
	v_pk_fma_f32 v[48:49], v[224:225], s[16:17], v[48:49] op_sel_hi:[1,0,1]
	v_pk_fma_f32 v[50:51], v[226:227], s[16:17], v[50:51] op_sel_hi:[1,0,1]
	v_pk_fma_f32 v[52:53], v[228:229], s[16:17], v[52:53] op_sel_hi:[1,0,1]
	v_pk_fma_f32 v[54:55], v[230:231], s[16:17], v[54:55] op_sel_hi:[1,0,1]
	v_pk_fma_f32 v[56:57], v[232:233], s[16:17], v[56:57] op_sel_hi:[1,0,1]
	v_pk_fma_f32 v[58:59], v[234:235], s[16:17], v[58:59] op_sel_hi:[1,0,1]
	v_pk_fma_f32 v[60:61], v[236:237], s[16:17], v[60:61] op_sel_hi:[1,0,1]
	v_pk_fma_f32 v[62:63], v[238:239], s[16:17], v[62:63] op_sel_hi:[1,0,1]
	v_cvt_pk_f32_fp8_e32 v[224:225], v100
	v_cvt_pk_f32_fp8_sdwa v[226:227], v100 src0_sel:WORD_1
	v_cvt_pk_f32_fp8_e32 v[228:229], v101
	v_cvt_pk_f32_fp8_sdwa v[230:231], v101 src0_sel:WORD_1
	v_cvt_pk_f32_fp8_e32 v[232:233], v102
	v_cvt_pk_f32_fp8_sdwa v[234:235], v102 src0_sel:WORD_1
	v_cvt_pk_f32_fp8_e32 v[236:237], v103
	v_cvt_pk_f32_fp8_sdwa v[238:239], v103 src0_sel:WORD_1
	v_pk_fma_f32 v[48:49], v[224:225], s[18:19], v[48:49] op_sel_hi:[1,0,1]
	v_pk_fma_f32 v[50:51], v[226:227], s[18:19], v[50:51] op_sel_hi:[1,0,1]
	v_pk_fma_f32 v[52:53], v[228:229], s[18:19], v[52:53] op_sel_hi:[1,0,1]
	v_pk_fma_f32 v[54:55], v[230:231], s[18:19], v[54:55] op_sel_hi:[1,0,1]
	v_pk_fma_f32 v[56:57], v[232:233], s[18:19], v[56:57] op_sel_hi:[1,0,1]
	v_pk_fma_f32 v[58:59], v[234:235], s[18:19], v[58:59] op_sel_hi:[1,0,1]
	v_pk_fma_f32 v[60:61], v[236:237], s[18:19], v[60:61] op_sel_hi:[1,0,1]
	v_pk_fma_f32 v[62:63], v[238:239], s[18:19], v[62:63] op_sel_hi:[1,0,1]
	v_cvt_pk_f32_fp8_e32 v[224:225], v104
	v_cvt_pk_f32_fp8_sdwa v[226:227], v104 src0_sel:WORD_1
	v_cvt_pk_f32_fp8_e32 v[228:229], v105
	v_cvt_pk_f32_fp8_sdwa v[230:231], v105 src0_sel:WORD_1
	v_cvt_pk_f32_fp8_e32 v[232:233], v106
	v_cvt_pk_f32_fp8_sdwa v[234:235], v106 src0_sel:WORD_1
	v_cvt_pk_f32_fp8_e32 v[236:237], v107
	v_cvt_pk_f32_fp8_sdwa v[238:239], v107 src0_sel:WORD_1
	v_pk_fma_f32 v[48:49], v[224:225], s[20:21], v[48:49] op_sel_hi:[1,0,1]
	v_pk_fma_f32 v[50:51], v[226:227], s[20:21], v[50:51] op_sel_hi:[1,0,1]
	v_pk_fma_f32 v[52:53], v[228:229], s[20:21], v[52:53] op_sel_hi:[1,0,1]
	v_pk_fma_f32 v[54:55], v[230:231], s[20:21], v[54:55] op_sel_hi:[1,0,1]
	v_pk_fma_f32 v[56:57], v[232:233], s[20:21], v[56:57] op_sel_hi:[1,0,1]
	v_pk_fma_f32 v[58:59], v[234:235], s[20:21], v[58:59] op_sel_hi:[1,0,1]
	v_pk_fma_f32 v[60:61], v[236:237], s[20:21], v[60:61] op_sel_hi:[1,0,1]
	v_pk_fma_f32 v[62:63], v[238:239], s[20:21], v[62:63] op_sel_hi:[1,0,1]
	v_cvt_pk_f32_fp8_e32 v[224:225], v108
	v_cvt_pk_f32_fp8_sdwa v[226:227], v108 src0_sel:WORD_1
	v_cvt_pk_f32_fp8_e32 v[228:229], v109
	v_cvt_pk_f32_fp8_sdwa v[230:231], v109 src0_sel:WORD_1
	v_cvt_pk_f32_fp8_e32 v[232:233], v110
	v_cvt_pk_f32_fp8_sdwa v[234:235], v110 src0_sel:WORD_1
	v_cvt_pk_f32_fp8_e32 v[236:237], v111
	v_cvt_pk_f32_fp8_sdwa v[238:239], v111 src0_sel:WORD_1
	v_pk_fma_f32 v[48:49], v[224:225], s[22:23], v[48:49] op_sel_hi:[1,0,1]
	v_pk_fma_f32 v[50:51], v[226:227], s[22:23], v[50:51] op_sel_hi:[1,0,1]
	v_pk_fma_f32 v[52:53], v[228:229], s[22:23], v[52:53] op_sel_hi:[1,0,1]
	v_pk_fma_f32 v[54:55], v[230:231], s[22:23], v[54:55] op_sel_hi:[1,0,1]
	v_pk_fma_f32 v[56:57], v[232:233], s[22:23], v[56:57] op_sel_hi:[1,0,1]
	v_pk_fma_f32 v[58:59], v[234:235], s[22:23], v[58:59] op_sel_hi:[1,0,1]
	v_pk_fma_f32 v[60:61], v[236:237], s[22:23], v[60:61] op_sel_hi:[1,0,1]
	v_pk_fma_f32 v[62:63], v[238:239], s[22:23], v[62:63] op_sel_hi:[1,0,1]
	v_cvt_pk_f32_fp8_e32 v[224:225], v112
	v_cvt_pk_f32_fp8_sdwa v[226:227], v112 src0_sel:WORD_1
	v_cvt_pk_f32_fp8_e32 v[228:229], v113
	v_cvt_pk_f32_fp8_sdwa v[230:231], v113 src0_sel:WORD_1
	v_cvt_pk_f32_fp8_e32 v[232:233], v114
	v_cvt_pk_f32_fp8_sdwa v[234:235], v114 src0_sel:WORD_1
	v_cvt_pk_f32_fp8_e32 v[236:237], v115
	v_cvt_pk_f32_fp8_sdwa v[238:239], v115 src0_sel:WORD_1
	v_pk_fma_f32 v[48:49], v[224:225], s[24:25], v[48:49] op_sel_hi:[1,0,1]
	v_pk_fma_f32 v[50:51], v[226:227], s[24:25], v[50:51] op_sel_hi:[1,0,1]
	v_pk_fma_f32 v[52:53], v[228:229], s[24:25], v[52:53] op_sel_hi:[1,0,1]
	v_pk_fma_f32 v[54:55], v[230:231], s[24:25], v[54:55] op_sel_hi:[1,0,1]
	v_pk_fma_f32 v[56:57], v[232:233], s[24:25], v[56:57] op_sel_hi:[1,0,1]
	v_pk_fma_f32 v[58:59], v[234:235], s[24:25], v[58:59] op_sel_hi:[1,0,1]
	v_pk_fma_f32 v[60:61], v[236:237], s[24:25], v[60:61] op_sel_hi:[1,0,1]
	v_pk_fma_f32 v[62:63], v[238:239], s[24:25], v[62:63] op_sel_hi:[1,0,1]
	v_cvt_pk_f32_fp8_e32 v[224:225], v116
	v_cvt_pk_f32_fp8_sdwa v[226:227], v116 src0_sel:WORD_1
	v_cvt_pk_f32_fp8_e32 v[228:229], v117
	v_cvt_pk_f32_fp8_sdwa v[230:231], v117 src0_sel:WORD_1
	v_cvt_pk_f32_fp8_e32 v[232:233], v118
	v_cvt_pk_f32_fp8_sdwa v[234:235], v118 src0_sel:WORD_1
	v_cvt_pk_f32_fp8_e32 v[236:237], v119
	v_cvt_pk_f32_fp8_sdwa v[238:239], v119 src0_sel:WORD_1
	v_pk_fma_f32 v[48:49], v[224:225], s[26:27], v[48:49] op_sel_hi:[1,0,1]
	v_pk_fma_f32 v[50:51], v[226:227], s[26:27], v[50:51] op_sel_hi:[1,0,1]
	v_pk_fma_f32 v[52:53], v[228:229], s[26:27], v[52:53] op_sel_hi:[1,0,1]
	v_pk_fma_f32 v[54:55], v[230:231], s[26:27], v[54:55] op_sel_hi:[1,0,1]
	v_pk_fma_f32 v[56:57], v[232:233], s[26:27], v[56:57] op_sel_hi:[1,0,1]
	v_pk_fma_f32 v[58:59], v[234:235], s[26:27], v[58:59] op_sel_hi:[1,0,1]
	v_pk_fma_f32 v[60:61], v[236:237], s[26:27], v[60:61] op_sel_hi:[1,0,1]
	v_pk_fma_f32 v[62:63], v[238:239], s[26:27], v[62:63] op_sel_hi:[1,0,1]
	v_cvt_pk_f32_fp8_e32 v[224:225], v120
	v_cvt_pk_f32_fp8_sdwa v[226:227], v120 src0_sel:WORD_1
	v_cvt_pk_f32_fp8_e32 v[228:229], v121
	v_cvt_pk_f32_fp8_sdwa v[230:231], v121 src0_sel:WORD_1
	v_cvt_pk_f32_fp8_e32 v[232:233], v122
	v_cvt_pk_f32_fp8_sdwa v[234:235], v122 src0_sel:WORD_1
	v_cvt_pk_f32_fp8_e32 v[236:237], v123
	v_cvt_pk_f32_fp8_sdwa v[238:239], v123 src0_sel:WORD_1
	v_pk_fma_f32 v[48:49], v[224:225], s[28:29], v[48:49] op_sel_hi:[1,0,1]
	v_pk_fma_f32 v[50:51], v[226:227], s[28:29], v[50:51] op_sel_hi:[1,0,1]
	v_pk_fma_f32 v[52:53], v[228:229], s[28:29], v[52:53] op_sel_hi:[1,0,1]
	v_pk_fma_f32 v[54:55], v[230:231], s[28:29], v[54:55] op_sel_hi:[1,0,1]
	v_pk_fma_f32 v[56:57], v[232:233], s[28:29], v[56:57] op_sel_hi:[1,0,1]
	v_pk_fma_f32 v[58:59], v[234:235], s[28:29], v[58:59] op_sel_hi:[1,0,1]
	v_pk_fma_f32 v[60:61], v[236:237], s[28:29], v[60:61] op_sel_hi:[1,0,1]
	v_pk_fma_f32 v[62:63], v[238:239], s[28:29], v[62:63] op_sel_hi:[1,0,1]
	v_cvt_pk_f32_fp8_e32 v[224:225], v124
	v_cvt_pk_f32_fp8_sdwa v[226:227], v124 src0_sel:WORD_1
	v_cvt_pk_f32_fp8_e32 v[228:229], v125
	v_cvt_pk_f32_fp8_sdwa v[230:231], v125 src0_sel:WORD_1
	v_cvt_pk_f32_fp8_e32 v[232:233], v126
	v_cvt_pk_f32_fp8_sdwa v[234:235], v126 src0_sel:WORD_1
	v_cvt_pk_f32_fp8_e32 v[236:237], v127
	v_cvt_pk_f32_fp8_sdwa v[238:239], v127 src0_sel:WORD_1
	v_pk_fma_f32 v[48:49], v[224:225], s[30:31], v[48:49] op_sel_hi:[1,0,1]
	v_pk_fma_f32 v[50:51], v[226:227], s[30:31], v[50:51] op_sel_hi:[1,0,1]
	v_pk_fma_f32 v[52:53], v[228:229], s[30:31], v[52:53] op_sel_hi:[1,0,1]
	v_pk_fma_f32 v[54:55], v[230:231], s[30:31], v[54:55] op_sel_hi:[1,0,1]
	v_pk_fma_f32 v[56:57], v[232:233], s[30:31], v[56:57] op_sel_hi:[1,0,1]
	v_pk_fma_f32 v[58:59], v[234:235], s[30:31], v[58:59] op_sel_hi:[1,0,1]
	v_pk_fma_f32 v[60:61], v[236:237], s[30:31], v[60:61] op_sel_hi:[1,0,1]
	v_pk_fma_f32 v[62:63], v[238:239], s[30:31], v[62:63] op_sel_hi:[1,0,1]
	v_readlane_b32 s16, v131, s72
	v_readlane_b32 s18, v131, s73
	v_readlane_b32 s20, v131, s74
	v_readlane_b32 s22, v131, s75
	v_readlane_b32 s24, v131, s76
	v_readlane_b32 s26, v131, s77
	v_readlane_b32 s28, v131, s78
	v_readlane_b32 s30, v131, s79
	v_readlane_b32 s48, v141, s72
	v_readlane_b32 s49, v141, s73
	v_readlane_b32 s50, v141, s74
	v_readlane_b32 s51, v141, s75
	v_readlane_b32 s52, v141, s76
	v_readlane_b32 s53, v141, s77
	v_readlane_b32 s54, v141, s78
	v_readlane_b32 s55, v141, s79
	s_add_u32 s32, s0, s48
	s_addc_u32 s33, s1, 0
	s_add_u32 s34, s0, s49
	s_addc_u32 s35, s1, 0
	s_add_u32 s36, s0, s50
	s_addc_u32 s37, s1, 0
	s_add_u32 s38, s0, s51
	s_addc_u32 s39, s1, 0
	s_add_u32 s40, s0, s52
	s_addc_u32 s41, s1, 0
	s_add_u32 s42, s0, s53
	s_addc_u32 s43, s1, 0
	s_add_u32 s44, s0, s54
	s_addc_u32 s45, s1, 0
	s_add_u32 s46, s0, s55
	s_addc_u32 s47, s1, 0
	global_load_dwordx4 v[96:99], v240, s[32:33]
	global_load_dwordx4 v[100:103], v240, s[34:35]
	global_load_dwordx4 v[104:107], v240, s[36:37]
	global_load_dwordx4 v[108:111], v240, s[38:39]
	global_load_dwordx4 v[112:115], v240, s[40:41]
	global_load_dwordx4 v[116:119], v240, s[42:43]
	global_load_dwordx4 v[120:123], v240, s[44:45]
	global_load_dwordx4 v[124:127], v240, s[46:47]
	s_waitcnt vmcnt(24)
	v_cvt_pk_f32_fp8_e32 v[224:225], v160
	v_cvt_pk_f32_fp8_sdwa v[226:227], v160 src0_sel:WORD_1
	v_cvt_pk_f32_fp8_e32 v[228:229], v161
	v_cvt_pk_f32_fp8_sdwa v[230:231], v161 src0_sel:WORD_1
	v_cvt_pk_f32_fp8_e32 v[232:233], v162
	v_cvt_pk_f32_fp8_sdwa v[234:235], v162 src0_sel:WORD_1
	v_cvt_pk_f32_fp8_e32 v[236:237], v163
	v_cvt_pk_f32_fp8_sdwa v[238:239], v163 src0_sel:WORD_1
	v_pk_fma_f32 v[0:1], v[224:225], s[16:17], v[0:1] op_sel_hi:[1,0,1]
	v_pk_fma_f32 v[2:3], v[226:227], s[16:17], v[2:3] op_sel_hi:[1,0,1]
	v_pk_fma_f32 v[4:5], v[228:229], s[16:17], v[4:5] op_sel_hi:[1,0,1]
	v_pk_fma_f32 v[6:7], v[230:231], s[16:17], v[6:7] op_sel_hi:[1,0,1]
	v_pk_fma_f32 v[8:9], v[232:233], s[16:17], v[8:9] op_sel_hi:[1,0,1]
	v_pk_fma_f32 v[10:11], v[234:235], s[16:17], v[10:11] op_sel_hi:[1,0,1]
	v_pk_fma_f32 v[12:13], v[236:237], s[16:17], v[12:13] op_sel_hi:[1,0,1]
	v_pk_fma_f32 v[14:15], v[238:239], s[16:17], v[14:15] op_sel_hi:[1,0,1]
	v_cvt_pk_f32_fp8_e32 v[224:225], v164
	v_cvt_pk_f32_fp8_sdwa v[226:227], v164 src0_sel:WORD_1
	v_cvt_pk_f32_fp8_e32 v[228:229], v165
	v_cvt_pk_f32_fp8_sdwa v[230:231], v165 src0_sel:WORD_1
	v_cvt_pk_f32_fp8_e32 v[232:233], v166
	v_cvt_pk_f32_fp8_sdwa v[234:235], v166 src0_sel:WORD_1
	v_cvt_pk_f32_fp8_e32 v[236:237], v167
	v_cvt_pk_f32_fp8_sdwa v[238:239], v167 src0_sel:WORD_1
	v_pk_fma_f32 v[0:1], v[224:225], s[18:19], v[0:1] op_sel_hi:[1,0,1]
	v_pk_fma_f32 v[2:3], v[226:227], s[18:19], v[2:3] op_sel_hi:[1,0,1]
	v_pk_fma_f32 v[4:5], v[228:229], s[18:19], v[4:5] op_sel_hi:[1,0,1]
	v_pk_fma_f32 v[6:7], v[230:231], s[18:19], v[6:7] op_sel_hi:[1,0,1]
	v_pk_fma_f32 v[8:9], v[232:233], s[18:19], v[8:9] op_sel_hi:[1,0,1]
	v_pk_fma_f32 v[10:11], v[234:235], s[18:19], v[10:11] op_sel_hi:[1,0,1]
	v_pk_fma_f32 v[12:13], v[236:237], s[18:19], v[12:13] op_sel_hi:[1,0,1]
	v_pk_fma_f32 v[14:15], v[238:239], s[18:19], v[14:15] op_sel_hi:[1,0,1]
	v_cvt_pk_f32_fp8_e32 v[224:225], v168
	v_cvt_pk_f32_fp8_sdwa v[226:227], v168 src0_sel:WORD_1
	v_cvt_pk_f32_fp8_e32 v[228:229], v169
	v_cvt_pk_f32_fp8_sdwa v[230:231], v169 src0_sel:WORD_1
	v_cvt_pk_f32_fp8_e32 v[232:233], v170
	v_cvt_pk_f32_fp8_sdwa v[234:235], v170 src0_sel:WORD_1
	v_cvt_pk_f32_fp8_e32 v[236:237], v171
	v_cvt_pk_f32_fp8_sdwa v[238:239], v171 src0_sel:WORD_1
	v_pk_fma_f32 v[0:1], v[224:225], s[20:21], v[0:1] op_sel_hi:[1,0,1]
	v_pk_fma_f32 v[2:3], v[226:227], s[20:21], v[2:3] op_sel_hi:[1,0,1]
	v_pk_fma_f32 v[4:5], v[228:229], s[20:21], v[4:5] op_sel_hi:[1,0,1]
	v_pk_fma_f32 v[6:7], v[230:231], s[20:21], v[6:7] op_sel_hi:[1,0,1]
	v_pk_fma_f32 v[8:9], v[232:233], s[20:21], v[8:9] op_sel_hi:[1,0,1]
	v_pk_fma_f32 v[10:11], v[234:235], s[20:21], v[10:11] op_sel_hi:[1,0,1]
	v_pk_fma_f32 v[12:13], v[236:237], s[20:21], v[12:13] op_sel_hi:[1,0,1]
	v_pk_fma_f32 v[14:15], v[238:239], s[20:21], v[14:15] op_sel_hi:[1,0,1]
	v_cvt_pk_f32_fp8_e32 v[224:225], v172
	v_cvt_pk_f32_fp8_sdwa v[226:227], v172 src0_sel:WORD_1
	v_cvt_pk_f32_fp8_e32 v[228:229], v173
	v_cvt_pk_f32_fp8_sdwa v[230:231], v173 src0_sel:WORD_1
	v_cvt_pk_f32_fp8_e32 v[232:233], v174
	v_cvt_pk_f32_fp8_sdwa v[234:235], v174 src0_sel:WORD_1
	v_cvt_pk_f32_fp8_e32 v[236:237], v175
	v_cvt_pk_f32_fp8_sdwa v[238:239], v175 src0_sel:WORD_1
	v_pk_fma_f32 v[0:1], v[224:225], s[22:23], v[0:1] op_sel_hi:[1,0,1]
	v_pk_fma_f32 v[2:3], v[226:227], s[22:23], v[2:3] op_sel_hi:[1,0,1]
	v_pk_fma_f32 v[4:5], v[228:229], s[22:23], v[4:5] op_sel_hi:[1,0,1]
	v_pk_fma_f32 v[6:7], v[230:231], s[22:23], v[6:7] op_sel_hi:[1,0,1]
	v_pk_fma_f32 v[8:9], v[232:233], s[22:23], v[8:9] op_sel_hi:[1,0,1]
	v_pk_fma_f32 v[10:11], v[234:235], s[22:23], v[10:11] op_sel_hi:[1,0,1]
	v_pk_fma_f32 v[12:13], v[236:237], s[22:23], v[12:13] op_sel_hi:[1,0,1]
	v_pk_fma_f32 v[14:15], v[238:239], s[22:23], v[14:15] op_sel_hi:[1,0,1]
	v_cvt_pk_f32_fp8_e32 v[224:225], v176
	v_cvt_pk_f32_fp8_sdwa v[226:227], v176 src0_sel:WORD_1
	v_cvt_pk_f32_fp8_e32 v[228:229], v177
	v_cvt_pk_f32_fp8_sdwa v[230:231], v177 src0_sel:WORD_1
	v_cvt_pk_f32_fp8_e32 v[232:233], v178
	v_cvt_pk_f32_fp8_sdwa v[234:235], v178 src0_sel:WORD_1
	v_cvt_pk_f32_fp8_e32 v[236:237], v179
	v_cvt_pk_f32_fp8_sdwa v[238:239], v179 src0_sel:WORD_1
	v_pk_fma_f32 v[0:1], v[224:225], s[24:25], v[0:1] op_sel_hi:[1,0,1]
	v_pk_fma_f32 v[2:3], v[226:227], s[24:25], v[2:3] op_sel_hi:[1,0,1]
	v_pk_fma_f32 v[4:5], v[228:229], s[24:25], v[4:5] op_sel_hi:[1,0,1]
	v_pk_fma_f32 v[6:7], v[230:231], s[24:25], v[6:7] op_sel_hi:[1,0,1]
	v_pk_fma_f32 v[8:9], v[232:233], s[24:25], v[8:9] op_sel_hi:[1,0,1]
	v_pk_fma_f32 v[10:11], v[234:235], s[24:25], v[10:11] op_sel_hi:[1,0,1]
	v_pk_fma_f32 v[12:13], v[236:237], s[24:25], v[12:13] op_sel_hi:[1,0,1]
	v_pk_fma_f32 v[14:15], v[238:239], s[24:25], v[14:15] op_sel_hi:[1,0,1]
	v_cvt_pk_f32_fp8_e32 v[224:225], v180
	v_cvt_pk_f32_fp8_sdwa v[226:227], v180 src0_sel:WORD_1
	v_cvt_pk_f32_fp8_e32 v[228:229], v181
	v_cvt_pk_f32_fp8_sdwa v[230:231], v181 src0_sel:WORD_1
	v_cvt_pk_f32_fp8_e32 v[232:233], v182
	v_cvt_pk_f32_fp8_sdwa v[234:235], v182 src0_sel:WORD_1
	v_cvt_pk_f32_fp8_e32 v[236:237], v183
	v_cvt_pk_f32_fp8_sdwa v[238:239], v183 src0_sel:WORD_1
	v_pk_fma_f32 v[0:1], v[224:225], s[26:27], v[0:1] op_sel_hi:[1,0,1]
	v_pk_fma_f32 v[2:3], v[226:227], s[26:27], v[2:3] op_sel_hi:[1,0,1]
	v_pk_fma_f32 v[4:5], v[228:229], s[26:27], v[4:5] op_sel_hi:[1,0,1]
	v_pk_fma_f32 v[6:7], v[230:231], s[26:27], v[6:7] op_sel_hi:[1,0,1]
	v_pk_fma_f32 v[8:9], v[232:233], s[26:27], v[8:9] op_sel_hi:[1,0,1]
	v_pk_fma_f32 v[10:11], v[234:235], s[26:27], v[10:11] op_sel_hi:[1,0,1]
	v_pk_fma_f32 v[12:13], v[236:237], s[26:27], v[12:13] op_sel_hi:[1,0,1]
	v_pk_fma_f32 v[14:15], v[238:239], s[26:27], v[14:15] op_sel_hi:[1,0,1]
	v_cvt_pk_f32_fp8_e32 v[224:225], v184
	v_cvt_pk_f32_fp8_sdwa v[226:227], v184 src0_sel:WORD_1
	v_cvt_pk_f32_fp8_e32 v[228:229], v185
	v_cvt_pk_f32_fp8_sdwa v[230:231], v185 src0_sel:WORD_1
	v_cvt_pk_f32_fp8_e32 v[232:233], v186
	v_cvt_pk_f32_fp8_sdwa v[234:235], v186 src0_sel:WORD_1
	v_cvt_pk_f32_fp8_e32 v[236:237], v187
	v_cvt_pk_f32_fp8_sdwa v[238:239], v187 src0_sel:WORD_1
	v_pk_fma_f32 v[0:1], v[224:225], s[28:29], v[0:1] op_sel_hi:[1,0,1]
	v_pk_fma_f32 v[2:3], v[226:227], s[28:29], v[2:3] op_sel_hi:[1,0,1]
	v_pk_fma_f32 v[4:5], v[228:229], s[28:29], v[4:5] op_sel_hi:[1,0,1]
	v_pk_fma_f32 v[6:7], v[230:231], s[28:29], v[6:7] op_sel_hi:[1,0,1]
	v_pk_fma_f32 v[8:9], v[232:233], s[28:29], v[8:9] op_sel_hi:[1,0,1]
	v_pk_fma_f32 v[10:11], v[234:235], s[28:29], v[10:11] op_sel_hi:[1,0,1]
	v_pk_fma_f32 v[12:13], v[236:237], s[28:29], v[12:13] op_sel_hi:[1,0,1]
	v_pk_fma_f32 v[14:15], v[238:239], s[28:29], v[14:15] op_sel_hi:[1,0,1]
	v_cvt_pk_f32_fp8_e32 v[224:225], v188
	v_cvt_pk_f32_fp8_sdwa v[226:227], v188 src0_sel:WORD_1
	v_cvt_pk_f32_fp8_e32 v[228:229], v189
	v_cvt_pk_f32_fp8_sdwa v[230:231], v189 src0_sel:WORD_1
	v_cvt_pk_f32_fp8_e32 v[232:233], v190
	v_cvt_pk_f32_fp8_sdwa v[234:235], v190 src0_sel:WORD_1
	v_cvt_pk_f32_fp8_e32 v[236:237], v191
	v_cvt_pk_f32_fp8_sdwa v[238:239], v191 src0_sel:WORD_1
	v_pk_fma_f32 v[0:1], v[224:225], s[30:31], v[0:1] op_sel_hi:[1,0,1]
	v_pk_fma_f32 v[2:3], v[226:227], s[30:31], v[2:3] op_sel_hi:[1,0,1]
	v_pk_fma_f32 v[4:5], v[228:229], s[30:31], v[4:5] op_sel_hi:[1,0,1]
	v_pk_fma_f32 v[6:7], v[230:231], s[30:31], v[6:7] op_sel_hi:[1,0,1]
	v_pk_fma_f32 v[8:9], v[232:233], s[30:31], v[8:9] op_sel_hi:[1,0,1]
	v_pk_fma_f32 v[10:11], v[234:235], s[30:31], v[10:11] op_sel_hi:[1,0,1]
	v_pk_fma_f32 v[12:13], v[236:237], s[30:31], v[12:13] op_sel_hi:[1,0,1]
	v_pk_fma_f32 v[14:15], v[238:239], s[30:31], v[14:15] op_sel_hi:[1,0,1]
	v_readlane_b32 s16, v135, s72
	v_readlane_b32 s18, v135, s73
	v_readlane_b32 s20, v135, s74
	v_readlane_b32 s22, v135, s75
	v_readlane_b32 s24, v135, s76
	v_readlane_b32 s26, v135, s77
	v_readlane_b32 s28, v135, s78
	v_readlane_b32 s30, v135, s79
	v_readlane_b32 s48, v128, s80
	v_readlane_b32 s49, v128, s81
	v_readlane_b32 s50, v128, s82
	v_readlane_b32 s51, v128, s83
	v_readlane_b32 s52, v128, s84
	v_readlane_b32 s53, v128, s85
	v_readlane_b32 s54, v128, s86
	v_readlane_b32 s55, v128, s87
	s_add_u32 s32, s0, s48
	s_addc_u32 s33, s1, 0
	s_add_u32 s34, s0, s49
	s_addc_u32 s35, s1, 0
	s_add_u32 s36, s0, s50
	s_addc_u32 s37, s1, 0
	s_add_u32 s38, s0, s51
	s_addc_u32 s39, s1, 0
	s_add_u32 s40, s0, s52
	s_addc_u32 s41, s1, 0
	s_add_u32 s42, s0, s53
	s_addc_u32 s43, s1, 0
	s_add_u32 s44, s0, s54
	s_addc_u32 s45, s1, 0
	s_add_u32 s46, s0, s55
	s_addc_u32 s47, s1, 0
	global_load_dwordx4 v[160:163], v240, s[32:33]
	global_load_dwordx4 v[164:167], v240, s[34:35]
	global_load_dwordx4 v[168:171], v240, s[36:37]
	global_load_dwordx4 v[172:175], v240, s[38:39]
	global_load_dwordx4 v[176:179], v240, s[40:41]
	global_load_dwordx4 v[180:183], v240, s[42:43]
	global_load_dwordx4 v[184:187], v240, s[44:45]
	global_load_dwordx4 v[188:191], v240, s[46:47]
	s_waitcnt vmcnt(24)
	v_cvt_pk_f32_fp8_e32 v[224:225], v192
	v_cvt_pk_f32_fp8_sdwa v[226:227], v192 src0_sel:WORD_1
	v_cvt_pk_f32_fp8_e32 v[228:229], v193
	v_cvt_pk_f32_fp8_sdwa v[230:231], v193 src0_sel:WORD_1
	v_cvt_pk_f32_fp8_e32 v[232:233], v194
	v_cvt_pk_f32_fp8_sdwa v[234:235], v194 src0_sel:WORD_1
	v_cvt_pk_f32_fp8_e32 v[236:237], v195
	v_cvt_pk_f32_fp8_sdwa v[238:239], v195 src0_sel:WORD_1
	v_pk_fma_f32 v[16:17], v[224:225], s[16:17], v[16:17] op_sel_hi:[1,0,1]
	v_pk_fma_f32 v[18:19], v[226:227], s[16:17], v[18:19] op_sel_hi:[1,0,1]
	v_pk_fma_f32 v[20:21], v[228:229], s[16:17], v[20:21] op_sel_hi:[1,0,1]
	v_pk_fma_f32 v[22:23], v[230:231], s[16:17], v[22:23] op_sel_hi:[1,0,1]
	v_pk_fma_f32 v[24:25], v[232:233], s[16:17], v[24:25] op_sel_hi:[1,0,1]
	v_pk_fma_f32 v[26:27], v[234:235], s[16:17], v[26:27] op_sel_hi:[1,0,1]
	v_pk_fma_f32 v[28:29], v[236:237], s[16:17], v[28:29] op_sel_hi:[1,0,1]
	v_pk_fma_f32 v[30:31], v[238:239], s[16:17], v[30:31] op_sel_hi:[1,0,1]
	v_cvt_pk_f32_fp8_e32 v[224:225], v196
	v_cvt_pk_f32_fp8_sdwa v[226:227], v196 src0_sel:WORD_1
	v_cvt_pk_f32_fp8_e32 v[228:229], v197
	v_cvt_pk_f32_fp8_sdwa v[230:231], v197 src0_sel:WORD_1
	v_cvt_pk_f32_fp8_e32 v[232:233], v198
	v_cvt_pk_f32_fp8_sdwa v[234:235], v198 src0_sel:WORD_1
	v_cvt_pk_f32_fp8_e32 v[236:237], v199
	v_cvt_pk_f32_fp8_sdwa v[238:239], v199 src0_sel:WORD_1
	v_pk_fma_f32 v[16:17], v[224:225], s[18:19], v[16:17] op_sel_hi:[1,0,1]
	v_pk_fma_f32 v[18:19], v[226:227], s[18:19], v[18:19] op_sel_hi:[1,0,1]
	v_pk_fma_f32 v[20:21], v[228:229], s[18:19], v[20:21] op_sel_hi:[1,0,1]
	v_pk_fma_f32 v[22:23], v[230:231], s[18:19], v[22:23] op_sel_hi:[1,0,1]
	v_pk_fma_f32 v[24:25], v[232:233], s[18:19], v[24:25] op_sel_hi:[1,0,1]
	v_pk_fma_f32 v[26:27], v[234:235], s[18:19], v[26:27] op_sel_hi:[1,0,1]
	v_pk_fma_f32 v[28:29], v[236:237], s[18:19], v[28:29] op_sel_hi:[1,0,1]
	v_pk_fma_f32 v[30:31], v[238:239], s[18:19], v[30:31] op_sel_hi:[1,0,1]
	v_cvt_pk_f32_fp8_e32 v[224:225], v200
	v_cvt_pk_f32_fp8_sdwa v[226:227], v200 src0_sel:WORD_1
	v_cvt_pk_f32_fp8_e32 v[228:229], v201
	v_cvt_pk_f32_fp8_sdwa v[230:231], v201 src0_sel:WORD_1
	v_cvt_pk_f32_fp8_e32 v[232:233], v202
	v_cvt_pk_f32_fp8_sdwa v[234:235], v202 src0_sel:WORD_1
	v_cvt_pk_f32_fp8_e32 v[236:237], v203
	v_cvt_pk_f32_fp8_sdwa v[238:239], v203 src0_sel:WORD_1
	v_pk_fma_f32 v[16:17], v[224:225], s[20:21], v[16:17] op_sel_hi:[1,0,1]
	v_pk_fma_f32 v[18:19], v[226:227], s[20:21], v[18:19] op_sel_hi:[1,0,1]
	v_pk_fma_f32 v[20:21], v[228:229], s[20:21], v[20:21] op_sel_hi:[1,0,1]
	v_pk_fma_f32 v[22:23], v[230:231], s[20:21], v[22:23] op_sel_hi:[1,0,1]
	v_pk_fma_f32 v[24:25], v[232:233], s[20:21], v[24:25] op_sel_hi:[1,0,1]
	v_pk_fma_f32 v[26:27], v[234:235], s[20:21], v[26:27] op_sel_hi:[1,0,1]
	v_pk_fma_f32 v[28:29], v[236:237], s[20:21], v[28:29] op_sel_hi:[1,0,1]
	v_pk_fma_f32 v[30:31], v[238:239], s[20:21], v[30:31] op_sel_hi:[1,0,1]
	v_cvt_pk_f32_fp8_e32 v[224:225], v204
	v_cvt_pk_f32_fp8_sdwa v[226:227], v204 src0_sel:WORD_1
	v_cvt_pk_f32_fp8_e32 v[228:229], v205
	v_cvt_pk_f32_fp8_sdwa v[230:231], v205 src0_sel:WORD_1
	v_cvt_pk_f32_fp8_e32 v[232:233], v206
	v_cvt_pk_f32_fp8_sdwa v[234:235], v206 src0_sel:WORD_1
	v_cvt_pk_f32_fp8_e32 v[236:237], v207
	v_cvt_pk_f32_fp8_sdwa v[238:239], v207 src0_sel:WORD_1
	v_pk_fma_f32 v[16:17], v[224:225], s[22:23], v[16:17] op_sel_hi:[1,0,1]
	v_pk_fma_f32 v[18:19], v[226:227], s[22:23], v[18:19] op_sel_hi:[1,0,1]
	v_pk_fma_f32 v[20:21], v[228:229], s[22:23], v[20:21] op_sel_hi:[1,0,1]
	v_pk_fma_f32 v[22:23], v[230:231], s[22:23], v[22:23] op_sel_hi:[1,0,1]
	v_pk_fma_f32 v[24:25], v[232:233], s[22:23], v[24:25] op_sel_hi:[1,0,1]
	v_pk_fma_f32 v[26:27], v[234:235], s[22:23], v[26:27] op_sel_hi:[1,0,1]
	v_pk_fma_f32 v[28:29], v[236:237], s[22:23], v[28:29] op_sel_hi:[1,0,1]
	v_pk_fma_f32 v[30:31], v[238:239], s[22:23], v[30:31] op_sel_hi:[1,0,1]
	v_cvt_pk_f32_fp8_e32 v[224:225], v208
	v_cvt_pk_f32_fp8_sdwa v[226:227], v208 src0_sel:WORD_1
	v_cvt_pk_f32_fp8_e32 v[228:229], v209
	v_cvt_pk_f32_fp8_sdwa v[230:231], v209 src0_sel:WORD_1
	v_cvt_pk_f32_fp8_e32 v[232:233], v210
	v_cvt_pk_f32_fp8_sdwa v[234:235], v210 src0_sel:WORD_1
	v_cvt_pk_f32_fp8_e32 v[236:237], v211
	v_cvt_pk_f32_fp8_sdwa v[238:239], v211 src0_sel:WORD_1
	v_pk_fma_f32 v[16:17], v[224:225], s[24:25], v[16:17] op_sel_hi:[1,0,1]
	v_pk_fma_f32 v[18:19], v[226:227], s[24:25], v[18:19] op_sel_hi:[1,0,1]
	v_pk_fma_f32 v[20:21], v[228:229], s[24:25], v[20:21] op_sel_hi:[1,0,1]
	v_pk_fma_f32 v[22:23], v[230:231], s[24:25], v[22:23] op_sel_hi:[1,0,1]
	v_pk_fma_f32 v[24:25], v[232:233], s[24:25], v[24:25] op_sel_hi:[1,0,1]
	v_pk_fma_f32 v[26:27], v[234:235], s[24:25], v[26:27] op_sel_hi:[1,0,1]
	v_pk_fma_f32 v[28:29], v[236:237], s[24:25], v[28:29] op_sel_hi:[1,0,1]
	v_pk_fma_f32 v[30:31], v[238:239], s[24:25], v[30:31] op_sel_hi:[1,0,1]
	v_cvt_pk_f32_fp8_e32 v[224:225], v212
	v_cvt_pk_f32_fp8_sdwa v[226:227], v212 src0_sel:WORD_1
	v_cvt_pk_f32_fp8_e32 v[228:229], v213
	v_cvt_pk_f32_fp8_sdwa v[230:231], v213 src0_sel:WORD_1
	v_cvt_pk_f32_fp8_e32 v[232:233], v214
	v_cvt_pk_f32_fp8_sdwa v[234:235], v214 src0_sel:WORD_1
	v_cvt_pk_f32_fp8_e32 v[236:237], v215
	v_cvt_pk_f32_fp8_sdwa v[238:239], v215 src0_sel:WORD_1
	v_pk_fma_f32 v[16:17], v[224:225], s[26:27], v[16:17] op_sel_hi:[1,0,1]
	v_pk_fma_f32 v[18:19], v[226:227], s[26:27], v[18:19] op_sel_hi:[1,0,1]
	v_pk_fma_f32 v[20:21], v[228:229], s[26:27], v[20:21] op_sel_hi:[1,0,1]
	v_pk_fma_f32 v[22:23], v[230:231], s[26:27], v[22:23] op_sel_hi:[1,0,1]
	v_pk_fma_f32 v[24:25], v[232:233], s[26:27], v[24:25] op_sel_hi:[1,0,1]
	v_pk_fma_f32 v[26:27], v[234:235], s[26:27], v[26:27] op_sel_hi:[1,0,1]
	v_pk_fma_f32 v[28:29], v[236:237], s[26:27], v[28:29] op_sel_hi:[1,0,1]
	v_pk_fma_f32 v[30:31], v[238:239], s[26:27], v[30:31] op_sel_hi:[1,0,1]
	v_cvt_pk_f32_fp8_e32 v[224:225], v216
	v_cvt_pk_f32_fp8_sdwa v[226:227], v216 src0_sel:WORD_1
	v_cvt_pk_f32_fp8_e32 v[228:229], v217
	v_cvt_pk_f32_fp8_sdwa v[230:231], v217 src0_sel:WORD_1
	v_cvt_pk_f32_fp8_e32 v[232:233], v218
	v_cvt_pk_f32_fp8_sdwa v[234:235], v218 src0_sel:WORD_1
	v_cvt_pk_f32_fp8_e32 v[236:237], v219
	v_cvt_pk_f32_fp8_sdwa v[238:239], v219 src0_sel:WORD_1
	v_pk_fma_f32 v[16:17], v[224:225], s[28:29], v[16:17] op_sel_hi:[1,0,1]
	v_pk_fma_f32 v[18:19], v[226:227], s[28:29], v[18:19] op_sel_hi:[1,0,1]
	v_pk_fma_f32 v[20:21], v[228:229], s[28:29], v[20:21] op_sel_hi:[1,0,1]
	v_pk_fma_f32 v[22:23], v[230:231], s[28:29], v[22:23] op_sel_hi:[1,0,1]
	v_pk_fma_f32 v[24:25], v[232:233], s[28:29], v[24:25] op_sel_hi:[1,0,1]
	v_pk_fma_f32 v[26:27], v[234:235], s[28:29], v[26:27] op_sel_hi:[1,0,1]
	v_pk_fma_f32 v[28:29], v[236:237], s[28:29], v[28:29] op_sel_hi:[1,0,1]
	v_pk_fma_f32 v[30:31], v[238:239], s[28:29], v[30:31] op_sel_hi:[1,0,1]
	v_cvt_pk_f32_fp8_e32 v[224:225], v220
	v_cvt_pk_f32_fp8_sdwa v[226:227], v220 src0_sel:WORD_1
	v_cvt_pk_f32_fp8_e32 v[228:229], v221
	v_cvt_pk_f32_fp8_sdwa v[230:231], v221 src0_sel:WORD_1
	v_cvt_pk_f32_fp8_e32 v[232:233], v222
	v_cvt_pk_f32_fp8_sdwa v[234:235], v222 src0_sel:WORD_1
	v_cvt_pk_f32_fp8_e32 v[236:237], v223
	v_cvt_pk_f32_fp8_sdwa v[238:239], v223 src0_sel:WORD_1
	v_pk_fma_f32 v[16:17], v[224:225], s[30:31], v[16:17] op_sel_hi:[1,0,1]
	v_pk_fma_f32 v[18:19], v[226:227], s[30:31], v[18:19] op_sel_hi:[1,0,1]
	v_pk_fma_f32 v[20:21], v[228:229], s[30:31], v[20:21] op_sel_hi:[1,0,1]
	v_pk_fma_f32 v[22:23], v[230:231], s[30:31], v[22:23] op_sel_hi:[1,0,1]
	v_pk_fma_f32 v[24:25], v[232:233], s[30:31], v[24:25] op_sel_hi:[1,0,1]
	v_pk_fma_f32 v[26:27], v[234:235], s[30:31], v[26:27] op_sel_hi:[1,0,1]
	v_pk_fma_f32 v[28:29], v[236:237], s[30:31], v[28:29] op_sel_hi:[1,0,1]
	v_pk_fma_f32 v[30:31], v[238:239], s[30:31], v[30:31] op_sel_hi:[1,0,1]
	v_readlane_b32 s16, v139, s72
	v_readlane_b32 s18, v139, s73
	v_readlane_b32 s20, v139, s74
	v_readlane_b32 s22, v139, s75
	v_readlane_b32 s24, v139, s76
	v_readlane_b32 s26, v139, s77
	v_readlane_b32 s28, v139, s78
	v_readlane_b32 s30, v139, s79
	v_readlane_b32 s48, v132, s80
	v_readlane_b32 s49, v132, s81
	v_readlane_b32 s50, v132, s82
	v_readlane_b32 s51, v132, s83
	v_readlane_b32 s52, v132, s84
	v_readlane_b32 s53, v132, s85
	v_readlane_b32 s54, v132, s86
	v_readlane_b32 s55, v132, s87
	s_add_u32 s32, s0, s48
	s_addc_u32 s33, s1, 0
	s_add_u32 s34, s0, s49
	s_addc_u32 s35, s1, 0
	s_add_u32 s36, s0, s50
	s_addc_u32 s37, s1, 0
	s_add_u32 s38, s0, s51
	s_addc_u32 s39, s1, 0
	s_add_u32 s40, s0, s52
	s_addc_u32 s41, s1, 0
	s_add_u32 s42, s0, s53
	s_addc_u32 s43, s1, 0
	s_add_u32 s44, s0, s54
	s_addc_u32 s45, s1, 0
	s_add_u32 s46, s0, s55
	s_addc_u32 s47, s1, 0
	global_load_dwordx4 v[192:195], v240, s[32:33]
	global_load_dwordx4 v[196:199], v240, s[34:35]
	global_load_dwordx4 v[200:203], v240, s[36:37]
	global_load_dwordx4 v[204:207], v240, s[38:39]
	global_load_dwordx4 v[208:211], v240, s[40:41]
	global_load_dwordx4 v[212:215], v240, s[42:43]
	global_load_dwordx4 v[216:219], v240, s[44:45]
	global_load_dwordx4 v[220:223], v240, s[46:47]
	s_waitcnt vmcnt(24)
	v_cvt_pk_f32_fp8_e32 v[224:225], v64
	v_cvt_pk_f32_fp8_sdwa v[226:227], v64 src0_sel:WORD_1
	v_cvt_pk_f32_fp8_e32 v[228:229], v65
	v_cvt_pk_f32_fp8_sdwa v[230:231], v65 src0_sel:WORD_1
	v_cvt_pk_f32_fp8_e32 v[232:233], v66
	v_cvt_pk_f32_fp8_sdwa v[234:235], v66 src0_sel:WORD_1
	v_cvt_pk_f32_fp8_e32 v[236:237], v67
	v_cvt_pk_f32_fp8_sdwa v[238:239], v67 src0_sel:WORD_1
	v_pk_fma_f32 v[32:33], v[224:225], s[16:17], v[32:33] op_sel_hi:[1,0,1]
	v_pk_fma_f32 v[34:35], v[226:227], s[16:17], v[34:35] op_sel_hi:[1,0,1]
	v_pk_fma_f32 v[36:37], v[228:229], s[16:17], v[36:37] op_sel_hi:[1,0,1]
	v_pk_fma_f32 v[38:39], v[230:231], s[16:17], v[38:39] op_sel_hi:[1,0,1]
	v_pk_fma_f32 v[40:41], v[232:233], s[16:17], v[40:41] op_sel_hi:[1,0,1]
	v_pk_fma_f32 v[42:43], v[234:235], s[16:17], v[42:43] op_sel_hi:[1,0,1]
	v_pk_fma_f32 v[44:45], v[236:237], s[16:17], v[44:45] op_sel_hi:[1,0,1]
	v_pk_fma_f32 v[46:47], v[238:239], s[16:17], v[46:47] op_sel_hi:[1,0,1]
	v_cvt_pk_f32_fp8_e32 v[224:225], v68
	v_cvt_pk_f32_fp8_sdwa v[226:227], v68 src0_sel:WORD_1
	v_cvt_pk_f32_fp8_e32 v[228:229], v69
	v_cvt_pk_f32_fp8_sdwa v[230:231], v69 src0_sel:WORD_1
	v_cvt_pk_f32_fp8_e32 v[232:233], v70
	v_cvt_pk_f32_fp8_sdwa v[234:235], v70 src0_sel:WORD_1
	v_cvt_pk_f32_fp8_e32 v[236:237], v71
	v_cvt_pk_f32_fp8_sdwa v[238:239], v71 src0_sel:WORD_1
	v_pk_fma_f32 v[32:33], v[224:225], s[18:19], v[32:33] op_sel_hi:[1,0,1]
	v_pk_fma_f32 v[34:35], v[226:227], s[18:19], v[34:35] op_sel_hi:[1,0,1]
	v_pk_fma_f32 v[36:37], v[228:229], s[18:19], v[36:37] op_sel_hi:[1,0,1]
	v_pk_fma_f32 v[38:39], v[230:231], s[18:19], v[38:39] op_sel_hi:[1,0,1]
	v_pk_fma_f32 v[40:41], v[232:233], s[18:19], v[40:41] op_sel_hi:[1,0,1]
	v_pk_fma_f32 v[42:43], v[234:235], s[18:19], v[42:43] op_sel_hi:[1,0,1]
	v_pk_fma_f32 v[44:45], v[236:237], s[18:19], v[44:45] op_sel_hi:[1,0,1]
	v_pk_fma_f32 v[46:47], v[238:239], s[18:19], v[46:47] op_sel_hi:[1,0,1]
	v_cvt_pk_f32_fp8_e32 v[224:225], v72
	v_cvt_pk_f32_fp8_sdwa v[226:227], v72 src0_sel:WORD_1
	v_cvt_pk_f32_fp8_e32 v[228:229], v73
	v_cvt_pk_f32_fp8_sdwa v[230:231], v73 src0_sel:WORD_1
	v_cvt_pk_f32_fp8_e32 v[232:233], v74
	v_cvt_pk_f32_fp8_sdwa v[234:235], v74 src0_sel:WORD_1
	v_cvt_pk_f32_fp8_e32 v[236:237], v75
	v_cvt_pk_f32_fp8_sdwa v[238:239], v75 src0_sel:WORD_1
	v_pk_fma_f32 v[32:33], v[224:225], s[20:21], v[32:33] op_sel_hi:[1,0,1]
	v_pk_fma_f32 v[34:35], v[226:227], s[20:21], v[34:35] op_sel_hi:[1,0,1]
	v_pk_fma_f32 v[36:37], v[228:229], s[20:21], v[36:37] op_sel_hi:[1,0,1]
	v_pk_fma_f32 v[38:39], v[230:231], s[20:21], v[38:39] op_sel_hi:[1,0,1]
	v_pk_fma_f32 v[40:41], v[232:233], s[20:21], v[40:41] op_sel_hi:[1,0,1]
	v_pk_fma_f32 v[42:43], v[234:235], s[20:21], v[42:43] op_sel_hi:[1,0,1]
	v_pk_fma_f32 v[44:45], v[236:237], s[20:21], v[44:45] op_sel_hi:[1,0,1]
	v_pk_fma_f32 v[46:47], v[238:239], s[20:21], v[46:47] op_sel_hi:[1,0,1]
	v_cvt_pk_f32_fp8_e32 v[224:225], v76
	v_cvt_pk_f32_fp8_sdwa v[226:227], v76 src0_sel:WORD_1
	v_cvt_pk_f32_fp8_e32 v[228:229], v77
	v_cvt_pk_f32_fp8_sdwa v[230:231], v77 src0_sel:WORD_1
	v_cvt_pk_f32_fp8_e32 v[232:233], v78
	v_cvt_pk_f32_fp8_sdwa v[234:235], v78 src0_sel:WORD_1
	v_cvt_pk_f32_fp8_e32 v[236:237], v79
	v_cvt_pk_f32_fp8_sdwa v[238:239], v79 src0_sel:WORD_1
	v_pk_fma_f32 v[32:33], v[224:225], s[22:23], v[32:33] op_sel_hi:[1,0,1]
	v_pk_fma_f32 v[34:35], v[226:227], s[22:23], v[34:35] op_sel_hi:[1,0,1]
	v_pk_fma_f32 v[36:37], v[228:229], s[22:23], v[36:37] op_sel_hi:[1,0,1]
	v_pk_fma_f32 v[38:39], v[230:231], s[22:23], v[38:39] op_sel_hi:[1,0,1]
	v_pk_fma_f32 v[40:41], v[232:233], s[22:23], v[40:41] op_sel_hi:[1,0,1]
	v_pk_fma_f32 v[42:43], v[234:235], s[22:23], v[42:43] op_sel_hi:[1,0,1]
	v_pk_fma_f32 v[44:45], v[236:237], s[22:23], v[44:45] op_sel_hi:[1,0,1]
	v_pk_fma_f32 v[46:47], v[238:239], s[22:23], v[46:47] op_sel_hi:[1,0,1]
	v_cvt_pk_f32_fp8_e32 v[224:225], v80
	v_cvt_pk_f32_fp8_sdwa v[226:227], v80 src0_sel:WORD_1
	v_cvt_pk_f32_fp8_e32 v[228:229], v81
	v_cvt_pk_f32_fp8_sdwa v[230:231], v81 src0_sel:WORD_1
	v_cvt_pk_f32_fp8_e32 v[232:233], v82
	v_cvt_pk_f32_fp8_sdwa v[234:235], v82 src0_sel:WORD_1
	v_cvt_pk_f32_fp8_e32 v[236:237], v83
	v_cvt_pk_f32_fp8_sdwa v[238:239], v83 src0_sel:WORD_1
	v_pk_fma_f32 v[32:33], v[224:225], s[24:25], v[32:33] op_sel_hi:[1,0,1]
	v_pk_fma_f32 v[34:35], v[226:227], s[24:25], v[34:35] op_sel_hi:[1,0,1]
	v_pk_fma_f32 v[36:37], v[228:229], s[24:25], v[36:37] op_sel_hi:[1,0,1]
	v_pk_fma_f32 v[38:39], v[230:231], s[24:25], v[38:39] op_sel_hi:[1,0,1]
	v_pk_fma_f32 v[40:41], v[232:233], s[24:25], v[40:41] op_sel_hi:[1,0,1]
	v_pk_fma_f32 v[42:43], v[234:235], s[24:25], v[42:43] op_sel_hi:[1,0,1]
	v_pk_fma_f32 v[44:45], v[236:237], s[24:25], v[44:45] op_sel_hi:[1,0,1]
	v_pk_fma_f32 v[46:47], v[238:239], s[24:25], v[46:47] op_sel_hi:[1,0,1]
	v_cvt_pk_f32_fp8_e32 v[224:225], v84
	v_cvt_pk_f32_fp8_sdwa v[226:227], v84 src0_sel:WORD_1
	v_cvt_pk_f32_fp8_e32 v[228:229], v85
	v_cvt_pk_f32_fp8_sdwa v[230:231], v85 src0_sel:WORD_1
	v_cvt_pk_f32_fp8_e32 v[232:233], v86
	v_cvt_pk_f32_fp8_sdwa v[234:235], v86 src0_sel:WORD_1
	v_cvt_pk_f32_fp8_e32 v[236:237], v87
	v_cvt_pk_f32_fp8_sdwa v[238:239], v87 src0_sel:WORD_1
	v_pk_fma_f32 v[32:33], v[224:225], s[26:27], v[32:33] op_sel_hi:[1,0,1]
	v_pk_fma_f32 v[34:35], v[226:227], s[26:27], v[34:35] op_sel_hi:[1,0,1]
	v_pk_fma_f32 v[36:37], v[228:229], s[26:27], v[36:37] op_sel_hi:[1,0,1]
	v_pk_fma_f32 v[38:39], v[230:231], s[26:27], v[38:39] op_sel_hi:[1,0,1]
	v_pk_fma_f32 v[40:41], v[232:233], s[26:27], v[40:41] op_sel_hi:[1,0,1]
	v_pk_fma_f32 v[42:43], v[234:235], s[26:27], v[42:43] op_sel_hi:[1,0,1]
	v_pk_fma_f32 v[44:45], v[236:237], s[26:27], v[44:45] op_sel_hi:[1,0,1]
	v_pk_fma_f32 v[46:47], v[238:239], s[26:27], v[46:47] op_sel_hi:[1,0,1]
	v_cvt_pk_f32_fp8_e32 v[224:225], v88
	v_cvt_pk_f32_fp8_sdwa v[226:227], v88 src0_sel:WORD_1
	v_cvt_pk_f32_fp8_e32 v[228:229], v89
	v_cvt_pk_f32_fp8_sdwa v[230:231], v89 src0_sel:WORD_1
	v_cvt_pk_f32_fp8_e32 v[232:233], v90
	v_cvt_pk_f32_fp8_sdwa v[234:235], v90 src0_sel:WORD_1
	v_cvt_pk_f32_fp8_e32 v[236:237], v91
	v_cvt_pk_f32_fp8_sdwa v[238:239], v91 src0_sel:WORD_1
	v_pk_fma_f32 v[32:33], v[224:225], s[28:29], v[32:33] op_sel_hi:[1,0,1]
	v_pk_fma_f32 v[34:35], v[226:227], s[28:29], v[34:35] op_sel_hi:[1,0,1]
	v_pk_fma_f32 v[36:37], v[228:229], s[28:29], v[36:37] op_sel_hi:[1,0,1]
	v_pk_fma_f32 v[38:39], v[230:231], s[28:29], v[38:39] op_sel_hi:[1,0,1]
	v_pk_fma_f32 v[40:41], v[232:233], s[28:29], v[40:41] op_sel_hi:[1,0,1]
	v_pk_fma_f32 v[42:43], v[234:235], s[28:29], v[42:43] op_sel_hi:[1,0,1]
	v_pk_fma_f32 v[44:45], v[236:237], s[28:29], v[44:45] op_sel_hi:[1,0,1]
	v_pk_fma_f32 v[46:47], v[238:239], s[28:29], v[46:47] op_sel_hi:[1,0,1]
	v_cvt_pk_f32_fp8_e32 v[224:225], v92
	v_cvt_pk_f32_fp8_sdwa v[226:227], v92 src0_sel:WORD_1
	v_cvt_pk_f32_fp8_e32 v[228:229], v93
	v_cvt_pk_f32_fp8_sdwa v[230:231], v93 src0_sel:WORD_1
	v_cvt_pk_f32_fp8_e32 v[232:233], v94
	v_cvt_pk_f32_fp8_sdwa v[234:235], v94 src0_sel:WORD_1
	v_cvt_pk_f32_fp8_e32 v[236:237], v95
	v_cvt_pk_f32_fp8_sdwa v[238:239], v95 src0_sel:WORD_1
	v_pk_fma_f32 v[32:33], v[224:225], s[30:31], v[32:33] op_sel_hi:[1,0,1]
	v_pk_fma_f32 v[34:35], v[226:227], s[30:31], v[34:35] op_sel_hi:[1,0,1]
	v_pk_fma_f32 v[36:37], v[228:229], s[30:31], v[36:37] op_sel_hi:[1,0,1]
	v_pk_fma_f32 v[38:39], v[230:231], s[30:31], v[38:39] op_sel_hi:[1,0,1]
	v_pk_fma_f32 v[40:41], v[232:233], s[30:31], v[40:41] op_sel_hi:[1,0,1]
	v_pk_fma_f32 v[42:43], v[234:235], s[30:31], v[42:43] op_sel_hi:[1,0,1]
	v_pk_fma_f32 v[44:45], v[236:237], s[30:31], v[44:45] op_sel_hi:[1,0,1]
	v_pk_fma_f32 v[46:47], v[238:239], s[30:31], v[46:47] op_sel_hi:[1,0,1]
	v_readlane_b32 s16, v143, s72
	v_readlane_b32 s18, v143, s73
	v_readlane_b32 s20, v143, s74
	v_readlane_b32 s22, v143, s75
	v_readlane_b32 s24, v143, s76
	v_readlane_b32 s26, v143, s77
	v_readlane_b32 s28, v143, s78
	v_readlane_b32 s30, v143, s79
	v_readlane_b32 s48, v136, s80
	v_readlane_b32 s49, v136, s81
	v_readlane_b32 s50, v136, s82
	v_readlane_b32 s51, v136, s83
	v_readlane_b32 s52, v136, s84
	v_readlane_b32 s53, v136, s85
	v_readlane_b32 s54, v136, s86
	v_readlane_b32 s55, v136, s87
	s_add_u32 s32, s0, s48
	s_addc_u32 s33, s1, 0
	s_add_u32 s34, s0, s49
	s_addc_u32 s35, s1, 0
	s_add_u32 s36, s0, s50
	s_addc_u32 s37, s1, 0
	s_add_u32 s38, s0, s51
	s_addc_u32 s39, s1, 0
	s_add_u32 s40, s0, s52
	s_addc_u32 s41, s1, 0
	s_add_u32 s42, s0, s53
	s_addc_u32 s43, s1, 0
	s_add_u32 s44, s0, s54
	s_addc_u32 s45, s1, 0
	s_add_u32 s46, s0, s55
	s_addc_u32 s47, s1, 0
	global_load_dwordx4 v[64:67], v240, s[32:33]
	global_load_dwordx4 v[68:71], v240, s[34:35]
	global_load_dwordx4 v[72:75], v240, s[36:37]
	global_load_dwordx4 v[76:79], v240, s[38:39]
	global_load_dwordx4 v[80:83], v240, s[40:41]
	global_load_dwordx4 v[84:87], v240, s[42:43]
	global_load_dwordx4 v[88:91], v240, s[44:45]
	global_load_dwordx4 v[92:95], v240, s[46:47]
	s_waitcnt vmcnt(24)
	v_cvt_pk_f32_fp8_e32 v[224:225], v96
	v_cvt_pk_f32_fp8_sdwa v[226:227], v96 src0_sel:WORD_1
	v_cvt_pk_f32_fp8_e32 v[228:229], v97
	v_cvt_pk_f32_fp8_sdwa v[230:231], v97 src0_sel:WORD_1
	v_cvt_pk_f32_fp8_e32 v[232:233], v98
	v_cvt_pk_f32_fp8_sdwa v[234:235], v98 src0_sel:WORD_1
	v_cvt_pk_f32_fp8_e32 v[236:237], v99
	v_cvt_pk_f32_fp8_sdwa v[238:239], v99 src0_sel:WORD_1
	v_pk_fma_f32 v[48:49], v[224:225], s[16:17], v[48:49] op_sel_hi:[1,0,1]
	v_pk_fma_f32 v[50:51], v[226:227], s[16:17], v[50:51] op_sel_hi:[1,0,1]
	v_pk_fma_f32 v[52:53], v[228:229], s[16:17], v[52:53] op_sel_hi:[1,0,1]
	v_pk_fma_f32 v[54:55], v[230:231], s[16:17], v[54:55] op_sel_hi:[1,0,1]
	v_pk_fma_f32 v[56:57], v[232:233], s[16:17], v[56:57] op_sel_hi:[1,0,1]
	v_pk_fma_f32 v[58:59], v[234:235], s[16:17], v[58:59] op_sel_hi:[1,0,1]
	v_pk_fma_f32 v[60:61], v[236:237], s[16:17], v[60:61] op_sel_hi:[1,0,1]
	v_pk_fma_f32 v[62:63], v[238:239], s[16:17], v[62:63] op_sel_hi:[1,0,1]
	v_cvt_pk_f32_fp8_e32 v[224:225], v100
	v_cvt_pk_f32_fp8_sdwa v[226:227], v100 src0_sel:WORD_1
	v_cvt_pk_f32_fp8_e32 v[228:229], v101
	v_cvt_pk_f32_fp8_sdwa v[230:231], v101 src0_sel:WORD_1
	v_cvt_pk_f32_fp8_e32 v[232:233], v102
	v_cvt_pk_f32_fp8_sdwa v[234:235], v102 src0_sel:WORD_1
	v_cvt_pk_f32_fp8_e32 v[236:237], v103
	v_cvt_pk_f32_fp8_sdwa v[238:239], v103 src0_sel:WORD_1
	v_pk_fma_f32 v[48:49], v[224:225], s[18:19], v[48:49] op_sel_hi:[1,0,1]
	v_pk_fma_f32 v[50:51], v[226:227], s[18:19], v[50:51] op_sel_hi:[1,0,1]
	v_pk_fma_f32 v[52:53], v[228:229], s[18:19], v[52:53] op_sel_hi:[1,0,1]
	v_pk_fma_f32 v[54:55], v[230:231], s[18:19], v[54:55] op_sel_hi:[1,0,1]
	v_pk_fma_f32 v[56:57], v[232:233], s[18:19], v[56:57] op_sel_hi:[1,0,1]
	v_pk_fma_f32 v[58:59], v[234:235], s[18:19], v[58:59] op_sel_hi:[1,0,1]
	v_pk_fma_f32 v[60:61], v[236:237], s[18:19], v[60:61] op_sel_hi:[1,0,1]
	v_pk_fma_f32 v[62:63], v[238:239], s[18:19], v[62:63] op_sel_hi:[1,0,1]
	v_cvt_pk_f32_fp8_e32 v[224:225], v104
	v_cvt_pk_f32_fp8_sdwa v[226:227], v104 src0_sel:WORD_1
	v_cvt_pk_f32_fp8_e32 v[228:229], v105
	v_cvt_pk_f32_fp8_sdwa v[230:231], v105 src0_sel:WORD_1
	v_cvt_pk_f32_fp8_e32 v[232:233], v106
	v_cvt_pk_f32_fp8_sdwa v[234:235], v106 src0_sel:WORD_1
	v_cvt_pk_f32_fp8_e32 v[236:237], v107
	v_cvt_pk_f32_fp8_sdwa v[238:239], v107 src0_sel:WORD_1
	v_pk_fma_f32 v[48:49], v[224:225], s[20:21], v[48:49] op_sel_hi:[1,0,1]
	v_pk_fma_f32 v[50:51], v[226:227], s[20:21], v[50:51] op_sel_hi:[1,0,1]
	v_pk_fma_f32 v[52:53], v[228:229], s[20:21], v[52:53] op_sel_hi:[1,0,1]
	v_pk_fma_f32 v[54:55], v[230:231], s[20:21], v[54:55] op_sel_hi:[1,0,1]
	v_pk_fma_f32 v[56:57], v[232:233], s[20:21], v[56:57] op_sel_hi:[1,0,1]
	v_pk_fma_f32 v[58:59], v[234:235], s[20:21], v[58:59] op_sel_hi:[1,0,1]
	v_pk_fma_f32 v[60:61], v[236:237], s[20:21], v[60:61] op_sel_hi:[1,0,1]
	v_pk_fma_f32 v[62:63], v[238:239], s[20:21], v[62:63] op_sel_hi:[1,0,1]
	v_cvt_pk_f32_fp8_e32 v[224:225], v108
	v_cvt_pk_f32_fp8_sdwa v[226:227], v108 src0_sel:WORD_1
	v_cvt_pk_f32_fp8_e32 v[228:229], v109
	v_cvt_pk_f32_fp8_sdwa v[230:231], v109 src0_sel:WORD_1
	v_cvt_pk_f32_fp8_e32 v[232:233], v110
	v_cvt_pk_f32_fp8_sdwa v[234:235], v110 src0_sel:WORD_1
	v_cvt_pk_f32_fp8_e32 v[236:237], v111
	v_cvt_pk_f32_fp8_sdwa v[238:239], v111 src0_sel:WORD_1
	v_pk_fma_f32 v[48:49], v[224:225], s[22:23], v[48:49] op_sel_hi:[1,0,1]
	v_pk_fma_f32 v[50:51], v[226:227], s[22:23], v[50:51] op_sel_hi:[1,0,1]
	v_pk_fma_f32 v[52:53], v[228:229], s[22:23], v[52:53] op_sel_hi:[1,0,1]
	v_pk_fma_f32 v[54:55], v[230:231], s[22:23], v[54:55] op_sel_hi:[1,0,1]
	v_pk_fma_f32 v[56:57], v[232:233], s[22:23], v[56:57] op_sel_hi:[1,0,1]
	v_pk_fma_f32 v[58:59], v[234:235], s[22:23], v[58:59] op_sel_hi:[1,0,1]
	v_pk_fma_f32 v[60:61], v[236:237], s[22:23], v[60:61] op_sel_hi:[1,0,1]
	v_pk_fma_f32 v[62:63], v[238:239], s[22:23], v[62:63] op_sel_hi:[1,0,1]
	v_cvt_pk_f32_fp8_e32 v[224:225], v112
	v_cvt_pk_f32_fp8_sdwa v[226:227], v112 src0_sel:WORD_1
	v_cvt_pk_f32_fp8_e32 v[228:229], v113
	v_cvt_pk_f32_fp8_sdwa v[230:231], v113 src0_sel:WORD_1
	v_cvt_pk_f32_fp8_e32 v[232:233], v114
	v_cvt_pk_f32_fp8_sdwa v[234:235], v114 src0_sel:WORD_1
	v_cvt_pk_f32_fp8_e32 v[236:237], v115
	v_cvt_pk_f32_fp8_sdwa v[238:239], v115 src0_sel:WORD_1
	v_pk_fma_f32 v[48:49], v[224:225], s[24:25], v[48:49] op_sel_hi:[1,0,1]
	v_pk_fma_f32 v[50:51], v[226:227], s[24:25], v[50:51] op_sel_hi:[1,0,1]
	v_pk_fma_f32 v[52:53], v[228:229], s[24:25], v[52:53] op_sel_hi:[1,0,1]
	v_pk_fma_f32 v[54:55], v[230:231], s[24:25], v[54:55] op_sel_hi:[1,0,1]
	v_pk_fma_f32 v[56:57], v[232:233], s[24:25], v[56:57] op_sel_hi:[1,0,1]
	v_pk_fma_f32 v[58:59], v[234:235], s[24:25], v[58:59] op_sel_hi:[1,0,1]
	v_pk_fma_f32 v[60:61], v[236:237], s[24:25], v[60:61] op_sel_hi:[1,0,1]
	v_pk_fma_f32 v[62:63], v[238:239], s[24:25], v[62:63] op_sel_hi:[1,0,1]
	v_cvt_pk_f32_fp8_e32 v[224:225], v116
	v_cvt_pk_f32_fp8_sdwa v[226:227], v116 src0_sel:WORD_1
	v_cvt_pk_f32_fp8_e32 v[228:229], v117
	v_cvt_pk_f32_fp8_sdwa v[230:231], v117 src0_sel:WORD_1
	v_cvt_pk_f32_fp8_e32 v[232:233], v118
	v_cvt_pk_f32_fp8_sdwa v[234:235], v118 src0_sel:WORD_1
	v_cvt_pk_f32_fp8_e32 v[236:237], v119
	v_cvt_pk_f32_fp8_sdwa v[238:239], v119 src0_sel:WORD_1
	v_pk_fma_f32 v[48:49], v[224:225], s[26:27], v[48:49] op_sel_hi:[1,0,1]
	v_pk_fma_f32 v[50:51], v[226:227], s[26:27], v[50:51] op_sel_hi:[1,0,1]
	v_pk_fma_f32 v[52:53], v[228:229], s[26:27], v[52:53] op_sel_hi:[1,0,1]
	v_pk_fma_f32 v[54:55], v[230:231], s[26:27], v[54:55] op_sel_hi:[1,0,1]
	v_pk_fma_f32 v[56:57], v[232:233], s[26:27], v[56:57] op_sel_hi:[1,0,1]
	v_pk_fma_f32 v[58:59], v[234:235], s[26:27], v[58:59] op_sel_hi:[1,0,1]
; DI void peer_item_v(const Params& p, int item) {
;     ...
;     for (int g = 0; g < 16; g += 2) {
;       V_ISSUE(vqb, g + 1)
;       V_CONSUME(vqa, g)
;       if (g + 2 < 16) V_ISSUE(vqa, g + 2)
;       V_CONSUME(vqb, g + 1)
;     }
;     ...
;     float* orow = p.out + tok * 1024 + lane * 4;
;     float4 y[4];
;     float ss = 0.f;
; #pragma unroll
;     for (int i = 0; i < 4; ++i) {
;       y[i] = *(const float4*)(orow + 256 * i);
;       y[i].x += out[4 * i]; y[i].y += out[4 * i + 1]; y[i].z += out[4 * i + 2]; y[i].w += out[4 * i + 3];
;       ss += y[i].x * y[i].x + y[i].y * y[i].y + y[i].z * y[i].z + y[i].w * y[i].w;
;     }
;     ss = wave_sum(ss);
	v_pk_fma_f32 v[60:61], v[236:237], s[26:27], v[60:61] op_sel_hi:[1,0,1]
	v_pk_fma_f32 v[62:63], v[238:239], s[26:27], v[62:63] op_sel_hi:[1,0,1]
	v_cvt_pk_f32_fp8_e32 v[224:225], v120
	v_cvt_pk_f32_fp8_sdwa v[226:227], v120 src0_sel:WORD_1
	v_cvt_pk_f32_fp8_e32 v[228:229], v121
	v_cvt_pk_f32_fp8_sdwa v[230:231], v121 src0_sel:WORD_1
	v_cvt_pk_f32_fp8_e32 v[232:233], v122
	v_cvt_pk_f32_fp8_sdwa v[234:235], v122 src0_sel:WORD_1
	v_cvt_pk_f32_fp8_e32 v[236:237], v123
	v_cvt_pk_f32_fp8_sdwa v[238:239], v123 src0_sel:WORD_1
	v_pk_fma_f32 v[48:49], v[224:225], s[28:29], v[48:49] op_sel_hi:[1,0,1]
	v_pk_fma_f32 v[50:51], v[226:227], s[28:29], v[50:51] op_sel_hi:[1,0,1]
	v_pk_fma_f32 v[52:53], v[228:229], s[28:29], v[52:53] op_sel_hi:[1,0,1]
	v_pk_fma_f32 v[54:55], v[230:231], s[28:29], v[54:55] op_sel_hi:[1,0,1]
	v_pk_fma_f32 v[56:57], v[232:233], s[28:29], v[56:57] op_sel_hi:[1,0,1]
	v_pk_fma_f32 v[58:59], v[234:235], s[28:29], v[58:59] op_sel_hi:[1,0,1]
	v_pk_fma_f32 v[60:61], v[236:237], s[28:29], v[60:61] op_sel_hi:[1,0,1]
	v_pk_fma_f32 v[62:63], v[238:239], s[28:29], v[62:63] op_sel_hi:[1,0,1]
	v_cvt_pk_f32_fp8_e32 v[224:225], v124
	v_cvt_pk_f32_fp8_sdwa v[226:227], v124 src0_sel:WORD_1
	v_cvt_pk_f32_fp8_e32 v[228:229], v125
	v_cvt_pk_f32_fp8_sdwa v[230:231], v125 src0_sel:WORD_1
	v_cvt_pk_f32_fp8_e32 v[232:233], v126
	v_cvt_pk_f32_fp8_sdwa v[234:235], v126 src0_sel:WORD_1
	v_cvt_pk_f32_fp8_e32 v[236:237], v127
	v_cvt_pk_f32_fp8_sdwa v[238:239], v127 src0_sel:WORD_1
	v_pk_fma_f32 v[48:49], v[224:225], s[30:31], v[48:49] op_sel_hi:[1,0,1]
	v_pk_fma_f32 v[50:51], v[226:227], s[30:31], v[50:51] op_sel_hi:[1,0,1]
	v_pk_fma_f32 v[52:53], v[228:229], s[30:31], v[52:53] op_sel_hi:[1,0,1]
	v_pk_fma_f32 v[54:55], v[230:231], s[30:31], v[54:55] op_sel_hi:[1,0,1]
	v_pk_fma_f32 v[56:57], v[232:233], s[30:31], v[56:57] op_sel_hi:[1,0,1]
	v_pk_fma_f32 v[58:59], v[234:235], s[30:31], v[58:59] op_sel_hi:[1,0,1]
	v_pk_fma_f32 v[60:61], v[236:237], s[30:31], v[60:61] op_sel_hi:[1,0,1]
	v_pk_fma_f32 v[62:63], v[238:239], s[30:31], v[62:63] op_sel_hi:[1,0,1]
	s_mov_b32 s72, s80
	s_mov_b32 s73, s81
	s_mov_b32 s74, s82
	s_mov_b32 s75, s83
	s_mov_b32 s76, s84
	s_mov_b32 s77, s85
	s_mov_b32 s78, s86
	s_mov_b32 s79, s87
	s_add_u32 s80, s80, 8
	s_add_u32 s81, s81, 8
	s_add_u32 s82, s82, 8
	s_add_u32 s83, s83, 8
	s_add_u32 s84, s84, 8
	s_add_u32 s85, s85, 8
	s_add_u32 s86, s86, 8
	s_add_u32 s87, s87, 8
	s_and_b32 s80, s80, 63
	s_and_b32 s81, s81, 63
	s_and_b32 s82, s82, 63
	s_and_b32 s83, s83, 63
	s_and_b32 s84, s84, 63
	s_and_b32 s85, s85, 63
	s_and_b32 s86, s86, 63
	s_and_b32 s87, s87, 63
	s_add_u32 s12, s12, 1
	s_cmp_lt_u32 s12, 8
	s_cbranch_scc1 .Lvq_kA
	s_waitcnt vmcnt(0)
	s_add_u32 s32, s62, 0
	s_addc_u32 s33, s63, 0
	s_add_u32 s34, s62, 4096
	s_addc_u32 s35, s63, 0
	s_add_u32 s36, s62, 8192
	s_addc_u32 s37, s63, 0
	s_add_u32 s38, s62, 12288
	s_addc_u32 s39, s63, 0
	global_load_dwordx4 v[64:67], v240, s[32:33]
	global_load_dwordx4 v[68:71], v240, s[32:33] offset:1024
	global_load_dwordx4 v[72:75], v240, s[32:33] offset:2048
	global_load_dwordx4 v[76:79], v240, s[32:33] offset:3072
	global_load_dwordx4 v[80:83], v240, s[34:35]
	global_load_dwordx4 v[84:87], v240, s[34:35] offset:1024
	global_load_dwordx4 v[88:91], v240, s[34:35] offset:2048
	global_load_dwordx4 v[92:95], v240, s[34:35] offset:3072
	global_load_dwordx4 v[96:99], v240, s[36:37]
	global_load_dwordx4 v[100:103], v240, s[36:37] offset:1024
	global_load_dwordx4 v[104:107], v240, s[36:37] offset:2048
	global_load_dwordx4 v[108:111], v240, s[36:37] offset:3072
	global_load_dwordx4 v[112:115], v240, s[38:39]
	global_load_dwordx4 v[116:119], v240, s[38:39] offset:1024
	global_load_dwordx4 v[120:123], v240, s[38:39] offset:2048
	global_load_dwordx4 v[124:127], v240, s[38:39] offset:3072
	s_waitcnt vmcnt(0)
	global_load_dwordx4 v[128:131], v240, s[8:9]
	global_load_dwordx4 v[132:135], v240, s[8:9] offset:1024
	global_load_dwordx4 v[136:139], v240, s[8:9] offset:2048
	global_load_dwordx4 v[140:143], v240, s[8:9] offset:3072
	s_add_u32 s32, s62, 0
	s_addc_u32 s33, s63, 0
	s_add_u32 s34, s62, 4096
	s_addc_u32 s35, s63, 0
	s_add_u32 s36, s62, 8192
	s_addc_u32 s37, s63, 0
	s_add_u32 s38, s62, 12288
	s_addc_u32 s39, s63, 0
	s_waitcnt vmcnt(0)
	v_pk_add_f32 v[64:65], v[64:65], v[0:1]
	v_pk_add_f32 v[66:67], v[66:67], v[2:3]
	v_pk_add_f32 v[68:69], v[68:69], v[4:5]
	v_pk_add_f32 v[70:71], v[70:71], v[6:7]
	v_pk_add_f32 v[72:73], v[72:73], v[8:9]
	v_pk_add_f32 v[74:75], v[74:75], v[10:11]
	v_pk_add_f32 v[76:77], v[76:77], v[12:13]
	v_pk_add_f32 v[78:79], v[78:79], v[14:15]
	v_pk_mul_f32 v[224:225], v[64:65], v[64:65]
	v_pk_mul_f32 v[226:227], v[66:67], v[66:67]
	v_pk_fma_f32 v[224:225], v[68:69], v[68:69], v[224:225]
	v_pk_fma_f32 v[226:227], v[70:71], v[70:71], v[226:227]
	v_pk_fma_f32 v[224:225], v[72:73], v[72:73], v[224:225]
	v_pk_fma_f32 v[226:227], v[74:75], v[74:75], v[226:227]
	v_pk_fma_f32 v[224:225], v[76:77], v[76:77], v[224:225]
	v_pk_fma_f32 v[226:227], v[78:79], v[78:79], v[226:227]
	v_pk_add_f32 v[224:225], v[224:225], v[226:227]
	s_nop 0
	v_add_f32_e32 v224, v224, v225
	ds_bpermute_b32 v225, v242, v224
	s_waitcnt lgkmcnt(0)
	v_add_f32_e32 v224, v224, v225
	ds_bpermute_b32 v225, v243, v224
	s_waitcnt lgkmcnt(0)
	v_add_f32_e32 v224, v224, v225
	ds_bpermute_b32 v225, v244, v224
	s_waitcnt lgkmcnt(0)
	v_add_f32_e32 v224, v224, v225
	ds_bpermute_b32 v225, v245, v224
	s_waitcnt lgkmcnt(0)
	v_add_f32_e32 v224, v224, v225
	ds_bpermute_b32 v225, v246, v224
	s_waitcnt lgkmcnt(0)
	v_add_f32_e32 v224, v224, v225
	ds_bpermute_b32 v225, v247, v224
	s_waitcnt lgkmcnt(0)
; DI void peer_item_v(const Params& p, int item) {
;     ...
;     for (int i = 0; i < 4; ++i) {
;       y[i] = *(const float4*)(orow + 256 * i);
;       y[i].x += out[4 * i]; y[i].y += out[4 * i + 1]; y[i].z += out[4 * i + 2]; y[i].w += out[4 * i + 3];
;       ss += y[i].x * y[i].x + y[i].y * y[i].y + y[i].z * y[i].z + y[i].w * y[i].w;
;     }
;     ss = wave_sum(ss);
;     const float r = rsqrtf(ss * (1.f / 1024.f) + 1e-6f);
; #pragma unroll
;     for (int i = 0; i < 4; ++i) {
;       float4 g = *(const float4*)(p.g_final + 256 * i + lane * 4);
;       y[i].x *= r * g.x; y[i].y *= r * g.y; y[i].z *= r * g.z; y[i].w *= r * g.w;
;       *(float4*)(orow + 256 * i) = y[i];
	v_add_f32_e32 v224, v224, v225
	v_fmamk_f32 v224, v224, 0x3a800000, v248
	v_rsq_f32_e32 v224, v224
	s_nop 1
	v_pk_mul_f32 v[226:227], v[128:129], v[224:225] op_sel_hi:[1,0]
	v_pk_mul_f32 v[64:65], v[64:65], v[226:227]
	v_pk_mul_f32 v[228:229], v[130:131], v[224:225] op_sel_hi:[1,0]
	v_pk_mul_f32 v[66:67], v[66:67], v[228:229]
	v_pk_mul_f32 v[230:231], v[132:133], v[224:225] op_sel_hi:[1,0]
	v_pk_mul_f32 v[68:69], v[68:69], v[230:231]
	v_pk_mul_f32 v[232:233], v[134:135], v[224:225] op_sel_hi:[1,0]
	v_pk_mul_f32 v[70:71], v[70:71], v[232:233]
	v_pk_mul_f32 v[226:227], v[136:137], v[224:225] op_sel_hi:[1,0]
	v_pk_mul_f32 v[72:73], v[72:73], v[226:227]
	v_pk_mul_f32 v[228:229], v[138:139], v[224:225] op_sel_hi:[1,0]
	v_pk_mul_f32 v[74:75], v[74:75], v[228:229]
	v_pk_mul_f32 v[230:231], v[140:141], v[224:225] op_sel_hi:[1,0]
	v_pk_mul_f32 v[76:77], v[76:77], v[230:231]
	v_pk_mul_f32 v[232:233], v[142:143], v[224:225] op_sel_hi:[1,0]
	v_pk_mul_f32 v[78:79], v[78:79], v[232:233]
	v_pk_add_f32 v[80:81], v[80:81], v[16:17]
	v_pk_add_f32 v[82:83], v[82:83], v[18:19]
	v_pk_add_f32 v[84:85], v[84:85], v[20:21]
	v_pk_add_f32 v[86:87], v[86:87], v[22:23]
	v_pk_add_f32 v[88:89], v[88:89], v[24:25]
	v_pk_add_f32 v[90:91], v[90:91], v[26:27]
	v_pk_add_f32 v[92:93], v[92:93], v[28:29]
	v_pk_add_f32 v[94:95], v[94:95], v[30:31]
	v_pk_mul_f32 v[224:225], v[80:81], v[80:81]
	v_pk_mul_f32 v[226:227], v[82:83], v[82:83]
	v_pk_fma_f32 v[224:225], v[84:85], v[84:85], v[224:225]
	v_pk_fma_f32 v[226:227], v[86:87], v[86:87], v[226:227]
	v_pk_fma_f32 v[224:225], v[88:89], v[88:89], v[224:225]
	v_pk_fma_f32 v[226:227], v[90:91], v[90:91], v[226:227]
	v_pk_fma_f32 v[224:225], v[92:93], v[92:93], v[224:225]
	v_pk_fma_f32 v[226:227], v[94:95], v[94:95], v[226:227]
	v_pk_add_f32 v[224:225], v[224:225], v[226:227]
	s_nop 0
	v_add_f32_e32 v224, v224, v225
	ds_bpermute_b32 v225, v242, v224
	s_waitcnt lgkmcnt(0)
	v_add_f32_e32 v224, v224, v225
	ds_bpermute_b32 v225, v243, v224
	s_waitcnt lgkmcnt(0)
	v_add_f32_e32 v224, v224, v225
	ds_bpermute_b32 v225, v244, v224
	s_waitcnt lgkmcnt(0)
	v_add_f32_e32 v224, v224, v225
	ds_bpermute_b32 v225, v245, v224
	s_waitcnt lgkmcnt(0)
	v_add_f32_e32 v224, v224, v225
	ds_bpermute_b32 v225, v246, v224
	s_waitcnt lgkmcnt(0)
	v_add_f32_e32 v224, v224, v225
	ds_bpermute_b32 v225, v247, v224
	s_waitcnt lgkmcnt(0)
	v_add_f32_e32 v224, v224, v225
	v_fmamk_f32 v224, v224, 0x3a800000, v248
	v_rsq_f32_e32 v224, v224
	s_nop 1
	v_pk_mul_f32 v[226:227], v[128:129], v[224:225] op_sel_hi:[1,0]
	v_pk_mul_f32 v[80:81], v[80:81], v[226:227]
	v_pk_mul_f32 v[228:229], v[130:131], v[224:225] op_sel_hi:[1,0]
	v_pk_mul_f32 v[82:83], v[82:83], v[228:229]
	v_pk_mul_f32 v[230:231], v[132:133], v[224:225] op_sel_hi:[1,0]
	v_pk_mul_f32 v[84:85], v[84:85], v[230:231]
	v_pk_mul_f32 v[232:233], v[134:135], v[224:225] op_sel_hi:[1,0]
	v_pk_mul_f32 v[86:87], v[86:87], v[232:233]
	v_pk_mul_f32 v[226:227], v[136:137], v[224:225] op_sel_hi:[1,0]
	v_pk_mul_f32 v[88:89], v[88:89], v[226:227]
	v_pk_mul_f32 v[228:229], v[138:139], v[224:225] op_sel_hi:[1,0]
	v_pk_mul_f32 v[90:91], v[90:91], v[228:229]
	v_pk_mul_f32 v[230:231], v[140:141], v[224:225] op_sel_hi:[1,0]
	v_pk_mul_f32 v[92:93], v[92:93], v[230:231]
	v_pk_mul_f32 v[232:233], v[142:143], v[224:225] op_sel_hi:[1,0]
	v_pk_mul_f32 v[94:95], v[94:95], v[232:233]
	v_pk_add_f32 v[96:97], v[96:97], v[32:33]
	v_pk_add_f32 v[98:99], v[98:99], v[34:35]
	v_pk_add_f32 v[100:101], v[100:101], v[36:37]
	v_pk_add_f32 v[102:103], v[102:103], v[38:39]
	v_pk_add_f32 v[104:105], v[104:105], v[40:41]
	v_pk_add_f32 v[106:107], v[106:107], v[42:43]
	v_pk_add_f32 v[108:109], v[108:109], v[44:45]
	v_pk_add_f32 v[110:111], v[110:111], v[46:47]
	v_pk_mul_f32 v[224:225], v[96:97], v[96:97]
	v_pk_mul_f32 v[226:227], v[98:99], v[98:99]
	v_pk_fma_f32 v[224:225], v[100:101], v[100:101], v[224:225]
	v_pk_fma_f32 v[226:227], v[102:103], v[102:103], v[226:227]
	v_pk_fma_f32 v[224:225], v[104:105], v[104:105], v[224:225]
	v_pk_fma_f32 v[226:227], v[106:107], v[106:107], v[226:227]
	v_pk_fma_f32 v[224:225], v[108:109], v[108:109], v[224:225]
	v_pk_fma_f32 v[226:227], v[110:111], v[110:111], v[226:227]
	v_pk_add_f32 v[224:225], v[224:225], v[226:227]
	s_nop 0
	v_add_f32_e32 v224, v224, v225
	ds_bpermute_b32 v225, v242, v224
	s_waitcnt lgkmcnt(0)
	v_add_f32_e32 v224, v224, v225
	ds_bpermute_b32 v225, v243, v224
	s_waitcnt lgkmcnt(0)
	v_add_f32_e32 v224, v224, v225
	ds_bpermute_b32 v225, v244, v224
	s_waitcnt lgkmcnt(0)
	v_add_f32_e32 v224, v224, v225
	ds_bpermute_b32 v225, v245, v224
	s_waitcnt lgkmcnt(0)
	v_add_f32_e32 v224, v224, v225
	ds_bpermute_b32 v225, v246, v224
	s_waitcnt lgkmcnt(0)
	v_add_f32_e32 v224, v224, v225
	ds_bpermute_b32 v225, v247, v224
	s_waitcnt lgkmcnt(0)
; DI void peer_item_v(const Params& p, int item) {
;     ...
;     float out[16];
; #pragma unroll
;     for (int i = 0; i < 16; ++i) out[i] = 0.f;
;     ...
;     const float r = rsqrtf(ss * (1.f / 1024.f) + 1e-6f);
; #pragma unroll
;     for (int i = 0; i < 4; ++i) {
;       float4 g = *(const float4*)(p.g_final + 256 * i + lane * 4);
;       y[i].x *= r * g.x; y[i].y *= r * g.y; y[i].z *= r * g.z; y[i].w *= r * g.w;
;       *(float4*)(orow + 256 * i) = y[i];
;     }
	v_add_f32_e32 v224, v224, v225
	v_fmamk_f32 v224, v224, 0x3a800000, v248
	v_rsq_f32_e32 v224, v224
	s_nop 1
	v_pk_mul_f32 v[226:227], v[128:129], v[224:225] op_sel_hi:[1,0]
	v_pk_mul_f32 v[96:97], v[96:97], v[226:227]
	v_pk_mul_f32 v[228:229], v[130:131], v[224:225] op_sel_hi:[1,0]
	v_pk_mul_f32 v[98:99], v[98:99], v[228:229]
	v_pk_mul_f32 v[230:231], v[132:133], v[224:225] op_sel_hi:[1,0]
	v_pk_mul_f32 v[100:101], v[100:101], v[230:231]
	v_pk_mul_f32 v[232:233], v[134:135], v[224:225] op_sel_hi:[1,0]
	v_pk_mul_f32 v[102:103], v[102:103], v[232:233]
	v_pk_mul_f32 v[226:227], v[136:137], v[224:225] op_sel_hi:[1,0]
	v_pk_mul_f32 v[104:105], v[104:105], v[226:227]
	v_pk_mul_f32 v[228:229], v[138:139], v[224:225] op_sel_hi:[1,0]
	v_pk_mul_f32 v[106:107], v[106:107], v[228:229]
	v_pk_mul_f32 v[230:231], v[140:141], v[224:225] op_sel_hi:[1,0]
	v_pk_mul_f32 v[108:109], v[108:109], v[230:231]
	v_pk_mul_f32 v[232:233], v[142:143], v[224:225] op_sel_hi:[1,0]
	v_pk_mul_f32 v[110:111], v[110:111], v[232:233]
	v_pk_add_f32 v[112:113], v[112:113], v[48:49]
	v_pk_add_f32 v[114:115], v[114:115], v[50:51]
	v_pk_add_f32 v[116:117], v[116:117], v[52:53]
	v_pk_add_f32 v[118:119], v[118:119], v[54:55]
	v_pk_add_f32 v[120:121], v[120:121], v[56:57]
	v_pk_add_f32 v[122:123], v[122:123], v[58:59]
	v_pk_add_f32 v[124:125], v[124:125], v[60:61]
	v_pk_add_f32 v[126:127], v[126:127], v[62:63]
	v_pk_mul_f32 v[224:225], v[112:113], v[112:113]
	v_pk_mul_f32 v[226:227], v[114:115], v[114:115]
	v_pk_fma_f32 v[224:225], v[116:117], v[116:117], v[224:225]
	v_pk_fma_f32 v[226:227], v[118:119], v[118:119], v[226:227]
	v_pk_fma_f32 v[224:225], v[120:121], v[120:121], v[224:225]
	v_pk_fma_f32 v[226:227], v[122:123], v[122:123], v[226:227]
	v_pk_fma_f32 v[224:225], v[124:125], v[124:125], v[224:225]
	v_pk_fma_f32 v[226:227], v[126:127], v[126:127], v[226:227]
	v_pk_add_f32 v[224:225], v[224:225], v[226:227]
	s_nop 0
	v_add_f32_e32 v224, v224, v225
	ds_bpermute_b32 v225, v242, v224
	s_waitcnt lgkmcnt(0)
	v_add_f32_e32 v224, v224, v225
	ds_bpermute_b32 v225, v243, v224
	s_waitcnt lgkmcnt(0)
	v_add_f32_e32 v224, v224, v225
	ds_bpermute_b32 v225, v244, v224
	s_waitcnt lgkmcnt(0)
	v_add_f32_e32 v224, v224, v225
	ds_bpermute_b32 v225, v245, v224
	s_waitcnt lgkmcnt(0)
	v_add_f32_e32 v224, v224, v225
	ds_bpermute_b32 v225, v246, v224
	s_waitcnt lgkmcnt(0)
	v_add_f32_e32 v224, v224, v225
	ds_bpermute_b32 v225, v247, v224
	s_waitcnt lgkmcnt(0)
	v_add_f32_e32 v224, v224, v225
	v_fmamk_f32 v224, v224, 0x3a800000, v248
	v_rsq_f32_e32 v224, v224
	s_nop 1
	v_pk_mul_f32 v[226:227], v[128:129], v[224:225] op_sel_hi:[1,0]
	v_pk_mul_f32 v[112:113], v[112:113], v[226:227]
	v_pk_mul_f32 v[228:229], v[130:131], v[224:225] op_sel_hi:[1,0]
	v_pk_mul_f32 v[114:115], v[114:115], v[228:229]
	v_pk_mul_f32 v[230:231], v[132:133], v[224:225] op_sel_hi:[1,0]
	v_pk_mul_f32 v[116:117], v[116:117], v[230:231]
	v_pk_mul_f32 v[232:233], v[134:135], v[224:225] op_sel_hi:[1,0]
	v_pk_mul_f32 v[118:119], v[118:119], v[232:233]
	v_pk_mul_f32 v[226:227], v[136:137], v[224:225] op_sel_hi:[1,0]
	v_pk_mul_f32 v[120:121], v[120:121], v[226:227]
	v_pk_mul_f32 v[228:229], v[138:139], v[224:225] op_sel_hi:[1,0]
	v_pk_mul_f32 v[122:123], v[122:123], v[228:229]
	v_pk_mul_f32 v[230:231], v[140:141], v[224:225] op_sel_hi:[1,0]
	v_pk_mul_f32 v[124:125], v[124:125], v[230:231]
	v_pk_mul_f32 v[232:233], v[142:143], v[224:225] op_sel_hi:[1,0]
	v_pk_mul_f32 v[126:127], v[126:127], v[232:233]
	global_store_dwordx4 v240, v[64:67], s[32:33]
	global_store_dwordx4 v240, v[68:71], s[32:33] offset:1024
	global_store_dwordx4 v240, v[72:75], s[32:33] offset:2048
	global_store_dwordx4 v240, v[76:79], s[32:33] offset:3072
	global_store_dwordx4 v240, v[80:83], s[34:35]
	global_store_dwordx4 v240, v[84:87], s[34:35] offset:1024
	global_store_dwordx4 v240, v[88:91], s[34:35] offset:2048
	global_store_dwordx4 v240, v[92:95], s[34:35] offset:3072
	global_store_dwordx4 v240, v[96:99], s[36:37]
	global_store_dwordx4 v240, v[100:103], s[36:37] offset:1024
	global_store_dwordx4 v240, v[104:107], s[36:37] offset:2048
	global_store_dwordx4 v240, v[108:111], s[36:37] offset:3072
	global_store_dwordx4 v240, v[112:115], s[38:39]
	global_store_dwordx4 v240, v[116:119], s[38:39] offset:1024
	global_store_dwordx4 v240, v[120:123], s[38:39] offset:2048
	global_store_dwordx4 v240, v[124:127], s[38:39] offset:3072
	s_nop 1
	v_mov_b32_e32 v64, 0
	v_mov_b32_e32 v65, 0
	v_mov_b32_e32 v66, 0
	v_mov_b32_e32 v67, 0
	v_mov_b32_e32 v68, 0
	v_mov_b32_e32 v69, 0
	v_mov_b32_e32 v70, 0
	v_mov_b32_e32 v71, 0
	v_mov_b32_e32 v72, 0
	v_mov_b32_e32 v73, 0
	v_mov_b32_e32 v74, 0
	v_mov_b32_e32 v75, 0
	v_mov_b32_e32 v76, 0
	v_mov_b32_e32 v77, 0
	v_mov_b32_e32 v78, 0
	v_mov_b32_e32 v79, 0
	v_mov_b32_e32 v80, 0
	v_mov_b32_e32 v81, 0
	v_mov_b32_e32 v82, 0
	v_mov_b32_e32 v83, 0
	v_mov_b32_e32 v84, 0
	v_mov_b32_e32 v85, 0
	v_mov_b32_e32 v86, 0
	v_mov_b32_e32 v87, 0
	v_mov_b32_e32 v88, 0
	v_mov_b32_e32 v89, 0
	v_mov_b32_e32 v90, 0
	v_mov_b32_e32 v91, 0
	v_mov_b32_e32 v92, 0
	v_mov_b32_e32 v93, 0
	v_mov_b32_e32 v94, 0
	v_mov_b32_e32 v95, 0
	v_mov_b32_e32 v96, 0
	v_mov_b32_e32 v97, 0
	v_mov_b32_e32 v98, 0
	v_mov_b32_e32 v99, 0
	v_mov_b32_e32 v100, 0
	v_mov_b32_e32 v101, 0
	v_mov_b32_e32 v102, 0
	v_mov_b32_e32 v103, 0
	v_mov_b32_e32 v104, 0
	v_mov_b32_e32 v105, 0
	v_mov_b32_e32 v106, 0
	v_mov_b32_e32 v107, 0
	v_mov_b32_e32 v108, 0
	v_mov_b32_e32 v109, 0
	v_mov_b32_e32 v110, 0
	v_mov_b32_e32 v111, 0
	v_mov_b32_e32 v112, 0
	v_mov_b32_e32 v113, 0
	v_mov_b32_e32 v114, 0
	v_mov_b32_e32 v115, 0
	v_mov_b32_e32 v116, 0
	v_mov_b32_e32 v117, 0
	v_mov_b32_e32 v118, 0
	v_mov_b32_e32 v119, 0
; DI void peer_item_v(const Params& p, int item) {
;     ...
;     float out[16];
; #pragma unroll
;     for (int i = 0; i < 16; ++i) out[i] = 0.f;
;     u32x4 vqa[8], vqb[8];
	v_mov_b32_e32 v120, 0
	v_mov_b32_e32 v121, 0
	v_mov_b32_e32 v122, 0
	v_mov_b32_e32 v123, 0
	v_mov_b32_e32 v124, 0
	v_mov_b32_e32 v125, 0
	v_mov_b32_e32 v126, 0
	v_mov_b32_e32 v127, 0
	s_mov_b32 s72, 0
	s_mov_b32 s73, 1
	s_mov_b32 s74, 2
	s_mov_b32 s75, 3
	s_mov_b32 s76, 4
	s_mov_b32 s77, 5
	s_mov_b32 s78, 6
	s_mov_b32 s79, 7
	s_mov_b32 s80, 8
	s_mov_b32 s81, 9
	s_mov_b32 s82, 10
	s_mov_b32 s83, 11
	s_mov_b32 s84, 12
	s_mov_b32 s85, 13
	s_mov_b32 s86, 14
	s_mov_b32 s87, 15
	s_nop 0
	v_readlane_b32 s48, v144, s72
	v_readlane_b32 s49, v144, s73
	v_readlane_b32 s50, v144, s74
	v_readlane_b32 s51, v144, s75
	v_readlane_b32 s52, v144, s76
	v_readlane_b32 s53, v144, s77
	v_readlane_b32 s54, v144, s78
	v_readlane_b32 s55, v144, s79
	s_add_u32 s32, s0, s48
	s_addc_u32 s33, s1, 0
	s_add_u32 s34, s0, s49
	s_addc_u32 s35, s1, 0
	s_add_u32 s36, s0, s50
	s_addc_u32 s37, s1, 0
	s_add_u32 s38, s0, s51
	s_addc_u32 s39, s1, 0
	s_add_u32 s40, s0, s52
	s_addc_u32 s41, s1, 0
	s_add_u32 s42, s0, s53
	s_addc_u32 s43, s1, 0
	s_add_u32 s44, s0, s54
	s_addc_u32 s45, s1, 0
	s_add_u32 s46, s0, s55
	s_addc_u32 s47, s1, 0
	global_load_dwordx4 v[160:163], v240, s[32:33]
	global_load_dwordx4 v[164:167], v240, s[34:35]
	global_load_dwordx4 v[168:171], v240, s[36:37]
	global_load_dwordx4 v[172:175], v240, s[38:39]
	global_load_dwordx4 v[176:179], v240, s[40:41]
	global_load_dwordx4 v[180:183], v240, s[42:43]
	global_load_dwordx4 v[184:187], v240, s[44:45]
	global_load_dwordx4 v[188:191], v240, s[46:47]
	v_readlane_b32 s48, v148, s72
	v_readlane_b32 s49, v148, s73
	v_readlane_b32 s50, v148, s74
	v_readlane_b32 s51, v148, s75
	v_readlane_b32 s52, v148, s76
	v_readlane_b32 s53, v148, s77
	v_readlane_b32 s54, v148, s78
	v_readlane_b32 s55, v148, s79
	s_add_u32 s32, s0, s48
	s_addc_u32 s33, s1, 0
	s_add_u32 s34, s0, s49
	s_addc_u32 s35, s1, 0
	s_add_u32 s36, s0, s50
	s_addc_u32 s37, s1, 0
	s_add_u32 s38, s0, s51
	s_addc_u32 s39, s1, 0
	s_add_u32 s40, s0, s52
	s_addc_u32 s41, s1, 0
	s_add_u32 s42, s0, s53
	s_addc_u32 s43, s1, 0
	s_add_u32 s44, s0, s54
	s_addc_u32 s45, s1, 0
	s_add_u32 s46, s0, s55
	s_addc_u32 s47, s1, 0
	global_load_dwordx4 v[192:195], v240, s[32:33]
	global_load_dwordx4 v[196:199], v240, s[34:35]
	global_load_dwordx4 v[200:203], v240, s[36:37]
	global_load_dwordx4 v[204:207], v240, s[38:39]
	global_load_dwordx4 v[208:211], v240, s[40:41]
	global_load_dwordx4 v[212:215], v240, s[42:43]
	global_load_dwordx4 v[216:219], v240, s[44:45]
	global_load_dwordx4 v[220:223], v240, s[46:47]
	v_readlane_b32 s48, v152, s72
	v_readlane_b32 s49, v152, s73
	v_readlane_b32 s50, v152, s74
	v_readlane_b32 s51, v152, s75
	v_readlane_b32 s52, v152, s76
	v_readlane_b32 s53, v152, s77
	v_readlane_b32 s54, v152, s78
	v_readlane_b32 s55, v152, s79
	s_add_u32 s32, s0, s48
	s_addc_u32 s33, s1, 0
	s_add_u32 s34, s0, s49
	s_addc_u32 s35, s1, 0
	s_add_u32 s36, s0, s50
	s_addc_u32 s37, s1, 0
	s_add_u32 s38, s0, s51
	s_addc_u32 s39, s1, 0
	s_add_u32 s40, s0, s52
	s_addc_u32 s41, s1, 0
	s_add_u32 s42, s0, s53
	s_addc_u32 s43, s1, 0
	s_add_u32 s44, s0, s54
	s_addc_u32 s45, s1, 0
	s_add_u32 s46, s0, s55
	s_addc_u32 s47, s1, 0
	global_load_dwordx4 v[0:3], v240, s[32:33]
	global_load_dwordx4 v[4:7], v240, s[34:35]
	global_load_dwordx4 v[8:11], v240, s[36:37]
	global_load_dwordx4 v[12:15], v240, s[38:39]
	global_load_dwordx4 v[16:19], v240, s[40:41]
	global_load_dwordx4 v[20:23], v240, s[42:43]
	global_load_dwordx4 v[24:27], v240, s[44:45]
	global_load_dwordx4 v[28:31], v240, s[46:47]
	s_mov_b32 s12, 0
.Lvq_kB:
	v_readlane_b32 s16, v146, s72
	v_readlane_b32 s18, v146, s73
	v_readlane_b32 s20, v146, s74
	v_readlane_b32 s22, v146, s75
	v_readlane_b32 s24, v146, s76
	v_readlane_b32 s26, v146, s77
	v_readlane_b32 s28, v146, s78
	v_readlane_b32 s30, v146, s79
	v_readlane_b32 s48, v156, s72
	v_readlane_b32 s49, v156, s73
	v_readlane_b32 s50, v156, s74
	v_readlane_b32 s51, v156, s75
	v_readlane_b32 s52, v156, s76
	v_readlane_b32 s53, v156, s77
	v_readlane_b32 s54, v156, s78
	v_readlane_b32 s55, v156, s79
	s_add_u32 s32, s0, s48
	s_addc_u32 s33, s1, 0
	s_add_u32 s34, s0, s49
	s_addc_u32 s35, s1, 0
	s_add_u32 s36, s0, s50
	s_addc_u32 s37, s1, 0
	s_add_u32 s38, s0, s51
	s_addc_u32 s39, s1, 0
	s_add_u32 s40, s0, s52
	s_addc_u32 s41, s1, 0
	s_add_u32 s42, s0, s53
	s_addc_u32 s43, s1, 0
	s_add_u32 s44, s0, s54
	s_addc_u32 s45, s1, 0
	s_add_u32 s46, s0, s55
	s_addc_u32 s47, s1, 0
	global_load_dwordx4 v[32:35], v240, s[32:33]
	global_load_dwordx4 v[36:39], v240, s[34:35]
	global_load_dwordx4 v[40:43], v240, s[36:37]
	global_load_dwordx4 v[44:47], v240, s[38:39]
	global_load_dwordx4 v[48:51], v240, s[40:41]
	global_load_dwordx4 v[52:55], v240, s[42:43]
	global_load_dwordx4 v[56:59], v240, s[44:45]
	global_load_dwordx4 v[60:63], v240, s[46:47]
	s_waitcnt vmcnt(24)
	v_cvt_pk_f32_fp8_e32 v[224:225], v160
	v_cvt_pk_f32_fp8_sdwa v[226:227], v160 src0_sel:WORD_1
	v_cvt_pk_f32_fp8_e32 v[228:229], v161
	v_cvt_pk_f32_fp8_sdwa v[230:231], v161 src0_sel:WORD_1
	v_cvt_pk_f32_fp8_e32 v[232:233], v162
	v_cvt_pk_f32_fp8_sdwa v[234:235], v162 src0_sel:WORD_1
	v_cvt_pk_f32_fp8_e32 v[236:237], v163
	v_cvt_pk_f32_fp8_sdwa v[238:239], v163 src0_sel:WORD_1
	v_pk_fma_f32 v[64:65], v[224:225], s[16:17], v[64:65] op_sel_hi:[1,0,1]
	v_pk_fma_f32 v[66:67], v[226:227], s[16:17], v[66:67] op_sel_hi:[1,0,1]
	v_pk_fma_f32 v[68:69], v[228:229], s[16:17], v[68:69] op_sel_hi:[1,0,1]
	v_pk_fma_f32 v[70:71], v[230:231], s[16:17], v[70:71] op_sel_hi:[1,0,1]
	v_pk_fma_f32 v[72:73], v[232:233], s[16:17], v[72:73] op_sel_hi:[1,0,1]
	v_pk_fma_f32 v[74:75], v[234:235], s[16:17], v[74:75] op_sel_hi:[1,0,1]
	v_pk_fma_f32 v[76:77], v[236:237], s[16:17], v[76:77] op_sel_hi:[1,0,1]
	v_pk_fma_f32 v[78:79], v[238:239], s[16:17], v[78:79] op_sel_hi:[1,0,1]
	v_cvt_pk_f32_fp8_e32 v[224:225], v164
	v_cvt_pk_f32_fp8_sdwa v[226:227], v164 src0_sel:WORD_1
	v_cvt_pk_f32_fp8_e32 v[228:229], v165
	v_cvt_pk_f32_fp8_sdwa v[230:231], v165 src0_sel:WORD_1
	v_cvt_pk_f32_fp8_e32 v[232:233], v166
	v_cvt_pk_f32_fp8_sdwa v[234:235], v166 src0_sel:WORD_1
	v_cvt_pk_f32_fp8_e32 v[236:237], v167
	v_cvt_pk_f32_fp8_sdwa v[238:239], v167 src0_sel:WORD_1
	v_pk_fma_f32 v[64:65], v[224:225], s[18:19], v[64:65] op_sel_hi:[1,0,1]
	v_pk_fma_f32 v[66:67], v[226:227], s[18:19], v[66:67] op_sel_hi:[1,0,1]
	v_pk_fma_f32 v[68:69], v[228:229], s[18:19], v[68:69] op_sel_hi:[1,0,1]
	v_pk_fma_f32 v[70:71], v[230:231], s[18:19], v[70:71] op_sel_hi:[1,0,1]
	v_pk_fma_f32 v[72:73], v[232:233], s[18:19], v[72:73] op_sel_hi:[1,0,1]
	v_pk_fma_f32 v[74:75], v[234:235], s[18:19], v[74:75] op_sel_hi:[1,0,1]
	v_pk_fma_f32 v[76:77], v[236:237], s[18:19], v[76:77] op_sel_hi:[1,0,1]
	v_pk_fma_f32 v[78:79], v[238:239], s[18:19], v[78:79] op_sel_hi:[1,0,1]
	v_cvt_pk_f32_fp8_e32 v[224:225], v168
	v_cvt_pk_f32_fp8_sdwa v[226:227], v168 src0_sel:WORD_1
	v_cvt_pk_f32_fp8_e32 v[228:229], v169
	v_cvt_pk_f32_fp8_sdwa v[230:231], v169 src0_sel:WORD_1
	v_cvt_pk_f32_fp8_e32 v[232:233], v170
	v_cvt_pk_f32_fp8_sdwa v[234:235], v170 src0_sel:WORD_1
	v_cvt_pk_f32_fp8_e32 v[236:237], v171
	v_cvt_pk_f32_fp8_sdwa v[238:239], v171 src0_sel:WORD_1
	v_pk_fma_f32 v[64:65], v[224:225], s[20:21], v[64:65] op_sel_hi:[1,0,1]
	v_pk_fma_f32 v[66:67], v[226:227], s[20:21], v[66:67] op_sel_hi:[1,0,1]
	v_pk_fma_f32 v[68:69], v[228:229], s[20:21], v[68:69] op_sel_hi:[1,0,1]
	v_pk_fma_f32 v[70:71], v[230:231], s[20:21], v[70:71] op_sel_hi:[1,0,1]
	v_pk_fma_f32 v[72:73], v[232:233], s[20:21], v[72:73] op_sel_hi:[1,0,1]
	v_pk_fma_f32 v[74:75], v[234:235], s[20:21], v[74:75] op_sel_hi:[1,0,1]
	v_pk_fma_f32 v[76:77], v[236:237], s[20:21], v[76:77] op_sel_hi:[1,0,1]
	v_pk_fma_f32 v[78:79], v[238:239], s[20:21], v[78:79] op_sel_hi:[1,0,1]
	v_cvt_pk_f32_fp8_e32 v[224:225], v172
	v_cvt_pk_f32_fp8_sdwa v[226:227], v172 src0_sel:WORD_1
	v_cvt_pk_f32_fp8_e32 v[228:229], v173
	v_cvt_pk_f32_fp8_sdwa v[230:231], v173 src0_sel:WORD_1
	v_cvt_pk_f32_fp8_e32 v[232:233], v174
	v_cvt_pk_f32_fp8_sdwa v[234:235], v174 src0_sel:WORD_1
	v_cvt_pk_f32_fp8_e32 v[236:237], v175
	v_cvt_pk_f32_fp8_sdwa v[238:239], v175 src0_sel:WORD_1
	v_pk_fma_f32 v[64:65], v[224:225], s[22:23], v[64:65] op_sel_hi:[1,0,1]
	v_pk_fma_f32 v[66:67], v[226:227], s[22:23], v[66:67] op_sel_hi:[1,0,1]
	v_pk_fma_f32 v[68:69], v[228:229], s[22:23], v[68:69] op_sel_hi:[1,0,1]
	v_pk_fma_f32 v[70:71], v[230:231], s[22:23], v[70:71] op_sel_hi:[1,0,1]
	v_pk_fma_f32 v[72:73], v[232:233], s[22:23], v[72:73] op_sel_hi:[1,0,1]
	v_pk_fma_f32 v[74:75], v[234:235], s[22:23], v[74:75] op_sel_hi:[1,0,1]
	v_pk_fma_f32 v[76:77], v[236:237], s[22:23], v[76:77] op_sel_hi:[1,0,1]
	v_pk_fma_f32 v[78:79], v[238:239], s[22:23], v[78:79] op_sel_hi:[1,0,1]
	v_cvt_pk_f32_fp8_e32 v[224:225], v176
	v_cvt_pk_f32_fp8_sdwa v[226:227], v176 src0_sel:WORD_1
	v_cvt_pk_f32_fp8_e32 v[228:229], v177
	v_cvt_pk_f32_fp8_sdwa v[230:231], v177 src0_sel:WORD_1
	v_cvt_pk_f32_fp8_e32 v[232:233], v178
	v_cvt_pk_f32_fp8_sdwa v[234:235], v178 src0_sel:WORD_1
	v_cvt_pk_f32_fp8_e32 v[236:237], v179
	v_cvt_pk_f32_fp8_sdwa v[238:239], v179 src0_sel:WORD_1
	v_pk_fma_f32 v[64:65], v[224:225], s[24:25], v[64:65] op_sel_hi:[1,0,1]
	v_pk_fma_f32 v[66:67], v[226:227], s[24:25], v[66:67] op_sel_hi:[1,0,1]
	v_pk_fma_f32 v[68:69], v[228:229], s[24:25], v[68:69] op_sel_hi:[1,0,1]
	v_pk_fma_f32 v[70:71], v[230:231], s[24:25], v[70:71] op_sel_hi:[1,0,1]
	v_pk_fma_f32 v[72:73], v[232:233], s[24:25], v[72:73] op_sel_hi:[1,0,1]
	v_pk_fma_f32 v[74:75], v[234:235], s[24:25], v[74:75] op_sel_hi:[1,0,1]
	v_pk_fma_f32 v[76:77], v[236:237], s[24:25], v[76:77] op_sel_hi:[1,0,1]
	v_pk_fma_f32 v[78:79], v[238:239], s[24:25], v[78:79] op_sel_hi:[1,0,1]
	v_cvt_pk_f32_fp8_e32 v[224:225], v180
	v_cvt_pk_f32_fp8_sdwa v[226:227], v180 src0_sel:WORD_1
	v_cvt_pk_f32_fp8_e32 v[228:229], v181
	v_cvt_pk_f32_fp8_sdwa v[230:231], v181 src0_sel:WORD_1
	v_cvt_pk_f32_fp8_e32 v[232:233], v182
	v_cvt_pk_f32_fp8_sdwa v[234:235], v182 src0_sel:WORD_1
	v_cvt_pk_f32_fp8_e32 v[236:237], v183
	v_cvt_pk_f32_fp8_sdwa v[238:239], v183 src0_sel:WORD_1
	v_pk_fma_f32 v[64:65], v[224:225], s[26:27], v[64:65] op_sel_hi:[1,0,1]
	v_pk_fma_f32 v[66:67], v[226:227], s[26:27], v[66:67] op_sel_hi:[1,0,1]
	v_pk_fma_f32 v[68:69], v[228:229], s[26:27], v[68:69] op_sel_hi:[1,0,1]
	v_pk_fma_f32 v[70:71], v[230:231], s[26:27], v[70:71] op_sel_hi:[1,0,1]
	v_pk_fma_f32 v[72:73], v[232:233], s[26:27], v[72:73] op_sel_hi:[1,0,1]
	v_pk_fma_f32 v[74:75], v[234:235], s[26:27], v[74:75] op_sel_hi:[1,0,1]
	v_pk_fma_f32 v[76:77], v[236:237], s[26:27], v[76:77] op_sel_hi:[1,0,1]
	v_pk_fma_f32 v[78:79], v[238:239], s[26:27], v[78:79] op_sel_hi:[1,0,1]
	v_cvt_pk_f32_fp8_e32 v[224:225], v184
	v_cvt_pk_f32_fp8_sdwa v[226:227], v184 src0_sel:WORD_1
	v_cvt_pk_f32_fp8_e32 v[228:229], v185
	v_cvt_pk_f32_fp8_sdwa v[230:231], v185 src0_sel:WORD_1
	v_cvt_pk_f32_fp8_e32 v[232:233], v186
	v_cvt_pk_f32_fp8_sdwa v[234:235], v186 src0_sel:WORD_1
	v_cvt_pk_f32_fp8_e32 v[236:237], v187
	v_cvt_pk_f32_fp8_sdwa v[238:239], v187 src0_sel:WORD_1
	v_pk_fma_f32 v[64:65], v[224:225], s[28:29], v[64:65] op_sel_hi:[1,0,1]
	v_pk_fma_f32 v[66:67], v[226:227], s[28:29], v[66:67] op_sel_hi:[1,0,1]
	v_pk_fma_f32 v[68:69], v[228:229], s[28:29], v[68:69] op_sel_hi:[1,0,1]
	v_pk_fma_f32 v[70:71], v[230:231], s[28:29], v[70:71] op_sel_hi:[1,0,1]
	v_pk_fma_f32 v[72:73], v[232:233], s[28:29], v[72:73] op_sel_hi:[1,0,1]
	v_pk_fma_f32 v[74:75], v[234:235], s[28:29], v[74:75] op_sel_hi:[1,0,1]
	v_pk_fma_f32 v[76:77], v[236:237], s[28:29], v[76:77] op_sel_hi:[1,0,1]
	v_pk_fma_f32 v[78:79], v[238:239], s[28:29], v[78:79] op_sel_hi:[1,0,1]
	v_cvt_pk_f32_fp8_e32 v[224:225], v188
	v_cvt_pk_f32_fp8_sdwa v[226:227], v188 src0_sel:WORD_1
	v_cvt_pk_f32_fp8_e32 v[228:229], v189
	v_cvt_pk_f32_fp8_sdwa v[230:231], v189 src0_sel:WORD_1
	v_cvt_pk_f32_fp8_e32 v[232:233], v190
	v_cvt_pk_f32_fp8_sdwa v[234:235], v190 src0_sel:WORD_1
	v_cvt_pk_f32_fp8_e32 v[236:237], v191
	v_cvt_pk_f32_fp8_sdwa v[238:239], v191 src0_sel:WORD_1
	v_pk_fma_f32 v[64:65], v[224:225], s[30:31], v[64:65] op_sel_hi:[1,0,1]
	v_pk_fma_f32 v[66:67], v[226:227], s[30:31], v[66:67] op_sel_hi:[1,0,1]
	v_pk_fma_f32 v[68:69], v[228:229], s[30:31], v[68:69] op_sel_hi:[1,0,1]
	v_pk_fma_f32 v[70:71], v[230:231], s[30:31], v[70:71] op_sel_hi:[1,0,1]
	v_pk_fma_f32 v[72:73], v[232:233], s[30:31], v[72:73] op_sel_hi:[1,0,1]
	v_pk_fma_f32 v[74:75], v[234:235], s[30:31], v[74:75] op_sel_hi:[1,0,1]
	v_pk_fma_f32 v[76:77], v[236:237], s[30:31], v[76:77] op_sel_hi:[1,0,1]
	v_pk_fma_f32 v[78:79], v[238:239], s[30:31], v[78:79] op_sel_hi:[1,0,1]
	v_readlane_b32 s16, v150, s72
	v_readlane_b32 s18, v150, s73
	v_readlane_b32 s20, v150, s74
	v_readlane_b32 s22, v150, s75
	v_readlane_b32 s24, v150, s76
	v_readlane_b32 s26, v150, s77
	v_readlane_b32 s28, v150, s78
	v_readlane_b32 s30, v150, s79
	v_readlane_b32 s48, v145, s72
	v_readlane_b32 s49, v145, s73
	v_readlane_b32 s50, v145, s74
	v_readlane_b32 s51, v145, s75
	v_readlane_b32 s52, v145, s76
	v_readlane_b32 s53, v145, s77
	v_readlane_b32 s54, v145, s78
	v_readlane_b32 s55, v145, s79
	s_add_u32 s32, s0, s48
	s_addc_u32 s33, s1, 0
	s_add_u32 s34, s0, s49
	s_addc_u32 s35, s1, 0
	s_add_u32 s36, s0, s50
	s_addc_u32 s37, s1, 0
	s_add_u32 s38, s0, s51
	s_addc_u32 s39, s1, 0
	s_add_u32 s40, s0, s52
	s_addc_u32 s41, s1, 0
	s_add_u32 s42, s0, s53
	s_addc_u32 s43, s1, 0
	s_add_u32 s44, s0, s54
	s_addc_u32 s45, s1, 0
	s_add_u32 s46, s0, s55
	s_addc_u32 s47, s1, 0
	global_load_dwordx4 v[160:163], v240, s[32:33]
	global_load_dwordx4 v[164:167], v240, s[34:35]
	global_load_dwordx4 v[168:171], v240, s[36:37]
	global_load_dwordx4 v[172:175], v240, s[38:39]
	global_load_dwordx4 v[176:179], v240, s[40:41]
	global_load_dwordx4 v[180:183], v240, s[42:43]
	global_load_dwordx4 v[184:187], v240, s[44:45]
	global_load_dwordx4 v[188:191], v240, s[46:47]
	s_waitcnt vmcnt(24)
	v_cvt_pk_f32_fp8_e32 v[224:225], v192
	v_cvt_pk_f32_fp8_sdwa v[226:227], v192 src0_sel:WORD_1
	v_cvt_pk_f32_fp8_e32 v[228:229], v193
	v_cvt_pk_f32_fp8_sdwa v[230:231], v193 src0_sel:WORD_1
	v_cvt_pk_f32_fp8_e32 v[232:233], v194
	v_cvt_pk_f32_fp8_sdwa v[234:235], v194 src0_sel:WORD_1
	v_cvt_pk_f32_fp8_e32 v[236:237], v195
	v_cvt_pk_f32_fp8_sdwa v[238:239], v195 src0_sel:WORD_1
	v_pk_fma_f32 v[80:81], v[224:225], s[16:17], v[80:81] op_sel_hi:[1,0,1]
	v_pk_fma_f32 v[82:83], v[226:227], s[16:17], v[82:83] op_sel_hi:[1,0,1]
	v_pk_fma_f32 v[84:85], v[228:229], s[16:17], v[84:85] op_sel_hi:[1,0,1]
	v_pk_fma_f32 v[86:87], v[230:231], s[16:17], v[86:87] op_sel_hi:[1,0,1]
	v_pk_fma_f32 v[88:89], v[232:233], s[16:17], v[88:89] op_sel_hi:[1,0,1]
	v_pk_fma_f32 v[90:91], v[234:235], s[16:17], v[90:91] op_sel_hi:[1,0,1]
	v_pk_fma_f32 v[92:93], v[236:237], s[16:17], v[92:93] op_sel_hi:[1,0,1]
	v_pk_fma_f32 v[94:95], v[238:239], s[16:17], v[94:95] op_sel_hi:[1,0,1]
	v_cvt_pk_f32_fp8_e32 v[224:225], v196
	v_cvt_pk_f32_fp8_sdwa v[226:227], v196 src0_sel:WORD_1
	v_cvt_pk_f32_fp8_e32 v[228:229], v197
	v_cvt_pk_f32_fp8_sdwa v[230:231], v197 src0_sel:WORD_1
	v_cvt_pk_f32_fp8_e32 v[232:233], v198
	v_cvt_pk_f32_fp8_sdwa v[234:235], v198 src0_sel:WORD_1
	v_cvt_pk_f32_fp8_e32 v[236:237], v199
	v_cvt_pk_f32_fp8_sdwa v[238:239], v199 src0_sel:WORD_1
	v_pk_fma_f32 v[80:81], v[224:225], s[18:19], v[80:81] op_sel_hi:[1,0,1]
	v_pk_fma_f32 v[82:83], v[226:227], s[18:19], v[82:83] op_sel_hi:[1,0,1]
	v_pk_fma_f32 v[84:85], v[228:229], s[18:19], v[84:85] op_sel_hi:[1,0,1]
	v_pk_fma_f32 v[86:87], v[230:231], s[18:19], v[86:87] op_sel_hi:[1,0,1]
	v_pk_fma_f32 v[88:89], v[232:233], s[18:19], v[88:89] op_sel_hi:[1,0,1]
	v_pk_fma_f32 v[90:91], v[234:235], s[18:19], v[90:91] op_sel_hi:[1,0,1]
	v_pk_fma_f32 v[92:93], v[236:237], s[18:19], v[92:93] op_sel_hi:[1,0,1]
	v_pk_fma_f32 v[94:95], v[238:239], s[18:19], v[94:95] op_sel_hi:[1,0,1]
	v_cvt_pk_f32_fp8_e32 v[224:225], v200
	v_cvt_pk_f32_fp8_sdwa v[226:227], v200 src0_sel:WORD_1
	v_cvt_pk_f32_fp8_e32 v[228:229], v201
	v_cvt_pk_f32_fp8_sdwa v[230:231], v201 src0_sel:WORD_1
	v_cvt_pk_f32_fp8_e32 v[232:233], v202
	v_cvt_pk_f32_fp8_sdwa v[234:235], v202 src0_sel:WORD_1
	v_cvt_pk_f32_fp8_e32 v[236:237], v203
	v_cvt_pk_f32_fp8_sdwa v[238:239], v203 src0_sel:WORD_1
	v_pk_fma_f32 v[80:81], v[224:225], s[20:21], v[80:81] op_sel_hi:[1,0,1]
	v_pk_fma_f32 v[82:83], v[226:227], s[20:21], v[82:83] op_sel_hi:[1,0,1]
	v_pk_fma_f32 v[84:85], v[228:229], s[20:21], v[84:85] op_sel_hi:[1,0,1]
	v_pk_fma_f32 v[86:87], v[230:231], s[20:21], v[86:87] op_sel_hi:[1,0,1]
	v_pk_fma_f32 v[88:89], v[232:233], s[20:21], v[88:89] op_sel_hi:[1,0,1]
	v_pk_fma_f32 v[90:91], v[234:235], s[20:21], v[90:91] op_sel_hi:[1,0,1]
	v_pk_fma_f32 v[92:93], v[236:237], s[20:21], v[92:93] op_sel_hi:[1,0,1]
	v_pk_fma_f32 v[94:95], v[238:239], s[20:21], v[94:95] op_sel_hi:[1,0,1]
	v_cvt_pk_f32_fp8_e32 v[224:225], v204
	v_cvt_pk_f32_fp8_sdwa v[226:227], v204 src0_sel:WORD_1
	v_cvt_pk_f32_fp8_e32 v[228:229], v205
	v_cvt_pk_f32_fp8_sdwa v[230:231], v205 src0_sel:WORD_1
	v_cvt_pk_f32_fp8_e32 v[232:233], v206
	v_cvt_pk_f32_fp8_sdwa v[234:235], v206 src0_sel:WORD_1
	v_cvt_pk_f32_fp8_e32 v[236:237], v207
	v_cvt_pk_f32_fp8_sdwa v[238:239], v207 src0_sel:WORD_1
	v_pk_fma_f32 v[80:81], v[224:225], s[22:23], v[80:81] op_sel_hi:[1,0,1]
	v_pk_fma_f32 v[82:83], v[226:227], s[22:23], v[82:83] op_sel_hi:[1,0,1]
	v_pk_fma_f32 v[84:85], v[228:229], s[22:23], v[84:85] op_sel_hi:[1,0,1]
	v_pk_fma_f32 v[86:87], v[230:231], s[22:23], v[86:87] op_sel_hi:[1,0,1]
	v_pk_fma_f32 v[88:89], v[232:233], s[22:23], v[88:89] op_sel_hi:[1,0,1]
	v_pk_fma_f32 v[90:91], v[234:235], s[22:23], v[90:91] op_sel_hi:[1,0,1]
	v_pk_fma_f32 v[92:93], v[236:237], s[22:23], v[92:93] op_sel_hi:[1,0,1]
	v_pk_fma_f32 v[94:95], v[238:239], s[22:23], v[94:95] op_sel_hi:[1,0,1]
	v_cvt_pk_f32_fp8_e32 v[224:225], v208
	v_cvt_pk_f32_fp8_sdwa v[226:227], v208 src0_sel:WORD_1
	v_cvt_pk_f32_fp8_e32 v[228:229], v209
	v_cvt_pk_f32_fp8_sdwa v[230:231], v209 src0_sel:WORD_1
	v_cvt_pk_f32_fp8_e32 v[232:233], v210
	v_cvt_pk_f32_fp8_sdwa v[234:235], v210 src0_sel:WORD_1
	v_cvt_pk_f32_fp8_e32 v[236:237], v211
	v_cvt_pk_f32_fp8_sdwa v[238:239], v211 src0_sel:WORD_1
	v_pk_fma_f32 v[80:81], v[224:225], s[24:25], v[80:81] op_sel_hi:[1,0,1]
	v_pk_fma_f32 v[82:83], v[226:227], s[24:25], v[82:83] op_sel_hi:[1,0,1]
	v_pk_fma_f32 v[84:85], v[228:229], s[24:25], v[84:85] op_sel_hi:[1,0,1]
	v_pk_fma_f32 v[86:87], v[230:231], s[24:25], v[86:87] op_sel_hi:[1,0,1]
	v_pk_fma_f32 v[88:89], v[232:233], s[24:25], v[88:89] op_sel_hi:[1,0,1]
	v_pk_fma_f32 v[90:91], v[234:235], s[24:25], v[90:91] op_sel_hi:[1,0,1]
	v_pk_fma_f32 v[92:93], v[236:237], s[24:25], v[92:93] op_sel_hi:[1,0,1]
	v_pk_fma_f32 v[94:95], v[238:239], s[24:25], v[94:95] op_sel_hi:[1,0,1]
	v_cvt_pk_f32_fp8_e32 v[224:225], v212
	v_cvt_pk_f32_fp8_sdwa v[226:227], v212 src0_sel:WORD_1
	v_cvt_pk_f32_fp8_e32 v[228:229], v213
	v_cvt_pk_f32_fp8_sdwa v[230:231], v213 src0_sel:WORD_1
	v_cvt_pk_f32_fp8_e32 v[232:233], v214
	v_cvt_pk_f32_fp8_sdwa v[234:235], v214 src0_sel:WORD_1
	v_cvt_pk_f32_fp8_e32 v[236:237], v215
	v_cvt_pk_f32_fp8_sdwa v[238:239], v215 src0_sel:WORD_1
	v_pk_fma_f32 v[80:81], v[224:225], s[26:27], v[80:81] op_sel_hi:[1,0,1]
	v_pk_fma_f32 v[82:83], v[226:227], s[26:27], v[82:83] op_sel_hi:[1,0,1]
	v_pk_fma_f32 v[84:85], v[228:229], s[26:27], v[84:85] op_sel_hi:[1,0,1]
	v_pk_fma_f32 v[86:87], v[230:231], s[26:27], v[86:87] op_sel_hi:[1,0,1]
	v_pk_fma_f32 v[88:89], v[232:233], s[26:27], v[88:89] op_sel_hi:[1,0,1]
	v_pk_fma_f32 v[90:91], v[234:235], s[26:27], v[90:91] op_sel_hi:[1,0,1]
	v_pk_fma_f32 v[92:93], v[236:237], s[26:27], v[92:93] op_sel_hi:[1,0,1]
	v_pk_fma_f32 v[94:95], v[238:239], s[26:27], v[94:95] op_sel_hi:[1,0,1]
	v_cvt_pk_f32_fp8_e32 v[224:225], v216
	v_cvt_pk_f32_fp8_sdwa v[226:227], v216 src0_sel:WORD_1
	v_cvt_pk_f32_fp8_e32 v[228:229], v217
	v_cvt_pk_f32_fp8_sdwa v[230:231], v217 src0_sel:WORD_1
	v_cvt_pk_f32_fp8_e32 v[232:233], v218
	v_cvt_pk_f32_fp8_sdwa v[234:235], v218 src0_sel:WORD_1
	v_cvt_pk_f32_fp8_e32 v[236:237], v219
	v_cvt_pk_f32_fp8_sdwa v[238:239], v219 src0_sel:WORD_1
	v_pk_fma_f32 v[80:81], v[224:225], s[28:29], v[80:81] op_sel_hi:[1,0,1]
	v_pk_fma_f32 v[82:83], v[226:227], s[28:29], v[82:83] op_sel_hi:[1,0,1]
	v_pk_fma_f32 v[84:85], v[228:229], s[28:29], v[84:85] op_sel_hi:[1,0,1]
	v_pk_fma_f32 v[86:87], v[230:231], s[28:29], v[86:87] op_sel_hi:[1,0,1]
	v_pk_fma_f32 v[88:89], v[232:233], s[28:29], v[88:89] op_sel_hi:[1,0,1]
	v_pk_fma_f32 v[90:91], v[234:235], s[28:29], v[90:91] op_sel_hi:[1,0,1]
	v_pk_fma_f32 v[92:93], v[236:237], s[28:29], v[92:93] op_sel_hi:[1,0,1]
	v_pk_fma_f32 v[94:95], v[238:239], s[28:29], v[94:95] op_sel_hi:[1,0,1]
	v_cvt_pk_f32_fp8_e32 v[224:225], v220
	v_cvt_pk_f32_fp8_sdwa v[226:227], v220 src0_sel:WORD_1
	v_cvt_pk_f32_fp8_e32 v[228:229], v221
	v_cvt_pk_f32_fp8_sdwa v[230:231], v221 src0_sel:WORD_1
	v_cvt_pk_f32_fp8_e32 v[232:233], v222
	v_cvt_pk_f32_fp8_sdwa v[234:235], v222 src0_sel:WORD_1
	v_cvt_pk_f32_fp8_e32 v[236:237], v223
	v_cvt_pk_f32_fp8_sdwa v[238:239], v223 src0_sel:WORD_1
	v_pk_fma_f32 v[80:81], v[224:225], s[30:31], v[80:81] op_sel_hi:[1,0,1]
	v_pk_fma_f32 v[82:83], v[226:227], s[30:31], v[82:83] op_sel_hi:[1,0,1]
	v_pk_fma_f32 v[84:85], v[228:229], s[30:31], v[84:85] op_sel_hi:[1,0,1]
	v_pk_fma_f32 v[86:87], v[230:231], s[30:31], v[86:87] op_sel_hi:[1,0,1]
	v_pk_fma_f32 v[88:89], v[232:233], s[30:31], v[88:89] op_sel_hi:[1,0,1]
	v_pk_fma_f32 v[90:91], v[234:235], s[30:31], v[90:91] op_sel_hi:[1,0,1]
	v_pk_fma_f32 v[92:93], v[236:237], s[30:31], v[92:93] op_sel_hi:[1,0,1]
	v_pk_fma_f32 v[94:95], v[238:239], s[30:31], v[94:95] op_sel_hi:[1,0,1]
	v_readlane_b32 s16, v154, s72
	v_readlane_b32 s18, v154, s73
	v_readlane_b32 s20, v154, s74
	v_readlane_b32 s22, v154, s75
	v_readlane_b32 s24, v154, s76
	v_readlane_b32 s26, v154, s77
	v_readlane_b32 s28, v154, s78
	v_readlane_b32 s30, v154, s79
	v_readlane_b32 s48, v149, s72
	v_readlane_b32 s49, v149, s73
	v_readlane_b32 s50, v149, s74
	v_readlane_b32 s51, v149, s75
	v_readlane_b32 s52, v149, s76
	v_readlane_b32 s53, v149, s77
	v_readlane_b32 s54, v149, s78
	v_readlane_b32 s55, v149, s79
	s_add_u32 s32, s0, s48
	s_addc_u32 s33, s1, 0
	s_add_u32 s34, s0, s49
	s_addc_u32 s35, s1, 0
	s_add_u32 s36, s0, s50
	s_addc_u32 s37, s1, 0
	s_add_u32 s38, s0, s51
	s_addc_u32 s39, s1, 0
	s_add_u32 s40, s0, s52
	s_addc_u32 s41, s1, 0
	s_add_u32 s42, s0, s53
	s_addc_u32 s43, s1, 0
	s_add_u32 s44, s0, s54
	s_addc_u32 s45, s1, 0
	s_add_u32 s46, s0, s55
	s_addc_u32 s47, s1, 0
	global_load_dwordx4 v[192:195], v240, s[32:33]
	global_load_dwordx4 v[196:199], v240, s[34:35]
	global_load_dwordx4 v[200:203], v240, s[36:37]
	global_load_dwordx4 v[204:207], v240, s[38:39]
	global_load_dwordx4 v[208:211], v240, s[40:41]
	global_load_dwordx4 v[212:215], v240, s[42:43]
	global_load_dwordx4 v[216:219], v240, s[44:45]
	global_load_dwordx4 v[220:223], v240, s[46:47]
	s_waitcnt vmcnt(24)
	v_cvt_pk_f32_fp8_e32 v[224:225], v0
	v_cvt_pk_f32_fp8_sdwa v[226:227], v0 src0_sel:WORD_1
	v_cvt_pk_f32_fp8_e32 v[228:229], v1
	v_cvt_pk_f32_fp8_sdwa v[230:231], v1 src0_sel:WORD_1
	v_cvt_pk_f32_fp8_e32 v[232:233], v2
	v_cvt_pk_f32_fp8_sdwa v[234:235], v2 src0_sel:WORD_1
	v_cvt_pk_f32_fp8_e32 v[236:237], v3
	v_cvt_pk_f32_fp8_sdwa v[238:239], v3 src0_sel:WORD_1
	v_pk_fma_f32 v[96:97], v[224:225], s[16:17], v[96:97] op_sel_hi:[1,0,1]
	v_pk_fma_f32 v[98:99], v[226:227], s[16:17], v[98:99] op_sel_hi:[1,0,1]
	v_pk_fma_f32 v[100:101], v[228:229], s[16:17], v[100:101] op_sel_hi:[1,0,1]
	v_pk_fma_f32 v[102:103], v[230:231], s[16:17], v[102:103] op_sel_hi:[1,0,1]
	v_pk_fma_f32 v[104:105], v[232:233], s[16:17], v[104:105] op_sel_hi:[1,0,1]
	v_pk_fma_f32 v[106:107], v[234:235], s[16:17], v[106:107] op_sel_hi:[1,0,1]
	v_pk_fma_f32 v[108:109], v[236:237], s[16:17], v[108:109] op_sel_hi:[1,0,1]
	v_pk_fma_f32 v[110:111], v[238:239], s[16:17], v[110:111] op_sel_hi:[1,0,1]
	v_cvt_pk_f32_fp8_e32 v[224:225], v4
	v_cvt_pk_f32_fp8_sdwa v[226:227], v4 src0_sel:WORD_1
	v_cvt_pk_f32_fp8_e32 v[228:229], v5
	v_cvt_pk_f32_fp8_sdwa v[230:231], v5 src0_sel:WORD_1
	v_cvt_pk_f32_fp8_e32 v[232:233], v6
	v_cvt_pk_f32_fp8_sdwa v[234:235], v6 src0_sel:WORD_1
	v_cvt_pk_f32_fp8_e32 v[236:237], v7
	v_cvt_pk_f32_fp8_sdwa v[238:239], v7 src0_sel:WORD_1
	v_pk_fma_f32 v[96:97], v[224:225], s[18:19], v[96:97] op_sel_hi:[1,0,1]
	v_pk_fma_f32 v[98:99], v[226:227], s[18:19], v[98:99] op_sel_hi:[1,0,1]
	v_pk_fma_f32 v[100:101], v[228:229], s[18:19], v[100:101] op_sel_hi:[1,0,1]
	v_pk_fma_f32 v[102:103], v[230:231], s[18:19], v[102:103] op_sel_hi:[1,0,1]
	v_pk_fma_f32 v[104:105], v[232:233], s[18:19], v[104:105] op_sel_hi:[1,0,1]
	v_pk_fma_f32 v[106:107], v[234:235], s[18:19], v[106:107] op_sel_hi:[1,0,1]
	v_pk_fma_f32 v[108:109], v[236:237], s[18:19], v[108:109] op_sel_hi:[1,0,1]
	v_pk_fma_f32 v[110:111], v[238:239], s[18:19], v[110:111] op_sel_hi:[1,0,1]
	v_cvt_pk_f32_fp8_e32 v[224:225], v8
	v_cvt_pk_f32_fp8_sdwa v[226:227], v8 src0_sel:WORD_1
	v_cvt_pk_f32_fp8_e32 v[228:229], v9
	v_cvt_pk_f32_fp8_sdwa v[230:231], v9 src0_sel:WORD_1
	v_cvt_pk_f32_fp8_e32 v[232:233], v10
	v_cvt_pk_f32_fp8_sdwa v[234:235], v10 src0_sel:WORD_1
	v_cvt_pk_f32_fp8_e32 v[236:237], v11
	v_cvt_pk_f32_fp8_sdwa v[238:239], v11 src0_sel:WORD_1
	v_pk_fma_f32 v[96:97], v[224:225], s[20:21], v[96:97] op_sel_hi:[1,0,1]
	v_pk_fma_f32 v[98:99], v[226:227], s[20:21], v[98:99] op_sel_hi:[1,0,1]
	v_pk_fma_f32 v[100:101], v[228:229], s[20:21], v[100:101] op_sel_hi:[1,0,1]
	v_pk_fma_f32 v[102:103], v[230:231], s[20:21], v[102:103] op_sel_hi:[1,0,1]
	v_pk_fma_f32 v[104:105], v[232:233], s[20:21], v[104:105] op_sel_hi:[1,0,1]
	v_pk_fma_f32 v[106:107], v[234:235], s[20:21], v[106:107] op_sel_hi:[1,0,1]
	v_pk_fma_f32 v[108:109], v[236:237], s[20:21], v[108:109] op_sel_hi:[1,0,1]
	v_pk_fma_f32 v[110:111], v[238:239], s[20:21], v[110:111] op_sel_hi:[1,0,1]
	v_cvt_pk_f32_fp8_e32 v[224:225], v12
	v_cvt_pk_f32_fp8_sdwa v[226:227], v12 src0_sel:WORD_1
	v_cvt_pk_f32_fp8_e32 v[228:229], v13
	v_cvt_pk_f32_fp8_sdwa v[230:231], v13 src0_sel:WORD_1
	v_cvt_pk_f32_fp8_e32 v[232:233], v14
	v_cvt_pk_f32_fp8_sdwa v[234:235], v14 src0_sel:WORD_1
	v_cvt_pk_f32_fp8_e32 v[236:237], v15
	v_cvt_pk_f32_fp8_sdwa v[238:239], v15 src0_sel:WORD_1
	v_pk_fma_f32 v[96:97], v[224:225], s[22:23], v[96:97] op_sel_hi:[1,0,1]
	v_pk_fma_f32 v[98:99], v[226:227], s[22:23], v[98:99] op_sel_hi:[1,0,1]
	v_pk_fma_f32 v[100:101], v[228:229], s[22:23], v[100:101] op_sel_hi:[1,0,1]
	v_pk_fma_f32 v[102:103], v[230:231], s[22:23], v[102:103] op_sel_hi:[1,0,1]
	v_pk_fma_f32 v[104:105], v[232:233], s[22:23], v[104:105] op_sel_hi:[1,0,1]
	v_pk_fma_f32 v[106:107], v[234:235], s[22:23], v[106:107] op_sel_hi:[1,0,1]
	v_pk_fma_f32 v[108:109], v[236:237], s[22:23], v[108:109] op_sel_hi:[1,0,1]
	v_pk_fma_f32 v[110:111], v[238:239], s[22:23], v[110:111] op_sel_hi:[1,0,1]
	v_cvt_pk_f32_fp8_e32 v[224:225], v16
	v_cvt_pk_f32_fp8_sdwa v[226:227], v16 src0_sel:WORD_1
	v_cvt_pk_f32_fp8_e32 v[228:229], v17
	v_cvt_pk_f32_fp8_sdwa v[230:231], v17 src0_sel:WORD_1
	v_cvt_pk_f32_fp8_e32 v[232:233], v18
	v_cvt_pk_f32_fp8_sdwa v[234:235], v18 src0_sel:WORD_1
	v_cvt_pk_f32_fp8_e32 v[236:237], v19
	v_cvt_pk_f32_fp8_sdwa v[238:239], v19 src0_sel:WORD_1
	v_pk_fma_f32 v[96:97], v[224:225], s[24:25], v[96:97] op_sel_hi:[1,0,1]
	v_pk_fma_f32 v[98:99], v[226:227], s[24:25], v[98:99] op_sel_hi:[1,0,1]
	v_pk_fma_f32 v[100:101], v[228:229], s[24:25], v[100:101] op_sel_hi:[1,0,1]
	v_pk_fma_f32 v[102:103], v[230:231], s[24:25], v[102:103] op_sel_hi:[1,0,1]
	v_pk_fma_f32 v[104:105], v[232:233], s[24:25], v[104:105] op_sel_hi:[1,0,1]
	v_pk_fma_f32 v[106:107], v[234:235], s[24:25], v[106:107] op_sel_hi:[1,0,1]
	v_pk_fma_f32 v[108:109], v[236:237], s[24:25], v[108:109] op_sel_hi:[1,0,1]
	v_pk_fma_f32 v[110:111], v[238:239], s[24:25], v[110:111] op_sel_hi:[1,0,1]
	v_cvt_pk_f32_fp8_e32 v[224:225], v20
	v_cvt_pk_f32_fp8_sdwa v[226:227], v20 src0_sel:WORD_1
	v_cvt_pk_f32_fp8_e32 v[228:229], v21
	v_cvt_pk_f32_fp8_sdwa v[230:231], v21 src0_sel:WORD_1
	v_cvt_pk_f32_fp8_e32 v[232:233], v22
	v_cvt_pk_f32_fp8_sdwa v[234:235], v22 src0_sel:WORD_1
	v_cvt_pk_f32_fp8_e32 v[236:237], v23
	v_cvt_pk_f32_fp8_sdwa v[238:239], v23 src0_sel:WORD_1
	v_pk_fma_f32 v[96:97], v[224:225], s[26:27], v[96:97] op_sel_hi:[1,0,1]
	v_pk_fma_f32 v[98:99], v[226:227], s[26:27], v[98:99] op_sel_hi:[1,0,1]
	v_pk_fma_f32 v[100:101], v[228:229], s[26:27], v[100:101] op_sel_hi:[1,0,1]
	v_pk_fma_f32 v[102:103], v[230:231], s[26:27], v[102:103] op_sel_hi:[1,0,1]
	v_pk_fma_f32 v[104:105], v[232:233], s[26:27], v[104:105] op_sel_hi:[1,0,1]
	v_pk_fma_f32 v[106:107], v[234:235], s[26:27], v[106:107] op_sel_hi:[1,0,1]
	v_pk_fma_f32 v[108:109], v[236:237], s[26:27], v[108:109] op_sel_hi:[1,0,1]
	v_pk_fma_f32 v[110:111], v[238:239], s[26:27], v[110:111] op_sel_hi:[1,0,1]
	v_cvt_pk_f32_fp8_e32 v[224:225], v24
	v_cvt_pk_f32_fp8_sdwa v[226:227], v24 src0_sel:WORD_1
	v_cvt_pk_f32_fp8_e32 v[228:229], v25
	v_cvt_pk_f32_fp8_sdwa v[230:231], v25 src0_sel:WORD_1
	v_cvt_pk_f32_fp8_e32 v[232:233], v26
	v_cvt_pk_f32_fp8_sdwa v[234:235], v26 src0_sel:WORD_1
	v_cvt_pk_f32_fp8_e32 v[236:237], v27
	v_cvt_pk_f32_fp8_sdwa v[238:239], v27 src0_sel:WORD_1
	v_pk_fma_f32 v[96:97], v[224:225], s[28:29], v[96:97] op_sel_hi:[1,0,1]
	v_pk_fma_f32 v[98:99], v[226:227], s[28:29], v[98:99] op_sel_hi:[1,0,1]
	v_pk_fma_f32 v[100:101], v[228:229], s[28:29], v[100:101] op_sel_hi:[1,0,1]
	v_pk_fma_f32 v[102:103], v[230:231], s[28:29], v[102:103] op_sel_hi:[1,0,1]
	v_pk_fma_f32 v[104:105], v[232:233], s[28:29], v[104:105] op_sel_hi:[1,0,1]
	v_pk_fma_f32 v[106:107], v[234:235], s[28:29], v[106:107] op_sel_hi:[1,0,1]
	v_pk_fma_f32 v[108:109], v[236:237], s[28:29], v[108:109] op_sel_hi:[1,0,1]
	v_pk_fma_f32 v[110:111], v[238:239], s[28:29], v[110:111] op_sel_hi:[1,0,1]
	v_cvt_pk_f32_fp8_e32 v[224:225], v28
	v_cvt_pk_f32_fp8_sdwa v[226:227], v28 src0_sel:WORD_1
	v_cvt_pk_f32_fp8_e32 v[228:229], v29
	v_cvt_pk_f32_fp8_sdwa v[230:231], v29 src0_sel:WORD_1
	v_cvt_pk_f32_fp8_e32 v[232:233], v30
	v_cvt_pk_f32_fp8_sdwa v[234:235], v30 src0_sel:WORD_1
	v_cvt_pk_f32_fp8_e32 v[236:237], v31
	v_cvt_pk_f32_fp8_sdwa v[238:239], v31 src0_sel:WORD_1
	v_pk_fma_f32 v[96:97], v[224:225], s[30:31], v[96:97] op_sel_hi:[1,0,1]
	v_pk_fma_f32 v[98:99], v[226:227], s[30:31], v[98:99] op_sel_hi:[1,0,1]
	v_pk_fma_f32 v[100:101], v[228:229], s[30:31], v[100:101] op_sel_hi:[1,0,1]
	v_pk_fma_f32 v[102:103], v[230:231], s[30:31], v[102:103] op_sel_hi:[1,0,1]
	v_pk_fma_f32 v[104:105], v[232:233], s[30:31], v[104:105] op_sel_hi:[1,0,1]
	v_pk_fma_f32 v[106:107], v[234:235], s[30:31], v[106:107] op_sel_hi:[1,0,1]
	v_pk_fma_f32 v[108:109], v[236:237], s[30:31], v[108:109] op_sel_hi:[1,0,1]
	v_pk_fma_f32 v[110:111], v[238:239], s[30:31], v[110:111] op_sel_hi:[1,0,1]
	v_readlane_b32 s16, v158, s72
	v_readlane_b32 s18, v158, s73
	v_readlane_b32 s20, v158, s74
	v_readlane_b32 s22, v158, s75
	v_readlane_b32 s24, v158, s76
	v_readlane_b32 s26, v158, s77
	v_readlane_b32 s28, v158, s78
	v_readlane_b32 s30, v158, s79
	v_readlane_b32 s48, v153, s72
	v_readlane_b32 s49, v153, s73
	v_readlane_b32 s50, v153, s74
	v_readlane_b32 s51, v153, s75
	v_readlane_b32 s52, v153, s76
	v_readlane_b32 s53, v153, s77
	v_readlane_b32 s54, v153, s78
	v_readlane_b32 s55, v153, s79
	s_add_u32 s32, s0, s48
	s_addc_u32 s33, s1, 0
	s_add_u32 s34, s0, s49
	s_addc_u32 s35, s1, 0
	s_add_u32 s36, s0, s50
	s_addc_u32 s37, s1, 0
	s_add_u32 s38, s0, s51
	s_addc_u32 s39, s1, 0
	s_add_u32 s40, s0, s52
	s_addc_u32 s41, s1, 0
	s_add_u32 s42, s0, s53
	s_addc_u32 s43, s1, 0
	s_add_u32 s44, s0, s54
	s_addc_u32 s45, s1, 0
	s_add_u32 s46, s0, s55
	s_addc_u32 s47, s1, 0
	global_load_dwordx4 v[0:3], v240, s[32:33]
	global_load_dwordx4 v[4:7], v240, s[34:35]
	global_load_dwordx4 v[8:11], v240, s[36:37]
	global_load_dwordx4 v[12:15], v240, s[38:39]
	global_load_dwordx4 v[16:19], v240, s[40:41]
	global_load_dwordx4 v[20:23], v240, s[42:43]
	global_load_dwordx4 v[24:27], v240, s[44:45]
	global_load_dwordx4 v[28:31], v240, s[46:47]
	s_waitcnt vmcnt(24)
	v_cvt_pk_f32_fp8_e32 v[224:225], v32
	v_cvt_pk_f32_fp8_sdwa v[226:227], v32 src0_sel:WORD_1
	v_cvt_pk_f32_fp8_e32 v[228:229], v33
	v_cvt_pk_f32_fp8_sdwa v[230:231], v33 src0_sel:WORD_1
	v_cvt_pk_f32_fp8_e32 v[232:233], v34
	v_cvt_pk_f32_fp8_sdwa v[234:235], v34 src0_sel:WORD_1
	v_cvt_pk_f32_fp8_e32 v[236:237], v35
	v_cvt_pk_f32_fp8_sdwa v[238:239], v35 src0_sel:WORD_1
	v_pk_fma_f32 v[112:113], v[224:225], s[16:17], v[112:113] op_sel_hi:[1,0,1]
	v_pk_fma_f32 v[114:115], v[226:227], s[16:17], v[114:115] op_sel_hi:[1,0,1]
	v_pk_fma_f32 v[116:117], v[228:229], s[16:17], v[116:117] op_sel_hi:[1,0,1]
	v_pk_fma_f32 v[118:119], v[230:231], s[16:17], v[118:119] op_sel_hi:[1,0,1]
	v_pk_fma_f32 v[120:121], v[232:233], s[16:17], v[120:121] op_sel_hi:[1,0,1]
	v_pk_fma_f32 v[122:123], v[234:235], s[16:17], v[122:123] op_sel_hi:[1,0,1]
	v_pk_fma_f32 v[124:125], v[236:237], s[16:17], v[124:125] op_sel_hi:[1,0,1]
	v_pk_fma_f32 v[126:127], v[238:239], s[16:17], v[126:127] op_sel_hi:[1,0,1]
	v_cvt_pk_f32_fp8_e32 v[224:225], v36
	v_cvt_pk_f32_fp8_sdwa v[226:227], v36 src0_sel:WORD_1
	v_cvt_pk_f32_fp8_e32 v[228:229], v37
	v_cvt_pk_f32_fp8_sdwa v[230:231], v37 src0_sel:WORD_1
	v_cvt_pk_f32_fp8_e32 v[232:233], v38
	v_cvt_pk_f32_fp8_sdwa v[234:235], v38 src0_sel:WORD_1
	v_cvt_pk_f32_fp8_e32 v[236:237], v39
	v_cvt_pk_f32_fp8_sdwa v[238:239], v39 src0_sel:WORD_1
	v_pk_fma_f32 v[112:113], v[224:225], s[18:19], v[112:113] op_sel_hi:[1,0,1]
	v_pk_fma_f32 v[114:115], v[226:227], s[18:19], v[114:115] op_sel_hi:[1,0,1]
	v_pk_fma_f32 v[116:117], v[228:229], s[18:19], v[116:117] op_sel_hi:[1,0,1]
	v_pk_fma_f32 v[118:119], v[230:231], s[18:19], v[118:119] op_sel_hi:[1,0,1]
	v_pk_fma_f32 v[120:121], v[232:233], s[18:19], v[120:121] op_sel_hi:[1,0,1]
	v_pk_fma_f32 v[122:123], v[234:235], s[18:19], v[122:123] op_sel_hi:[1,0,1]
	v_pk_fma_f32 v[124:125], v[236:237], s[18:19], v[124:125] op_sel_hi:[1,0,1]
	v_pk_fma_f32 v[126:127], v[238:239], s[18:19], v[126:127] op_sel_hi:[1,0,1]
	v_cvt_pk_f32_fp8_e32 v[224:225], v40
	v_cvt_pk_f32_fp8_sdwa v[226:227], v40 src0_sel:WORD_1
	v_cvt_pk_f32_fp8_e32 v[228:229], v41
	v_cvt_pk_f32_fp8_sdwa v[230:231], v41 src0_sel:WORD_1
	v_cvt_pk_f32_fp8_e32 v[232:233], v42
	v_cvt_pk_f32_fp8_sdwa v[234:235], v42 src0_sel:WORD_1
	v_cvt_pk_f32_fp8_e32 v[236:237], v43
	v_cvt_pk_f32_fp8_sdwa v[238:239], v43 src0_sel:WORD_1
	v_pk_fma_f32 v[112:113], v[224:225], s[20:21], v[112:113] op_sel_hi:[1,0,1]
	v_pk_fma_f32 v[114:115], v[226:227], s[20:21], v[114:115] op_sel_hi:[1,0,1]
	v_pk_fma_f32 v[116:117], v[228:229], s[20:21], v[116:117] op_sel_hi:[1,0,1]
	v_pk_fma_f32 v[118:119], v[230:231], s[20:21], v[118:119] op_sel_hi:[1,0,1]
	v_pk_fma_f32 v[120:121], v[232:233], s[20:21], v[120:121] op_sel_hi:[1,0,1]
	v_pk_fma_f32 v[122:123], v[234:235], s[20:21], v[122:123] op_sel_hi:[1,0,1]
	v_pk_fma_f32 v[124:125], v[236:237], s[20:21], v[124:125] op_sel_hi:[1,0,1]
	v_pk_fma_f32 v[126:127], v[238:239], s[20:21], v[126:127] op_sel_hi:[1,0,1]
	v_cvt_pk_f32_fp8_e32 v[224:225], v44
	v_cvt_pk_f32_fp8_sdwa v[226:227], v44 src0_sel:WORD_1
	v_cvt_pk_f32_fp8_e32 v[228:229], v45
	v_cvt_pk_f32_fp8_sdwa v[230:231], v45 src0_sel:WORD_1
	v_cvt_pk_f32_fp8_e32 v[232:233], v46
	v_cvt_pk_f32_fp8_sdwa v[234:235], v46 src0_sel:WORD_1
	v_cvt_pk_f32_fp8_e32 v[236:237], v47
	v_cvt_pk_f32_fp8_sdwa v[238:239], v47 src0_sel:WORD_1
	v_pk_fma_f32 v[112:113], v[224:225], s[22:23], v[112:113] op_sel_hi:[1,0,1]
	v_pk_fma_f32 v[114:115], v[226:227], s[22:23], v[114:115] op_sel_hi:[1,0,1]
	v_pk_fma_f32 v[116:117], v[228:229], s[22:23], v[116:117] op_sel_hi:[1,0,1]
	v_pk_fma_f32 v[118:119], v[230:231], s[22:23], v[118:119] op_sel_hi:[1,0,1]
	v_pk_fma_f32 v[120:121], v[232:233], s[22:23], v[120:121] op_sel_hi:[1,0,1]
	v_pk_fma_f32 v[122:123], v[234:235], s[22:23], v[122:123] op_sel_hi:[1,0,1]
	v_pk_fma_f32 v[124:125], v[236:237], s[22:23], v[124:125] op_sel_hi:[1,0,1]
	v_pk_fma_f32 v[126:127], v[238:239], s[22:23], v[126:127] op_sel_hi:[1,0,1]
	v_cvt_pk_f32_fp8_e32 v[224:225], v48
	v_cvt_pk_f32_fp8_sdwa v[226:227], v48 src0_sel:WORD_1
	v_cvt_pk_f32_fp8_e32 v[228:229], v49
	v_cvt_pk_f32_fp8_sdwa v[230:231], v49 src0_sel:WORD_1
	v_cvt_pk_f32_fp8_e32 v[232:233], v50
	v_cvt_pk_f32_fp8_sdwa v[234:235], v50 src0_sel:WORD_1
	v_cvt_pk_f32_fp8_e32 v[236:237], v51
	v_cvt_pk_f32_fp8_sdwa v[238:239], v51 src0_sel:WORD_1
	v_pk_fma_f32 v[112:113], v[224:225], s[24:25], v[112:113] op_sel_hi:[1,0,1]
	v_pk_fma_f32 v[114:115], v[226:227], s[24:25], v[114:115] op_sel_hi:[1,0,1]
	v_pk_fma_f32 v[116:117], v[228:229], s[24:25], v[116:117] op_sel_hi:[1,0,1]
	v_pk_fma_f32 v[118:119], v[230:231], s[24:25], v[118:119] op_sel_hi:[1,0,1]
	v_pk_fma_f32 v[120:121], v[232:233], s[24:25], v[120:121] op_sel_hi:[1,0,1]
	v_pk_fma_f32 v[122:123], v[234:235], s[24:25], v[122:123] op_sel_hi:[1,0,1]
	v_pk_fma_f32 v[124:125], v[236:237], s[24:25], v[124:125] op_sel_hi:[1,0,1]
	v_pk_fma_f32 v[126:127], v[238:239], s[24:25], v[126:127] op_sel_hi:[1,0,1]
	v_cvt_pk_f32_fp8_e32 v[224:225], v52
	v_cvt_pk_f32_fp8_sdwa v[226:227], v52 src0_sel:WORD_1
	v_cvt_pk_f32_fp8_e32 v[228:229], v53
	v_cvt_pk_f32_fp8_sdwa v[230:231], v53 src0_sel:WORD_1
	v_cvt_pk_f32_fp8_e32 v[232:233], v54
	v_cvt_pk_f32_fp8_sdwa v[234:235], v54 src0_sel:WORD_1
	v_cvt_pk_f32_fp8_e32 v[236:237], v55
	v_cvt_pk_f32_fp8_sdwa v[238:239], v55 src0_sel:WORD_1
	v_pk_fma_f32 v[112:113], v[224:225], s[26:27], v[112:113] op_sel_hi:[1,0,1]
	v_pk_fma_f32 v[114:115], v[226:227], s[26:27], v[114:115] op_sel_hi:[1,0,1]
	v_pk_fma_f32 v[116:117], v[228:229], s[26:27], v[116:117] op_sel_hi:[1,0,1]
	v_pk_fma_f32 v[118:119], v[230:231], s[26:27], v[118:119] op_sel_hi:[1,0,1]
	v_pk_fma_f32 v[120:121], v[232:233], s[26:27], v[120:121] op_sel_hi:[1,0,1]
	v_pk_fma_f32 v[122:123], v[234:235], s[26:27], v[122:123] op_sel_hi:[1,0,1]
	v_pk_fma_f32 v[124:125], v[236:237], s[26:27], v[124:125] op_sel_hi:[1,0,1]
	v_pk_fma_f32 v[126:127], v[238:239], s[26:27], v[126:127] op_sel_hi:[1,0,1]
	v_cvt_pk_f32_fp8_e32 v[224:225], v56
	v_cvt_pk_f32_fp8_sdwa v[226:227], v56 src0_sel:WORD_1
	v_cvt_pk_f32_fp8_e32 v[228:229], v57
	v_cvt_pk_f32_fp8_sdwa v[230:231], v57 src0_sel:WORD_1
	v_cvt_pk_f32_fp8_e32 v[232:233], v58
	v_cvt_pk_f32_fp8_sdwa v[234:235], v58 src0_sel:WORD_1
	v_cvt_pk_f32_fp8_e32 v[236:237], v59
	v_cvt_pk_f32_fp8_sdwa v[238:239], v59 src0_sel:WORD_1
	v_pk_fma_f32 v[112:113], v[224:225], s[28:29], v[112:113] op_sel_hi:[1,0,1]
	v_pk_fma_f32 v[114:115], v[226:227], s[28:29], v[114:115] op_sel_hi:[1,0,1]
	v_pk_fma_f32 v[116:117], v[228:229], s[28:29], v[116:117] op_sel_hi:[1,0,1]
	v_pk_fma_f32 v[118:119], v[230:231], s[28:29], v[118:119] op_sel_hi:[1,0,1]
	v_pk_fma_f32 v[120:121], v[232:233], s[28:29], v[120:121] op_sel_hi:[1,0,1]
	v_pk_fma_f32 v[122:123], v[234:235], s[28:29], v[122:123] op_sel_hi:[1,0,1]
	v_pk_fma_f32 v[124:125], v[236:237], s[28:29], v[124:125] op_sel_hi:[1,0,1]
	v_pk_fma_f32 v[126:127], v[238:239], s[28:29], v[126:127] op_sel_hi:[1,0,1]
	v_cvt_pk_f32_fp8_e32 v[224:225], v60
	v_cvt_pk_f32_fp8_sdwa v[226:227], v60 src0_sel:WORD_1
	v_cvt_pk_f32_fp8_e32 v[228:229], v61
	v_cvt_pk_f32_fp8_sdwa v[230:231], v61 src0_sel:WORD_1
	v_cvt_pk_f32_fp8_e32 v[232:233], v62
	v_cvt_pk_f32_fp8_sdwa v[234:235], v62 src0_sel:WORD_1
	v_cvt_pk_f32_fp8_e32 v[236:237], v63
	v_cvt_pk_f32_fp8_sdwa v[238:239], v63 src0_sel:WORD_1
	v_pk_fma_f32 v[112:113], v[224:225], s[30:31], v[112:113] op_sel_hi:[1,0,1]
	v_pk_fma_f32 v[114:115], v[226:227], s[30:31], v[114:115] op_sel_hi:[1,0,1]
	v_pk_fma_f32 v[116:117], v[228:229], s[30:31], v[116:117] op_sel_hi:[1,0,1]
	v_pk_fma_f32 v[118:119], v[230:231], s[30:31], v[118:119] op_sel_hi:[1,0,1]
	v_pk_fma_f32 v[120:121], v[232:233], s[30:31], v[120:121] op_sel_hi:[1,0,1]
	v_pk_fma_f32 v[122:123], v[234:235], s[30:31], v[122:123] op_sel_hi:[1,0,1]
	v_pk_fma_f32 v[124:125], v[236:237], s[30:31], v[124:125] op_sel_hi:[1,0,1]
	v_pk_fma_f32 v[126:127], v[238:239], s[30:31], v[126:127] op_sel_hi:[1,0,1]
	v_readlane_b32 s16, v147, s72
	v_readlane_b32 s18, v147, s73
	v_readlane_b32 s20, v147, s74
	v_readlane_b32 s22, v147, s75
	v_readlane_b32 s24, v147, s76
	v_readlane_b32 s26, v147, s77
	v_readlane_b32 s28, v147, s78
	v_readlane_b32 s30, v147, s79
	v_readlane_b32 s48, v157, s72
	v_readlane_b32 s49, v157, s73
	v_readlane_b32 s50, v157, s74
	v_readlane_b32 s51, v157, s75
	v_readlane_b32 s52, v157, s76
	v_readlane_b32 s53, v157, s77
	v_readlane_b32 s54, v157, s78
	v_readlane_b32 s55, v157, s79
	s_add_u32 s32, s0, s48
	s_addc_u32 s33, s1, 0
	s_add_u32 s34, s0, s49
	s_addc_u32 s35, s1, 0
	s_add_u32 s36, s0, s50
	s_addc_u32 s37, s1, 0
	s_add_u32 s38, s0, s51
	s_addc_u32 s39, s1, 0
	s_add_u32 s40, s0, s52
	s_addc_u32 s41, s1, 0
	s_add_u32 s42, s0, s53
	s_addc_u32 s43, s1, 0
	s_add_u32 s44, s0, s54
	s_addc_u32 s45, s1, 0
	s_add_u32 s46, s0, s55
	s_addc_u32 s47, s1, 0
	global_load_dwordx4 v[32:35], v240, s[32:33]
	global_load_dwordx4 v[36:39], v240, s[34:35]
	global_load_dwordx4 v[40:43], v240, s[36:37]
	global_load_dwordx4 v[44:47], v240, s[38:39]
	global_load_dwordx4 v[48:51], v240, s[40:41]
	global_load_dwordx4 v[52:55], v240, s[42:43]
	global_load_dwordx4 v[56:59], v240, s[44:45]
	global_load_dwordx4 v[60:63], v240, s[46:47]
	s_waitcnt vmcnt(24)
	v_cvt_pk_f32_fp8_e32 v[224:225], v160
	v_cvt_pk_f32_fp8_sdwa v[226:227], v160 src0_sel:WORD_1
	v_cvt_pk_f32_fp8_e32 v[228:229], v161
	v_cvt_pk_f32_fp8_sdwa v[230:231], v161 src0_sel:WORD_1
	v_cvt_pk_f32_fp8_e32 v[232:233], v162
	v_cvt_pk_f32_fp8_sdwa v[234:235], v162 src0_sel:WORD_1
	v_cvt_pk_f32_fp8_e32 v[236:237], v163
	v_cvt_pk_f32_fp8_sdwa v[238:239], v163 src0_sel:WORD_1
	v_pk_fma_f32 v[64:65], v[224:225], s[16:17], v[64:65] op_sel_hi:[1,0,1]
	v_pk_fma_f32 v[66:67], v[226:227], s[16:17], v[66:67] op_sel_hi:[1,0,1]
	v_pk_fma_f32 v[68:69], v[228:229], s[16:17], v[68:69] op_sel_hi:[1,0,1]
	v_pk_fma_f32 v[70:71], v[230:231], s[16:17], v[70:71] op_sel_hi:[1,0,1]
	v_pk_fma_f32 v[72:73], v[232:233], s[16:17], v[72:73] op_sel_hi:[1,0,1]
	v_pk_fma_f32 v[74:75], v[234:235], s[16:17], v[74:75] op_sel_hi:[1,0,1]
	v_pk_fma_f32 v[76:77], v[236:237], s[16:17], v[76:77] op_sel_hi:[1,0,1]
	v_pk_fma_f32 v[78:79], v[238:239], s[16:17], v[78:79] op_sel_hi:[1,0,1]
	v_cvt_pk_f32_fp8_e32 v[224:225], v164
	v_cvt_pk_f32_fp8_sdwa v[226:227], v164 src0_sel:WORD_1
	v_cvt_pk_f32_fp8_e32 v[228:229], v165
	v_cvt_pk_f32_fp8_sdwa v[230:231], v165 src0_sel:WORD_1
	v_cvt_pk_f32_fp8_e32 v[232:233], v166
	v_cvt_pk_f32_fp8_sdwa v[234:235], v166 src0_sel:WORD_1
	v_cvt_pk_f32_fp8_e32 v[236:237], v167
	v_cvt_pk_f32_fp8_sdwa v[238:239], v167 src0_sel:WORD_1
	v_pk_fma_f32 v[64:65], v[224:225], s[18:19], v[64:65] op_sel_hi:[1,0,1]
	v_pk_fma_f32 v[66:67], v[226:227], s[18:19], v[66:67] op_sel_hi:[1,0,1]
	v_pk_fma_f32 v[68:69], v[228:229], s[18:19], v[68:69] op_sel_hi:[1,0,1]
	v_pk_fma_f32 v[70:71], v[230:231], s[18:19], v[70:71] op_sel_hi:[1,0,1]
	v_pk_fma_f32 v[72:73], v[232:233], s[18:19], v[72:73] op_sel_hi:[1,0,1]
	v_pk_fma_f32 v[74:75], v[234:235], s[18:19], v[74:75] op_sel_hi:[1,0,1]
	v_pk_fma_f32 v[76:77], v[236:237], s[18:19], v[76:77] op_sel_hi:[1,0,1]
	v_pk_fma_f32 v[78:79], v[238:239], s[18:19], v[78:79] op_sel_hi:[1,0,1]
	v_cvt_pk_f32_fp8_e32 v[224:225], v168
	v_cvt_pk_f32_fp8_sdwa v[226:227], v168 src0_sel:WORD_1
	v_cvt_pk_f32_fp8_e32 v[228:229], v169
	v_cvt_pk_f32_fp8_sdwa v[230:231], v169 src0_sel:WORD_1
	v_cvt_pk_f32_fp8_e32 v[232:233], v170
	v_cvt_pk_f32_fp8_sdwa v[234:235], v170 src0_sel:WORD_1
	v_cvt_pk_f32_fp8_e32 v[236:237], v171
	v_cvt_pk_f32_fp8_sdwa v[238:239], v171 src0_sel:WORD_1
	v_pk_fma_f32 v[64:65], v[224:225], s[20:21], v[64:65] op_sel_hi:[1,0,1]
	v_pk_fma_f32 v[66:67], v[226:227], s[20:21], v[66:67] op_sel_hi:[1,0,1]
	v_pk_fma_f32 v[68:69], v[228:229], s[20:21], v[68:69] op_sel_hi:[1,0,1]
	v_pk_fma_f32 v[70:71], v[230:231], s[20:21], v[70:71] op_sel_hi:[1,0,1]
	v_pk_fma_f32 v[72:73], v[232:233], s[20:21], v[72:73] op_sel_hi:[1,0,1]
	v_pk_fma_f32 v[74:75], v[234:235], s[20:21], v[74:75] op_sel_hi:[1,0,1]
	v_pk_fma_f32 v[76:77], v[236:237], s[20:21], v[76:77] op_sel_hi:[1,0,1]
	v_pk_fma_f32 v[78:79], v[238:239], s[20:21], v[78:79] op_sel_hi:[1,0,1]
	v_cvt_pk_f32_fp8_e32 v[224:225], v172
	v_cvt_pk_f32_fp8_sdwa v[226:227], v172 src0_sel:WORD_1
	v_cvt_pk_f32_fp8_e32 v[228:229], v173
	v_cvt_pk_f32_fp8_sdwa v[230:231], v173 src0_sel:WORD_1
	v_cvt_pk_f32_fp8_e32 v[232:233], v174
	v_cvt_pk_f32_fp8_sdwa v[234:235], v174 src0_sel:WORD_1
	v_cvt_pk_f32_fp8_e32 v[236:237], v175
	v_cvt_pk_f32_fp8_sdwa v[238:239], v175 src0_sel:WORD_1
	v_pk_fma_f32 v[64:65], v[224:225], s[22:23], v[64:65] op_sel_hi:[1,0,1]
	v_pk_fma_f32 v[66:67], v[226:227], s[22:23], v[66:67] op_sel_hi:[1,0,1]
	v_pk_fma_f32 v[68:69], v[228:229], s[22:23], v[68:69] op_sel_hi:[1,0,1]
	v_pk_fma_f32 v[70:71], v[230:231], s[22:23], v[70:71] op_sel_hi:[1,0,1]
	v_pk_fma_f32 v[72:73], v[232:233], s[22:23], v[72:73] op_sel_hi:[1,0,1]
	v_pk_fma_f32 v[74:75], v[234:235], s[22:23], v[74:75] op_sel_hi:[1,0,1]
	v_pk_fma_f32 v[76:77], v[236:237], s[22:23], v[76:77] op_sel_hi:[1,0,1]
	v_pk_fma_f32 v[78:79], v[238:239], s[22:23], v[78:79] op_sel_hi:[1,0,1]
	v_cvt_pk_f32_fp8_e32 v[224:225], v176
	v_cvt_pk_f32_fp8_sdwa v[226:227], v176 src0_sel:WORD_1
	v_cvt_pk_f32_fp8_e32 v[228:229], v177
	v_cvt_pk_f32_fp8_sdwa v[230:231], v177 src0_sel:WORD_1
	v_cvt_pk_f32_fp8_e32 v[232:233], v178
	v_cvt_pk_f32_fp8_sdwa v[234:235], v178 src0_sel:WORD_1
	v_cvt_pk_f32_fp8_e32 v[236:237], v179
	v_cvt_pk_f32_fp8_sdwa v[238:239], v179 src0_sel:WORD_1
	v_pk_fma_f32 v[64:65], v[224:225], s[24:25], v[64:65] op_sel_hi:[1,0,1]
	v_pk_fma_f32 v[66:67], v[226:227], s[24:25], v[66:67] op_sel_hi:[1,0,1]
	v_pk_fma_f32 v[68:69], v[228:229], s[24:25], v[68:69] op_sel_hi:[1,0,1]
	v_pk_fma_f32 v[70:71], v[230:231], s[24:25], v[70:71] op_sel_hi:[1,0,1]
	v_pk_fma_f32 v[72:73], v[232:233], s[24:25], v[72:73] op_sel_hi:[1,0,1]
	v_pk_fma_f32 v[74:75], v[234:235], s[24:25], v[74:75] op_sel_hi:[1,0,1]
	v_pk_fma_f32 v[76:77], v[236:237], s[24:25], v[76:77] op_sel_hi:[1,0,1]
	v_pk_fma_f32 v[78:79], v[238:239], s[24:25], v[78:79] op_sel_hi:[1,0,1]
	v_cvt_pk_f32_fp8_e32 v[224:225], v180
	v_cvt_pk_f32_fp8_sdwa v[226:227], v180 src0_sel:WORD_1
	v_cvt_pk_f32_fp8_e32 v[228:229], v181
	v_cvt_pk_f32_fp8_sdwa v[230:231], v181 src0_sel:WORD_1
	v_cvt_pk_f32_fp8_e32 v[232:233], v182
	v_cvt_pk_f32_fp8_sdwa v[234:235], v182 src0_sel:WORD_1
	v_cvt_pk_f32_fp8_e32 v[236:237], v183
	v_cvt_pk_f32_fp8_sdwa v[238:239], v183 src0_sel:WORD_1
	v_pk_fma_f32 v[64:65], v[224:225], s[26:27], v[64:65] op_sel_hi:[1,0,1]
	v_pk_fma_f32 v[66:67], v[226:227], s[26:27], v[66:67] op_sel_hi:[1,0,1]
	v_pk_fma_f32 v[68:69], v[228:229], s[26:27], v[68:69] op_sel_hi:[1,0,1]
	v_pk_fma_f32 v[70:71], v[230:231], s[26:27], v[70:71] op_sel_hi:[1,0,1]
	v_pk_fma_f32 v[72:73], v[232:233], s[26:27], v[72:73] op_sel_hi:[1,0,1]
	v_pk_fma_f32 v[74:75], v[234:235], s[26:27], v[74:75] op_sel_hi:[1,0,1]
	v_pk_fma_f32 v[76:77], v[236:237], s[26:27], v[76:77] op_sel_hi:[1,0,1]
	v_pk_fma_f32 v[78:79], v[238:239], s[26:27], v[78:79] op_sel_hi:[1,0,1]
	v_cvt_pk_f32_fp8_e32 v[224:225], v184
	v_cvt_pk_f32_fp8_sdwa v[226:227], v184 src0_sel:WORD_1
	v_cvt_pk_f32_fp8_e32 v[228:229], v185
	v_cvt_pk_f32_fp8_sdwa v[230:231], v185 src0_sel:WORD_1
	v_cvt_pk_f32_fp8_e32 v[232:233], v186
	v_cvt_pk_f32_fp8_sdwa v[234:235], v186 src0_sel:WORD_1
	v_cvt_pk_f32_fp8_e32 v[236:237], v187
	v_cvt_pk_f32_fp8_sdwa v[238:239], v187 src0_sel:WORD_1
	v_pk_fma_f32 v[64:65], v[224:225], s[28:29], v[64:65] op_sel_hi:[1,0,1]
	v_pk_fma_f32 v[66:67], v[226:227], s[28:29], v[66:67] op_sel_hi:[1,0,1]
	v_pk_fma_f32 v[68:69], v[228:229], s[28:29], v[68:69] op_sel_hi:[1,0,1]
	v_pk_fma_f32 v[70:71], v[230:231], s[28:29], v[70:71] op_sel_hi:[1,0,1]
	v_pk_fma_f32 v[72:73], v[232:233], s[28:29], v[72:73] op_sel_hi:[1,0,1]
	v_pk_fma_f32 v[74:75], v[234:235], s[28:29], v[74:75] op_sel_hi:[1,0,1]
	v_pk_fma_f32 v[76:77], v[236:237], s[28:29], v[76:77] op_sel_hi:[1,0,1]
	v_pk_fma_f32 v[78:79], v[238:239], s[28:29], v[78:79] op_sel_hi:[1,0,1]
	v_cvt_pk_f32_fp8_e32 v[224:225], v188
	v_cvt_pk_f32_fp8_sdwa v[226:227], v188 src0_sel:WORD_1
	v_cvt_pk_f32_fp8_e32 v[228:229], v189
	v_cvt_pk_f32_fp8_sdwa v[230:231], v189 src0_sel:WORD_1
	v_cvt_pk_f32_fp8_e32 v[232:233], v190
	v_cvt_pk_f32_fp8_sdwa v[234:235], v190 src0_sel:WORD_1
	v_cvt_pk_f32_fp8_e32 v[236:237], v191
	v_cvt_pk_f32_fp8_sdwa v[238:239], v191 src0_sel:WORD_1
	v_pk_fma_f32 v[64:65], v[224:225], s[30:31], v[64:65] op_sel_hi:[1,0,1]
	v_pk_fma_f32 v[66:67], v[226:227], s[30:31], v[66:67] op_sel_hi:[1,0,1]
	v_pk_fma_f32 v[68:69], v[228:229], s[30:31], v[68:69] op_sel_hi:[1,0,1]
	v_pk_fma_f32 v[70:71], v[230:231], s[30:31], v[70:71] op_sel_hi:[1,0,1]
	v_pk_fma_f32 v[72:73], v[232:233], s[30:31], v[72:73] op_sel_hi:[1,0,1]
	v_pk_fma_f32 v[74:75], v[234:235], s[30:31], v[74:75] op_sel_hi:[1,0,1]
	v_pk_fma_f32 v[76:77], v[236:237], s[30:31], v[76:77] op_sel_hi:[1,0,1]
	v_pk_fma_f32 v[78:79], v[238:239], s[30:31], v[78:79] op_sel_hi:[1,0,1]
	v_readlane_b32 s16, v151, s72
	v_readlane_b32 s18, v151, s73
	v_readlane_b32 s20, v151, s74
	v_readlane_b32 s22, v151, s75
	v_readlane_b32 s24, v151, s76
	v_readlane_b32 s26, v151, s77
	v_readlane_b32 s28, v151, s78
	v_readlane_b32 s30, v151, s79
	v_readlane_b32 s48, v144, s80
	v_readlane_b32 s49, v144, s81
	v_readlane_b32 s50, v144, s82
	v_readlane_b32 s51, v144, s83
	v_readlane_b32 s52, v144, s84
	v_readlane_b32 s53, v144, s85
	v_readlane_b32 s54, v144, s86
	v_readlane_b32 s55, v144, s87
	s_add_u32 s32, s0, s48
	s_addc_u32 s33, s1, 0
	s_add_u32 s34, s0, s49
	s_addc_u32 s35, s1, 0
	s_add_u32 s36, s0, s50
	s_addc_u32 s37, s1, 0
	s_add_u32 s38, s0, s51
	s_addc_u32 s39, s1, 0
	s_add_u32 s40, s0, s52
	s_addc_u32 s41, s1, 0
	s_add_u32 s42, s0, s53
	s_addc_u32 s43, s1, 0
	s_add_u32 s44, s0, s54
	s_addc_u32 s45, s1, 0
	s_add_u32 s46, s0, s55
	s_addc_u32 s47, s1, 0
	global_load_dwordx4 v[160:163], v240, s[32:33]
	global_load_dwordx4 v[164:167], v240, s[34:35]
	global_load_dwordx4 v[168:171], v240, s[36:37]
	global_load_dwordx4 v[172:175], v240, s[38:39]
	global_load_dwordx4 v[176:179], v240, s[40:41]
	global_load_dwordx4 v[180:183], v240, s[42:43]
	global_load_dwordx4 v[184:187], v240, s[44:45]
	global_load_dwordx4 v[188:191], v240, s[46:47]
	s_waitcnt vmcnt(24)
	v_cvt_pk_f32_fp8_e32 v[224:225], v192
	v_cvt_pk_f32_fp8_sdwa v[226:227], v192 src0_sel:WORD_1
	v_cvt_pk_f32_fp8_e32 v[228:229], v193
	v_cvt_pk_f32_fp8_sdwa v[230:231], v193 src0_sel:WORD_1
	v_cvt_pk_f32_fp8_e32 v[232:233], v194
	v_cvt_pk_f32_fp8_sdwa v[234:235], v194 src0_sel:WORD_1
	v_cvt_pk_f32_fp8_e32 v[236:237], v195
	v_cvt_pk_f32_fp8_sdwa v[238:239], v195 src0_sel:WORD_1
	v_pk_fma_f32 v[80:81], v[224:225], s[16:17], v[80:81] op_sel_hi:[1,0,1]
	v_pk_fma_f32 v[82:83], v[226:227], s[16:17], v[82:83] op_sel_hi:[1,0,1]
	v_pk_fma_f32 v[84:85], v[228:229], s[16:17], v[84:85] op_sel_hi:[1,0,1]
	v_pk_fma_f32 v[86:87], v[230:231], s[16:17], v[86:87] op_sel_hi:[1,0,1]
	v_pk_fma_f32 v[88:89], v[232:233], s[16:17], v[88:89] op_sel_hi:[1,0,1]
	v_pk_fma_f32 v[90:91], v[234:235], s[16:17], v[90:91] op_sel_hi:[1,0,1]
	v_pk_fma_f32 v[92:93], v[236:237], s[16:17], v[92:93] op_sel_hi:[1,0,1]
	v_pk_fma_f32 v[94:95], v[238:239], s[16:17], v[94:95] op_sel_hi:[1,0,1]
	v_cvt_pk_f32_fp8_e32 v[224:225], v196
	v_cvt_pk_f32_fp8_sdwa v[226:227], v196 src0_sel:WORD_1
	v_cvt_pk_f32_fp8_e32 v[228:229], v197
	v_cvt_pk_f32_fp8_sdwa v[230:231], v197 src0_sel:WORD_1
	v_cvt_pk_f32_fp8_e32 v[232:233], v198
	v_cvt_pk_f32_fp8_sdwa v[234:235], v198 src0_sel:WORD_1
	v_cvt_pk_f32_fp8_e32 v[236:237], v199
	v_cvt_pk_f32_fp8_sdwa v[238:239], v199 src0_sel:WORD_1
	v_pk_fma_f32 v[80:81], v[224:225], s[18:19], v[80:81] op_sel_hi:[1,0,1]
	v_pk_fma_f32 v[82:83], v[226:227], s[18:19], v[82:83] op_sel_hi:[1,0,1]
	v_pk_fma_f32 v[84:85], v[228:229], s[18:19], v[84:85] op_sel_hi:[1,0,1]
	v_pk_fma_f32 v[86:87], v[230:231], s[18:19], v[86:87] op_sel_hi:[1,0,1]
	v_pk_fma_f32 v[88:89], v[232:233], s[18:19], v[88:89] op_sel_hi:[1,0,1]
	v_pk_fma_f32 v[90:91], v[234:235], s[18:19], v[90:91] op_sel_hi:[1,0,1]
	v_pk_fma_f32 v[92:93], v[236:237], s[18:19], v[92:93] op_sel_hi:[1,0,1]
	v_pk_fma_f32 v[94:95], v[238:239], s[18:19], v[94:95] op_sel_hi:[1,0,1]
	v_cvt_pk_f32_fp8_e32 v[224:225], v200
	v_cvt_pk_f32_fp8_sdwa v[226:227], v200 src0_sel:WORD_1
	v_cvt_pk_f32_fp8_e32 v[228:229], v201
	v_cvt_pk_f32_fp8_sdwa v[230:231], v201 src0_sel:WORD_1
	v_cvt_pk_f32_fp8_e32 v[232:233], v202
	v_cvt_pk_f32_fp8_sdwa v[234:235], v202 src0_sel:WORD_1
	v_cvt_pk_f32_fp8_e32 v[236:237], v203
	v_cvt_pk_f32_fp8_sdwa v[238:239], v203 src0_sel:WORD_1
; DI void peer_item_v(const Params& p, int item) {
;     ...
;     V_ISSUE(vqa, 0)
; #pragma unroll 1
;     for (int g = 0; g < 16; g += 2) {
;       V_ISSUE(vqb, g + 1)
;       V_CONSUME(vqa, g)
;       if (g + 2 < 16) V_ISSUE(vqa, g + 2)
;       V_CONSUME(vqb, g + 1)
;     }
	v_pk_fma_f32 v[80:81], v[224:225], s[20:21], v[80:81] op_sel_hi:[1,0,1]
	v_pk_fma_f32 v[82:83], v[226:227], s[20:21], v[82:83] op_sel_hi:[1,0,1]
	v_pk_fma_f32 v[84:85], v[228:229], s[20:21], v[84:85] op_sel_hi:[1,0,1]
	v_pk_fma_f32 v[86:87], v[230:231], s[20:21], v[86:87] op_sel_hi:[1,0,1]
	v_pk_fma_f32 v[88:89], v[232:233], s[20:21], v[88:89] op_sel_hi:[1,0,1]
	v_pk_fma_f32 v[90:91], v[234:235], s[20:21], v[90:91] op_sel_hi:[1,0,1]
	v_pk_fma_f32 v[92:93], v[236:237], s[20:21], v[92:93] op_sel_hi:[1,0,1]
	v_pk_fma_f32 v[94:95], v[238:239], s[20:21], v[94:95] op_sel_hi:[1,0,1]
	v_cvt_pk_f32_fp8_e32 v[224:225], v204
	v_cvt_pk_f32_fp8_sdwa v[226:227], v204 src0_sel:WORD_1
	v_cvt_pk_f32_fp8_e32 v[228:229], v205
	v_cvt_pk_f32_fp8_sdwa v[230:231], v205 src0_sel:WORD_1
	v_cvt_pk_f32_fp8_e32 v[232:233], v206
	v_cvt_pk_f32_fp8_sdwa v[234:235], v206 src0_sel:WORD_1
	v_cvt_pk_f32_fp8_e32 v[236:237], v207
	v_cvt_pk_f32_fp8_sdwa v[238:239], v207 src0_sel:WORD_1
	v_pk_fma_f32 v[80:81], v[224:225], s[22:23], v[80:81] op_sel_hi:[1,0,1]
	v_pk_fma_f32 v[82:83], v[226:227], s[22:23], v[82:83] op_sel_hi:[1,0,1]
	v_pk_fma_f32 v[84:85], v[228:229], s[22:23], v[84:85] op_sel_hi:[1,0,1]
	v_pk_fma_f32 v[86:87], v[230:231], s[22:23], v[86:87] op_sel_hi:[1,0,1]
	v_pk_fma_f32 v[88:89], v[232:233], s[22:23], v[88:89] op_sel_hi:[1,0,1]
	v_pk_fma_f32 v[90:91], v[234:235], s[22:23], v[90:91] op_sel_hi:[1,0,1]
	v_pk_fma_f32 v[92:93], v[236:237], s[22:23], v[92:93] op_sel_hi:[1,0,1]
	v_pk_fma_f32 v[94:95], v[238:239], s[22:23], v[94:95] op_sel_hi:[1,0,1]
	v_cvt_pk_f32_fp8_e32 v[224:225], v208
	v_cvt_pk_f32_fp8_sdwa v[226:227], v208 src0_sel:WORD_1
	v_cvt_pk_f32_fp8_e32 v[228:229], v209
	v_cvt_pk_f32_fp8_sdwa v[230:231], v209 src0_sel:WORD_1
	v_cvt_pk_f32_fp8_e32 v[232:233], v210
	v_cvt_pk_f32_fp8_sdwa v[234:235], v210 src0_sel:WORD_1
	v_cvt_pk_f32_fp8_e32 v[236:237], v211
	v_cvt_pk_f32_fp8_sdwa v[238:239], v211 src0_sel:WORD_1
	v_pk_fma_f32 v[80:81], v[224:225], s[24:25], v[80:81] op_sel_hi:[1,0,1]
	v_pk_fma_f32 v[82:83], v[226:227], s[24:25], v[82:83] op_sel_hi:[1,0,1]
	v_pk_fma_f32 v[84:85], v[228:229], s[24:25], v[84:85] op_sel_hi:[1,0,1]
	v_pk_fma_f32 v[86:87], v[230:231], s[24:25], v[86:87] op_sel_hi:[1,0,1]
	v_pk_fma_f32 v[88:89], v[232:233], s[24:25], v[88:89] op_sel_hi:[1,0,1]
	v_pk_fma_f32 v[90:91], v[234:235], s[24:25], v[90:91] op_sel_hi:[1,0,1]
	v_pk_fma_f32 v[92:93], v[236:237], s[24:25], v[92:93] op_sel_hi:[1,0,1]
	v_pk_fma_f32 v[94:95], v[238:239], s[24:25], v[94:95] op_sel_hi:[1,0,1]
	v_cvt_pk_f32_fp8_e32 v[224:225], v212
	v_cvt_pk_f32_fp8_sdwa v[226:227], v212 src0_sel:WORD_1
	v_cvt_pk_f32_fp8_e32 v[228:229], v213
	v_cvt_pk_f32_fp8_sdwa v[230:231], v213 src0_sel:WORD_1
	v_cvt_pk_f32_fp8_e32 v[232:233], v214
	v_cvt_pk_f32_fp8_sdwa v[234:235], v214 src0_sel:WORD_1
	v_cvt_pk_f32_fp8_e32 v[236:237], v215
	v_cvt_pk_f32_fp8_sdwa v[238:239], v215 src0_sel:WORD_1
	v_pk_fma_f32 v[80:81], v[224:225], s[26:27], v[80:81] op_sel_hi:[1,0,1]
	v_pk_fma_f32 v[82:83], v[226:227], s[26:27], v[82:83] op_sel_hi:[1,0,1]
	v_pk_fma_f32 v[84:85], v[228:229], s[26:27], v[84:85] op_sel_hi:[1,0,1]
	v_pk_fma_f32 v[86:87], v[230:231], s[26:27], v[86:87] op_sel_hi:[1,0,1]
	v_pk_fma_f32 v[88:89], v[232:233], s[26:27], v[88:89] op_sel_hi:[1,0,1]
	v_pk_fma_f32 v[90:91], v[234:235], s[26:27], v[90:91] op_sel_hi:[1,0,1]
	v_pk_fma_f32 v[92:93], v[236:237], s[26:27], v[92:93] op_sel_hi:[1,0,1]
	v_pk_fma_f32 v[94:95], v[238:239], s[26:27], v[94:95] op_sel_hi:[1,0,1]
	v_cvt_pk_f32_fp8_e32 v[224:225], v216
	v_cvt_pk_f32_fp8_sdwa v[226:227], v216 src0_sel:WORD_1
	v_cvt_pk_f32_fp8_e32 v[228:229], v217
	v_cvt_pk_f32_fp8_sdwa v[230:231], v217 src0_sel:WORD_1
	v_cvt_pk_f32_fp8_e32 v[232:233], v218
	v_cvt_pk_f32_fp8_sdwa v[234:235], v218 src0_sel:WORD_1
	v_cvt_pk_f32_fp8_e32 v[236:237], v219
	v_cvt_pk_f32_fp8_sdwa v[238:239], v219 src0_sel:WORD_1
	v_pk_fma_f32 v[80:81], v[224:225], s[28:29], v[80:81] op_sel_hi:[1,0,1]
	v_pk_fma_f32 v[82:83], v[226:227], s[28:29], v[82:83] op_sel_hi:[1,0,1]
	v_pk_fma_f32 v[84:85], v[228:229], s[28:29], v[84:85] op_sel_hi:[1,0,1]
	v_pk_fma_f32 v[86:87], v[230:231], s[28:29], v[86:87] op_sel_hi:[1,0,1]
	v_pk_fma_f32 v[88:89], v[232:233], s[28:29], v[88:89] op_sel_hi:[1,0,1]
	v_pk_fma_f32 v[90:91], v[234:235], s[28:29], v[90:91] op_sel_hi:[1,0,1]
	v_pk_fma_f32 v[92:93], v[236:237], s[28:29], v[92:93] op_sel_hi:[1,0,1]
	v_pk_fma_f32 v[94:95], v[238:239], s[28:29], v[94:95] op_sel_hi:[1,0,1]
	v_cvt_pk_f32_fp8_e32 v[224:225], v220
	v_cvt_pk_f32_fp8_sdwa v[226:227], v220 src0_sel:WORD_1
	v_cvt_pk_f32_fp8_e32 v[228:229], v221
	v_cvt_pk_f32_fp8_sdwa v[230:231], v221 src0_sel:WORD_1
	v_cvt_pk_f32_fp8_e32 v[232:233], v222
	v_cvt_pk_f32_fp8_sdwa v[234:235], v222 src0_sel:WORD_1
	v_cvt_pk_f32_fp8_e32 v[236:237], v223
	v_cvt_pk_f32_fp8_sdwa v[238:239], v223 src0_sel:WORD_1
	v_pk_fma_f32 v[80:81], v[224:225], s[30:31], v[80:81] op_sel_hi:[1,0,1]
	v_pk_fma_f32 v[82:83], v[226:227], s[30:31], v[82:83] op_sel_hi:[1,0,1]
	v_pk_fma_f32 v[84:85], v[228:229], s[30:31], v[84:85] op_sel_hi:[1,0,1]
	v_pk_fma_f32 v[86:87], v[230:231], s[30:31], v[86:87] op_sel_hi:[1,0,1]
	v_pk_fma_f32 v[88:89], v[232:233], s[30:31], v[88:89] op_sel_hi:[1,0,1]
	v_pk_fma_f32 v[90:91], v[234:235], s[30:31], v[90:91] op_sel_hi:[1,0,1]
	v_pk_fma_f32 v[92:93], v[236:237], s[30:31], v[92:93] op_sel_hi:[1,0,1]
	v_pk_fma_f32 v[94:95], v[238:239], s[30:31], v[94:95] op_sel_hi:[1,0,1]
	v_readlane_b32 s16, v155, s72
	v_readlane_b32 s18, v155, s73
	v_readlane_b32 s20, v155, s74
	v_readlane_b32 s22, v155, s75
	v_readlane_b32 s24, v155, s76
	v_readlane_b32 s26, v155, s77
	v_readlane_b32 s28, v155, s78
	v_readlane_b32 s30, v155, s79
	v_readlane_b32 s48, v148, s80
	v_readlane_b32 s49, v148, s81
	v_readlane_b32 s50, v148, s82
	v_readlane_b32 s51, v148, s83
	v_readlane_b32 s52, v148, s84
	v_readlane_b32 s53, v148, s85
	v_readlane_b32 s54, v148, s86
	v_readlane_b32 s55, v148, s87
	s_add_u32 s32, s0, s48
	s_addc_u32 s33, s1, 0
	s_add_u32 s34, s0, s49
	s_addc_u32 s35, s1, 0
	s_add_u32 s36, s0, s50
	s_addc_u32 s37, s1, 0
	s_add_u32 s38, s0, s51
	s_addc_u32 s39, s1, 0
	s_add_u32 s40, s0, s52
	s_addc_u32 s41, s1, 0
	s_add_u32 s42, s0, s53
	s_addc_u32 s43, s1, 0
	s_add_u32 s44, s0, s54
	s_addc_u32 s45, s1, 0
	s_add_u32 s46, s0, s55
	s_addc_u32 s47, s1, 0
	global_load_dwordx4 v[192:195], v240, s[32:33]
	global_load_dwordx4 v[196:199], v240, s[34:35]
	global_load_dwordx4 v[200:203], v240, s[36:37]
	global_load_dwordx4 v[204:207], v240, s[38:39]
	global_load_dwordx4 v[208:211], v240, s[40:41]
	global_load_dwordx4 v[212:215], v240, s[42:43]
	global_load_dwordx4 v[216:219], v240, s[44:45]
	global_load_dwordx4 v[220:223], v240, s[46:47]
	s_waitcnt vmcnt(24)
	v_cvt_pk_f32_fp8_e32 v[224:225], v0
	v_cvt_pk_f32_fp8_sdwa v[226:227], v0 src0_sel:WORD_1
	v_cvt_pk_f32_fp8_e32 v[228:229], v1
	v_cvt_pk_f32_fp8_sdwa v[230:231], v1 src0_sel:WORD_1
	v_cvt_pk_f32_fp8_e32 v[232:233], v2
	v_cvt_pk_f32_fp8_sdwa v[234:235], v2 src0_sel:WORD_1
	v_cvt_pk_f32_fp8_e32 v[236:237], v3
	v_cvt_pk_f32_fp8_sdwa v[238:239], v3 src0_sel:WORD_1
	v_pk_fma_f32 v[96:97], v[224:225], s[16:17], v[96:97] op_sel_hi:[1,0,1]
	v_pk_fma_f32 v[98:99], v[226:227], s[16:17], v[98:99] op_sel_hi:[1,0,1]
	v_pk_fma_f32 v[100:101], v[228:229], s[16:17], v[100:101] op_sel_hi:[1,0,1]
	v_pk_fma_f32 v[102:103], v[230:231], s[16:17], v[102:103] op_sel_hi:[1,0,1]
	v_pk_fma_f32 v[104:105], v[232:233], s[16:17], v[104:105] op_sel_hi:[1,0,1]
	v_pk_fma_f32 v[106:107], v[234:235], s[16:17], v[106:107] op_sel_hi:[1,0,1]
	v_pk_fma_f32 v[108:109], v[236:237], s[16:17], v[108:109] op_sel_hi:[1,0,1]
	v_pk_fma_f32 v[110:111], v[238:239], s[16:17], v[110:111] op_sel_hi:[1,0,1]
	v_cvt_pk_f32_fp8_e32 v[224:225], v4
	v_cvt_pk_f32_fp8_sdwa v[226:227], v4 src0_sel:WORD_1
	v_cvt_pk_f32_fp8_e32 v[228:229], v5
	v_cvt_pk_f32_fp8_sdwa v[230:231], v5 src0_sel:WORD_1
	v_cvt_pk_f32_fp8_e32 v[232:233], v6
	v_cvt_pk_f32_fp8_sdwa v[234:235], v6 src0_sel:WORD_1
	v_cvt_pk_f32_fp8_e32 v[236:237], v7
	v_cvt_pk_f32_fp8_sdwa v[238:239], v7 src0_sel:WORD_1
	v_pk_fma_f32 v[96:97], v[224:225], s[18:19], v[96:97] op_sel_hi:[1,0,1]
	v_pk_fma_f32 v[98:99], v[226:227], s[18:19], v[98:99] op_sel_hi:[1,0,1]
	v_pk_fma_f32 v[100:101], v[228:229], s[18:19], v[100:101] op_sel_hi:[1,0,1]
	v_pk_fma_f32 v[102:103], v[230:231], s[18:19], v[102:103] op_sel_hi:[1,0,1]
	v_pk_fma_f32 v[104:105], v[232:233], s[18:19], v[104:105] op_sel_hi:[1,0,1]
	v_pk_fma_f32 v[106:107], v[234:235], s[18:19], v[106:107] op_sel_hi:[1,0,1]
	v_pk_fma_f32 v[108:109], v[236:237], s[18:19], v[108:109] op_sel_hi:[1,0,1]
	v_pk_fma_f32 v[110:111], v[238:239], s[18:19], v[110:111] op_sel_hi:[1,0,1]
	v_cvt_pk_f32_fp8_e32 v[224:225], v8
	v_cvt_pk_f32_fp8_sdwa v[226:227], v8 src0_sel:WORD_1
	v_cvt_pk_f32_fp8_e32 v[228:229], v9
	v_cvt_pk_f32_fp8_sdwa v[230:231], v9 src0_sel:WORD_1
	v_cvt_pk_f32_fp8_e32 v[232:233], v10
	v_cvt_pk_f32_fp8_sdwa v[234:235], v10 src0_sel:WORD_1
	v_cvt_pk_f32_fp8_e32 v[236:237], v11
	v_cvt_pk_f32_fp8_sdwa v[238:239], v11 src0_sel:WORD_1
	v_pk_fma_f32 v[96:97], v[224:225], s[20:21], v[96:97] op_sel_hi:[1,0,1]
	v_pk_fma_f32 v[98:99], v[226:227], s[20:21], v[98:99] op_sel_hi:[1,0,1]
	v_pk_fma_f32 v[100:101], v[228:229], s[20:21], v[100:101] op_sel_hi:[1,0,1]
	v_pk_fma_f32 v[102:103], v[230:231], s[20:21], v[102:103] op_sel_hi:[1,0,1]
	v_pk_fma_f32 v[104:105], v[232:233], s[20:21], v[104:105] op_sel_hi:[1,0,1]
	v_pk_fma_f32 v[106:107], v[234:235], s[20:21], v[106:107] op_sel_hi:[1,0,1]
	v_pk_fma_f32 v[108:109], v[236:237], s[20:21], v[108:109] op_sel_hi:[1,0,1]
	v_pk_fma_f32 v[110:111], v[238:239], s[20:21], v[110:111] op_sel_hi:[1,0,1]
	v_cvt_pk_f32_fp8_e32 v[224:225], v12
	v_cvt_pk_f32_fp8_sdwa v[226:227], v12 src0_sel:WORD_1
	v_cvt_pk_f32_fp8_e32 v[228:229], v13
	v_cvt_pk_f32_fp8_sdwa v[230:231], v13 src0_sel:WORD_1
	v_cvt_pk_f32_fp8_e32 v[232:233], v14
	v_cvt_pk_f32_fp8_sdwa v[234:235], v14 src0_sel:WORD_1
	v_cvt_pk_f32_fp8_e32 v[236:237], v15
	v_cvt_pk_f32_fp8_sdwa v[238:239], v15 src0_sel:WORD_1
	v_pk_fma_f32 v[96:97], v[224:225], s[22:23], v[96:97] op_sel_hi:[1,0,1]
	v_pk_fma_f32 v[98:99], v[226:227], s[22:23], v[98:99] op_sel_hi:[1,0,1]
	v_pk_fma_f32 v[100:101], v[228:229], s[22:23], v[100:101] op_sel_hi:[1,0,1]
	v_pk_fma_f32 v[102:103], v[230:231], s[22:23], v[102:103] op_sel_hi:[1,0,1]
	v_pk_fma_f32 v[104:105], v[232:233], s[22:23], v[104:105] op_sel_hi:[1,0,1]
	v_pk_fma_f32 v[106:107], v[234:235], s[22:23], v[106:107] op_sel_hi:[1,0,1]
	v_pk_fma_f32 v[108:109], v[236:237], s[22:23], v[108:109] op_sel_hi:[1,0,1]
	v_pk_fma_f32 v[110:111], v[238:239], s[22:23], v[110:111] op_sel_hi:[1,0,1]
	v_cvt_pk_f32_fp8_e32 v[224:225], v16
	v_cvt_pk_f32_fp8_sdwa v[226:227], v16 src0_sel:WORD_1
	v_cvt_pk_f32_fp8_e32 v[228:229], v17
	v_cvt_pk_f32_fp8_sdwa v[230:231], v17 src0_sel:WORD_1
	v_cvt_pk_f32_fp8_e32 v[232:233], v18
	v_cvt_pk_f32_fp8_sdwa v[234:235], v18 src0_sel:WORD_1
	v_cvt_pk_f32_fp8_e32 v[236:237], v19
	v_cvt_pk_f32_fp8_sdwa v[238:239], v19 src0_sel:WORD_1
	v_pk_fma_f32 v[96:97], v[224:225], s[24:25], v[96:97] op_sel_hi:[1,0,1]
	v_pk_fma_f32 v[98:99], v[226:227], s[24:25], v[98:99] op_sel_hi:[1,0,1]
	v_pk_fma_f32 v[100:101], v[228:229], s[24:25], v[100:101] op_sel_hi:[1,0,1]
	v_pk_fma_f32 v[102:103], v[230:231], s[24:25], v[102:103] op_sel_hi:[1,0,1]
	v_pk_fma_f32 v[104:105], v[232:233], s[24:25], v[104:105] op_sel_hi:[1,0,1]
	v_pk_fma_f32 v[106:107], v[234:235], s[24:25], v[106:107] op_sel_hi:[1,0,1]
	v_pk_fma_f32 v[108:109], v[236:237], s[24:25], v[108:109] op_sel_hi:[1,0,1]
	v_pk_fma_f32 v[110:111], v[238:239], s[24:25], v[110:111] op_sel_hi:[1,0,1]
	v_cvt_pk_f32_fp8_e32 v[224:225], v20
	v_cvt_pk_f32_fp8_sdwa v[226:227], v20 src0_sel:WORD_1
	v_cvt_pk_f32_fp8_e32 v[228:229], v21
	v_cvt_pk_f32_fp8_sdwa v[230:231], v21 src0_sel:WORD_1
	v_cvt_pk_f32_fp8_e32 v[232:233], v22
	v_cvt_pk_f32_fp8_sdwa v[234:235], v22 src0_sel:WORD_1
	v_cvt_pk_f32_fp8_e32 v[236:237], v23
	v_cvt_pk_f32_fp8_sdwa v[238:239], v23 src0_sel:WORD_1
	v_pk_fma_f32 v[96:97], v[224:225], s[26:27], v[96:97] op_sel_hi:[1,0,1]
	v_pk_fma_f32 v[98:99], v[226:227], s[26:27], v[98:99] op_sel_hi:[1,0,1]
	v_pk_fma_f32 v[100:101], v[228:229], s[26:27], v[100:101] op_sel_hi:[1,0,1]
	v_pk_fma_f32 v[102:103], v[230:231], s[26:27], v[102:103] op_sel_hi:[1,0,1]
	v_pk_fma_f32 v[104:105], v[232:233], s[26:27], v[104:105] op_sel_hi:[1,0,1]
; DI void peer_item_v(const Params& p, int item) {
;     ...
;     V_ISSUE(vqa, 0)
; #pragma unroll 1
;     for (int g = 0; g < 16; g += 2) {
;       V_ISSUE(vqb, g + 1)
;       V_CONSUME(vqa, g)
;       if (g + 2 < 16) V_ISSUE(vqa, g + 2)
;       V_CONSUME(vqb, g + 1)
;     }
	v_pk_fma_f32 v[106:107], v[234:235], s[26:27], v[106:107] op_sel_hi:[1,0,1]
	v_pk_fma_f32 v[108:109], v[236:237], s[26:27], v[108:109] op_sel_hi:[1,0,1]
	v_pk_fma_f32 v[110:111], v[238:239], s[26:27], v[110:111] op_sel_hi:[1,0,1]
	v_cvt_pk_f32_fp8_e32 v[224:225], v24
	v_cvt_pk_f32_fp8_sdwa v[226:227], v24 src0_sel:WORD_1
	v_cvt_pk_f32_fp8_e32 v[228:229], v25
	v_cvt_pk_f32_fp8_sdwa v[230:231], v25 src0_sel:WORD_1
	v_cvt_pk_f32_fp8_e32 v[232:233], v26
	v_cvt_pk_f32_fp8_sdwa v[234:235], v26 src0_sel:WORD_1
	v_cvt_pk_f32_fp8_e32 v[236:237], v27
	v_cvt_pk_f32_fp8_sdwa v[238:239], v27 src0_sel:WORD_1
	v_pk_fma_f32 v[96:97], v[224:225], s[28:29], v[96:97] op_sel_hi:[1,0,1]
	v_pk_fma_f32 v[98:99], v[226:227], s[28:29], v[98:99] op_sel_hi:[1,0,1]
	v_pk_fma_f32 v[100:101], v[228:229], s[28:29], v[100:101] op_sel_hi:[1,0,1]
	v_pk_fma_f32 v[102:103], v[230:231], s[28:29], v[102:103] op_sel_hi:[1,0,1]
	v_pk_fma_f32 v[104:105], v[232:233], s[28:29], v[104:105] op_sel_hi:[1,0,1]
	v_pk_fma_f32 v[106:107], v[234:235], s[28:29], v[106:107] op_sel_hi:[1,0,1]
	v_pk_fma_f32 v[108:109], v[236:237], s[28:29], v[108:109] op_sel_hi:[1,0,1]
	v_pk_fma_f32 v[110:111], v[238:239], s[28:29], v[110:111] op_sel_hi:[1,0,1]
	v_cvt_pk_f32_fp8_e32 v[224:225], v28
	v_cvt_pk_f32_fp8_sdwa v[226:227], v28 src0_sel:WORD_1
	v_cvt_pk_f32_fp8_e32 v[228:229], v29
	v_cvt_pk_f32_fp8_sdwa v[230:231], v29 src0_sel:WORD_1
	v_cvt_pk_f32_fp8_e32 v[232:233], v30
	v_cvt_pk_f32_fp8_sdwa v[234:235], v30 src0_sel:WORD_1
	v_cvt_pk_f32_fp8_e32 v[236:237], v31
	v_cvt_pk_f32_fp8_sdwa v[238:239], v31 src0_sel:WORD_1
	v_pk_fma_f32 v[96:97], v[224:225], s[30:31], v[96:97] op_sel_hi:[1,0,1]
	v_pk_fma_f32 v[98:99], v[226:227], s[30:31], v[98:99] op_sel_hi:[1,0,1]
	v_pk_fma_f32 v[100:101], v[228:229], s[30:31], v[100:101] op_sel_hi:[1,0,1]
	v_pk_fma_f32 v[102:103], v[230:231], s[30:31], v[102:103] op_sel_hi:[1,0,1]
	v_pk_fma_f32 v[104:105], v[232:233], s[30:31], v[104:105] op_sel_hi:[1,0,1]
	v_pk_fma_f32 v[106:107], v[234:235], s[30:31], v[106:107] op_sel_hi:[1,0,1]
	v_pk_fma_f32 v[108:109], v[236:237], s[30:31], v[108:109] op_sel_hi:[1,0,1]
	v_pk_fma_f32 v[110:111], v[238:239], s[30:31], v[110:111] op_sel_hi:[1,0,1]
	v_readlane_b32 s16, v159, s72
	v_readlane_b32 s18, v159, s73
	v_readlane_b32 s20, v159, s74
	v_readlane_b32 s22, v159, s75
	v_readlane_b32 s24, v159, s76
	v_readlane_b32 s26, v159, s77
	v_readlane_b32 s28, v159, s78
	v_readlane_b32 s30, v159, s79
	v_readlane_b32 s48, v152, s80
	v_readlane_b32 s49, v152, s81
	v_readlane_b32 s50, v152, s82
	v_readlane_b32 s51, v152, s83
	v_readlane_b32 s52, v152, s84
	v_readlane_b32 s53, v152, s85
	v_readlane_b32 s54, v152, s86
	v_readlane_b32 s55, v152, s87
	s_add_u32 s32, s0, s48
	s_addc_u32 s33, s1, 0
	s_add_u32 s34, s0, s49
	s_addc_u32 s35, s1, 0
	s_add_u32 s36, s0, s50
	s_addc_u32 s37, s1, 0
	s_add_u32 s38, s0, s51
	s_addc_u32 s39, s1, 0
	s_add_u32 s40, s0, s52
	s_addc_u32 s41, s1, 0
	s_add_u32 s42, s0, s53
	s_addc_u32 s43, s1, 0
	s_add_u32 s44, s0, s54
	s_addc_u32 s45, s1, 0
	s_add_u32 s46, s0, s55
	s_addc_u32 s47, s1, 0
	global_load_dwordx4 v[0:3], v240, s[32:33]
	global_load_dwordx4 v[4:7], v240, s[34:35]
	global_load_dwordx4 v[8:11], v240, s[36:37]
	global_load_dwordx4 v[12:15], v240, s[38:39]
	global_load_dwordx4 v[16:19], v240, s[40:41]
	global_load_dwordx4 v[20:23], v240, s[42:43]
	global_load_dwordx4 v[24:27], v240, s[44:45]
	global_load_dwordx4 v[28:31], v240, s[46:47]
	s_waitcnt vmcnt(24)
	v_cvt_pk_f32_fp8_e32 v[224:225], v32
	v_cvt_pk_f32_fp8_sdwa v[226:227], v32 src0_sel:WORD_1
	v_cvt_pk_f32_fp8_e32 v[228:229], v33
	v_cvt_pk_f32_fp8_sdwa v[230:231], v33 src0_sel:WORD_1
	v_cvt_pk_f32_fp8_e32 v[232:233], v34
	v_cvt_pk_f32_fp8_sdwa v[234:235], v34 src0_sel:WORD_1
	v_cvt_pk_f32_fp8_e32 v[236:237], v35
	v_cvt_pk_f32_fp8_sdwa v[238:239], v35 src0_sel:WORD_1
	v_pk_fma_f32 v[112:113], v[224:225], s[16:17], v[112:113] op_sel_hi:[1,0,1]
	v_pk_fma_f32 v[114:115], v[226:227], s[16:17], v[114:115] op_sel_hi:[1,0,1]
	v_pk_fma_f32 v[116:117], v[228:229], s[16:17], v[116:117] op_sel_hi:[1,0,1]
	v_pk_fma_f32 v[118:119], v[230:231], s[16:17], v[118:119] op_sel_hi:[1,0,1]
	v_pk_fma_f32 v[120:121], v[232:233], s[16:17], v[120:121] op_sel_hi:[1,0,1]
	v_pk_fma_f32 v[122:123], v[234:235], s[16:17], v[122:123] op_sel_hi:[1,0,1]
	v_pk_fma_f32 v[124:125], v[236:237], s[16:17], v[124:125] op_sel_hi:[1,0,1]
	v_pk_fma_f32 v[126:127], v[238:239], s[16:17], v[126:127] op_sel_hi:[1,0,1]
	v_cvt_pk_f32_fp8_e32 v[224:225], v36
	v_cvt_pk_f32_fp8_sdwa v[226:227], v36 src0_sel:WORD_1
	v_cvt_pk_f32_fp8_e32 v[228:229], v37
	v_cvt_pk_f32_fp8_sdwa v[230:231], v37 src0_sel:WORD_1
	v_cvt_pk_f32_fp8_e32 v[232:233], v38
	v_cvt_pk_f32_fp8_sdwa v[234:235], v38 src0_sel:WORD_1
	v_cvt_pk_f32_fp8_e32 v[236:237], v39
	v_cvt_pk_f32_fp8_sdwa v[238:239], v39 src0_sel:WORD_1
	v_pk_fma_f32 v[112:113], v[224:225], s[18:19], v[112:113] op_sel_hi:[1,0,1]
	v_pk_fma_f32 v[114:115], v[226:227], s[18:19], v[114:115] op_sel_hi:[1,0,1]
	v_pk_fma_f32 v[116:117], v[228:229], s[18:19], v[116:117] op_sel_hi:[1,0,1]
	v_pk_fma_f32 v[118:119], v[230:231], s[18:19], v[118:119] op_sel_hi:[1,0,1]
	v_pk_fma_f32 v[120:121], v[232:233], s[18:19], v[120:121] op_sel_hi:[1,0,1]
	v_pk_fma_f32 v[122:123], v[234:235], s[18:19], v[122:123] op_sel_hi:[1,0,1]
	v_pk_fma_f32 v[124:125], v[236:237], s[18:19], v[124:125] op_sel_hi:[1,0,1]
	v_pk_fma_f32 v[126:127], v[238:239], s[18:19], v[126:127] op_sel_hi:[1,0,1]
	v_cvt_pk_f32_fp8_e32 v[224:225], v40
	v_cvt_pk_f32_fp8_sdwa v[226:227], v40 src0_sel:WORD_1
	v_cvt_pk_f32_fp8_e32 v[228:229], v41
	v_cvt_pk_f32_fp8_sdwa v[230:231], v41 src0_sel:WORD_1
	v_cvt_pk_f32_fp8_e32 v[232:233], v42
; DI void peer_item_v(const Params& p, int item) {
;     ...
;     V_ISSUE(vqa, 0)
; #pragma unroll 1
;     for (int g = 0; g < 16; g += 2) {
;       V_ISSUE(vqb, g + 1)
;       V_CONSUME(vqa, g)
;       if (g + 2 < 16) V_ISSUE(vqa, g + 2)
;       V_CONSUME(vqb, g + 1)
;     }
	v_cvt_pk_f32_fp8_sdwa v[234:235], v42 src0_sel:WORD_1
	v_cvt_pk_f32_fp8_e32 v[236:237], v43
	v_cvt_pk_f32_fp8_sdwa v[238:239], v43 src0_sel:WORD_1
	v_pk_fma_f32 v[112:113], v[224:225], s[20:21], v[112:113] op_sel_hi:[1,0,1]
	v_pk_fma_f32 v[114:115], v[226:227], s[20:21], v[114:115] op_sel_hi:[1,0,1]
	v_pk_fma_f32 v[116:117], v[228:229], s[20:21], v[116:117] op_sel_hi:[1,0,1]
	v_pk_fma_f32 v[118:119], v[230:231], s[20:21], v[118:119] op_sel_hi:[1,0,1]
	v_pk_fma_f32 v[120:121], v[232:233], s[20:21], v[120:121] op_sel_hi:[1,0,1]
	v_pk_fma_f32 v[122:123], v[234:235], s[20:21], v[122:123] op_sel_hi:[1,0,1]
	v_pk_fma_f32 v[124:125], v[236:237], s[20:21], v[124:125] op_sel_hi:[1,0,1]
	v_pk_fma_f32 v[126:127], v[238:239], s[20:21], v[126:127] op_sel_hi:[1,0,1]
	v_cvt_pk_f32_fp8_e32 v[224:225], v44
	v_cvt_pk_f32_fp8_sdwa v[226:227], v44 src0_sel:WORD_1
	v_cvt_pk_f32_fp8_e32 v[228:229], v45
	v_cvt_pk_f32_fp8_sdwa v[230:231], v45 src0_sel:WORD_1
	v_cvt_pk_f32_fp8_e32 v[232:233], v46
	v_cvt_pk_f32_fp8_sdwa v[234:235], v46 src0_sel:WORD_1
	v_cvt_pk_f32_fp8_e32 v[236:237], v47
	v_cvt_pk_f32_fp8_sdwa v[238:239], v47 src0_sel:WORD_1
	v_pk_fma_f32 v[112:113], v[224:225], s[22:23], v[112:113] op_sel_hi:[1,0,1]
	v_pk_fma_f32 v[114:115], v[226:227], s[22:23], v[114:115] op_sel_hi:[1,0,1]
	v_pk_fma_f32 v[116:117], v[228:229], s[22:23], v[116:117] op_sel_hi:[1,0,1]
	v_pk_fma_f32 v[118:119], v[230:231], s[22:23], v[118:119] op_sel_hi:[1,0,1]
	v_pk_fma_f32 v[120:121], v[232:233], s[22:23], v[120:121] op_sel_hi:[1,0,1]
	v_pk_fma_f32 v[122:123], v[234:235], s[22:23], v[122:123] op_sel_hi:[1,0,1]
	v_pk_fma_f32 v[124:125], v[236:237], s[22:23], v[124:125] op_sel_hi:[1,0,1]
	v_pk_fma_f32 v[126:127], v[238:239], s[22:23], v[126:127] op_sel_hi:[1,0,1]
	v_cvt_pk_f32_fp8_e32 v[224:225], v48
	v_cvt_pk_f32_fp8_sdwa v[226:227], v48 src0_sel:WORD_1
	v_cvt_pk_f32_fp8_e32 v[228:229], v49
	v_cvt_pk_f32_fp8_sdwa v[230:231], v49 src0_sel:WORD_1
	v_cvt_pk_f32_fp8_e32 v[232:233], v50
	v_cvt_pk_f32_fp8_sdwa v[234:235], v50 src0_sel:WORD_1
	v_cvt_pk_f32_fp8_e32 v[236:237], v51
	v_cvt_pk_f32_fp8_sdwa v[238:239], v51 src0_sel:WORD_1
	v_pk_fma_f32 v[112:113], v[224:225], s[24:25], v[112:113] op_sel_hi:[1,0,1]
	v_pk_fma_f32 v[114:115], v[226:227], s[24:25], v[114:115] op_sel_hi:[1,0,1]
	v_pk_fma_f32 v[116:117], v[228:229], s[24:25], v[116:117] op_sel_hi:[1,0,1]
	v_pk_fma_f32 v[118:119], v[230:231], s[24:25], v[118:119] op_sel_hi:[1,0,1]
	v_pk_fma_f32 v[120:121], v[232:233], s[24:25], v[120:121] op_sel_hi:[1,0,1]
	v_pk_fma_f32 v[122:123], v[234:235], s[24:25], v[122:123] op_sel_hi:[1,0,1]
	v_pk_fma_f32 v[124:125], v[236:237], s[24:25], v[124:125] op_sel_hi:[1,0,1]
	v_pk_fma_f32 v[126:127], v[238:239], s[24:25], v[126:127] op_sel_hi:[1,0,1]
	v_cvt_pk_f32_fp8_e32 v[224:225], v52
	v_cvt_pk_f32_fp8_sdwa v[226:227], v52 src0_sel:WORD_1
	v_cvt_pk_f32_fp8_e32 v[228:229], v53
	v_cvt_pk_f32_fp8_sdwa v[230:231], v53 src0_sel:WORD_1
	v_cvt_pk_f32_fp8_e32 v[232:233], v54
	v_cvt_pk_f32_fp8_sdwa v[234:235], v54 src0_sel:WORD_1
	v_cvt_pk_f32_fp8_e32 v[236:237], v55
	v_cvt_pk_f32_fp8_sdwa v[238:239], v55 src0_sel:WORD_1
	v_pk_fma_f32 v[112:113], v[224:225], s[26:27], v[112:113] op_sel_hi:[1,0,1]
	v_pk_fma_f32 v[114:115], v[226:227], s[26:27], v[114:115] op_sel_hi:[1,0,1]
	v_pk_fma_f32 v[116:117], v[228:229], s[26:27], v[116:117] op_sel_hi:[1,0,1]
	v_pk_fma_f32 v[118:119], v[230:231], s[26:27], v[118:119] op_sel_hi:[1,0,1]
	v_pk_fma_f32 v[120:121], v[232:233], s[26:27], v[120:121] op_sel_hi:[1,0,1]
	v_pk_fma_f32 v[122:123], v[234:235], s[26:27], v[122:123] op_sel_hi:[1,0,1]
	v_pk_fma_f32 v[124:125], v[236:237], s[26:27], v[124:125] op_sel_hi:[1,0,1]
	v_pk_fma_f32 v[126:127], v[238:239], s[26:27], v[126:127] op_sel_hi:[1,0,1]
	v_cvt_pk_f32_fp8_e32 v[224:225], v56
	v_cvt_pk_f32_fp8_sdwa v[226:227], v56 src0_sel:WORD_1
	v_cvt_pk_f32_fp8_e32 v[228:229], v57
	v_cvt_pk_f32_fp8_sdwa v[230:231], v57 src0_sel:WORD_1
	v_cvt_pk_f32_fp8_e32 v[232:233], v58
	v_cvt_pk_f32_fp8_sdwa v[234:235], v58 src0_sel:WORD_1
	v_cvt_pk_f32_fp8_e32 v[236:237], v59
	v_cvt_pk_f32_fp8_sdwa v[238:239], v59 src0_sel:WORD_1
	v_pk_fma_f32 v[112:113], v[224:225], s[28:29], v[112:113] op_sel_hi:[1,0,1]
	v_pk_fma_f32 v[114:115], v[226:227], s[28:29], v[114:115] op_sel_hi:[1,0,1]
	v_pk_fma_f32 v[116:117], v[228:229], s[28:29], v[116:117] op_sel_hi:[1,0,1]
	v_pk_fma_f32 v[118:119], v[230:231], s[28:29], v[118:119] op_sel_hi:[1,0,1]
	v_pk_fma_f32 v[120:121], v[232:233], s[28:29], v[120:121] op_sel_hi:[1,0,1]
	v_pk_fma_f32 v[122:123], v[234:235], s[28:29], v[122:123] op_sel_hi:[1,0,1]
	v_pk_fma_f32 v[124:125], v[236:237], s[28:29], v[124:125] op_sel_hi:[1,0,1]
	v_pk_fma_f32 v[126:127], v[238:239], s[28:29], v[126:127] op_sel_hi:[1,0,1]
	v_cvt_pk_f32_fp8_e32 v[224:225], v60
	v_cvt_pk_f32_fp8_sdwa v[226:227], v60 src0_sel:WORD_1
	v_cvt_pk_f32_fp8_e32 v[228:229], v61
	v_cvt_pk_f32_fp8_sdwa v[230:231], v61 src0_sel:WORD_1
	v_cvt_pk_f32_fp8_e32 v[232:233], v62
	v_cvt_pk_f32_fp8_sdwa v[234:235], v62 src0_sel:WORD_1
	v_cvt_pk_f32_fp8_e32 v[236:237], v63
	v_cvt_pk_f32_fp8_sdwa v[238:239], v63 src0_sel:WORD_1
	v_pk_fma_f32 v[112:113], v[224:225], s[30:31], v[112:113] op_sel_hi:[1,0,1]
	v_pk_fma_f32 v[114:115], v[226:227], s[30:31], v[114:115] op_sel_hi:[1,0,1]
	v_pk_fma_f32 v[116:117], v[228:229], s[30:31], v[116:117] op_sel_hi:[1,0,1]
	v_pk_fma_f32 v[118:119], v[230:231], s[30:31], v[118:119] op_sel_hi:[1,0,1]
	v_pk_fma_f32 v[120:121], v[232:233], s[30:31], v[120:121] op_sel_hi:[1,0,1]
	v_pk_fma_f32 v[122:123], v[234:235], s[30:31], v[122:123] op_sel_hi:[1,0,1]
	v_pk_fma_f32 v[124:125], v[236:237], s[30:31], v[124:125] op_sel_hi:[1,0,1]
	v_pk_fma_f32 v[126:127], v[238:239], s[30:31], v[126:127] op_sel_hi:[1,0,1]
	s_mov_b32 s72, s80
	s_mov_b32 s73, s81
	s_mov_b32 s74, s82
	s_mov_b32 s75, s83
	s_mov_b32 s76, s84
	s_mov_b32 s77, s85
	s_mov_b32 s78, s86
	s_mov_b32 s79, s87
	s_add_u32 s80, s80, 8
	s_add_u32 s81, s81, 8
	s_add_u32 s82, s82, 8
	s_add_u32 s83, s83, 8
	s_add_u32 s84, s84, 8
	s_add_u32 s85, s85, 8
	s_add_u32 s86, s86, 8
	s_add_u32 s87, s87, 8
	s_and_b32 s80, s80, 63
	s_and_b32 s81, s81, 63
	s_and_b32 s82, s82, 63
	s_and_b32 s83, s83, 63
	s_and_b32 s84, s84, 63
	s_and_b32 s85, s85, 63
	s_and_b32 s86, s86, 63
	s_and_b32 s87, s87, 63
	s_add_u32 s12, s12, 1
	s_cmp_lt_u32 s12, 8
	s_cbranch_scc1 .Lvq_kB
; DI void peer_item_v(const Params& p, int item) {
;     ...
;     float* orow = p.out + tok * 1024 + lane * 4;
;     float4 y[4];
;     float ss = 0.f;
; #pragma unroll
;     for (int i = 0; i < 4; ++i) {
;       y[i] = *(const float4*)(orow + 256 * i);
;       y[i].x += out[4 * i]; y[i].y += out[4 * i + 1]; y[i].z += out[4 * i + 2]; y[i].w += out[4 * i + 3];
;       ss += y[i].x * y[i].x + y[i].y * y[i].y + y[i].z * y[i].z + y[i].w * y[i].w;
;     }
;     ss = wave_sum(ss);
;     const float r = rsqrtf(ss * (1.f / 1024.f) + 1e-6f);
; #pragma unroll
;     for (int i = 0; i < 4; ++i) {
;       float4 g = *(const float4*)(p.g_final + 256 * i + lane * 4);
;       y[i].x *= r * g.x; y[i].y *= r * g.y; y[i].z *= r * g.z; y[i].w *= r * g.w;
;       *(float4*)(orow + 256 * i) = y[i];
;     }
	s_waitcnt vmcnt(0)
	s_add_u32 s32, s62, 16384
	s_addc_u32 s33, s63, 0
	s_add_u32 s34, s62, 20480
	s_addc_u32 s35, s63, 0
	s_add_u32 s36, s62, 24576
	s_addc_u32 s37, s63, 0
	s_add_u32 s38, s62, 28672
	s_addc_u32 s39, s63, 0
	global_load_dwordx4 v[0:3], v240, s[32:33]
	global_load_dwordx4 v[4:7], v240, s[32:33] offset:1024
	global_load_dwordx4 v[8:11], v240, s[32:33] offset:2048
	global_load_dwordx4 v[12:15], v240, s[32:33] offset:3072
	global_load_dwordx4 v[16:19], v240, s[34:35]
	global_load_dwordx4 v[20:23], v240, s[34:35] offset:1024
	global_load_dwordx4 v[24:27], v240, s[34:35] offset:2048
	global_load_dwordx4 v[28:31], v240, s[34:35] offset:3072
	global_load_dwordx4 v[32:35], v240, s[36:37]
	global_load_dwordx4 v[36:39], v240, s[36:37] offset:1024
	global_load_dwordx4 v[40:43], v240, s[36:37] offset:2048
	global_load_dwordx4 v[44:47], v240, s[36:37] offset:3072
	global_load_dwordx4 v[48:51], v240, s[38:39]
	global_load_dwordx4 v[52:55], v240, s[38:39] offset:1024
	global_load_dwordx4 v[56:59], v240, s[38:39] offset:2048
	global_load_dwordx4 v[60:63], v240, s[38:39] offset:3072
	s_waitcnt vmcnt(0)
	s_add_u32 s32, s62, 16384
	s_addc_u32 s33, s63, 0
	s_add_u32 s34, s62, 20480
	s_addc_u32 s35, s63, 0
	s_add_u32 s36, s62, 24576
	s_addc_u32 s37, s63, 0
	s_add_u32 s38, s62, 28672
	s_addc_u32 s39, s63, 0
	v_pk_add_f32 v[0:1], v[0:1], v[64:65]
	v_pk_add_f32 v[2:3], v[2:3], v[66:67]
	v_pk_add_f32 v[4:5], v[4:5], v[68:69]
	v_pk_add_f32 v[6:7], v[6:7], v[70:71]
	v_pk_add_f32 v[8:9], v[8:9], v[72:73]
	v_pk_add_f32 v[10:11], v[10:11], v[74:75]
	v_pk_add_f32 v[12:13], v[12:13], v[76:77]
	v_pk_add_f32 v[14:15], v[14:15], v[78:79]
	v_pk_mul_f32 v[224:225], v[0:1], v[0:1]
	v_pk_mul_f32 v[226:227], v[2:3], v[2:3]
	v_pk_fma_f32 v[224:225], v[4:5], v[4:5], v[224:225]
	v_pk_fma_f32 v[226:227], v[6:7], v[6:7], v[226:227]
	v_pk_fma_f32 v[224:225], v[8:9], v[8:9], v[224:225]
	v_pk_fma_f32 v[226:227], v[10:11], v[10:11], v[226:227]
	v_pk_fma_f32 v[224:225], v[12:13], v[12:13], v[224:225]
	v_pk_fma_f32 v[226:227], v[14:15], v[14:15], v[226:227]
	v_pk_add_f32 v[224:225], v[224:225], v[226:227]
	s_nop 0
	v_add_f32_e32 v224, v224, v225
	ds_bpermute_b32 v225, v242, v224
	s_waitcnt lgkmcnt(0)
	v_add_f32_e32 v224, v224, v225
	ds_bpermute_b32 v225, v243, v224
	s_waitcnt lgkmcnt(0)
	v_add_f32_e32 v224, v224, v225
	ds_bpermute_b32 v225, v244, v224
	s_waitcnt lgkmcnt(0)
	v_add_f32_e32 v224, v224, v225
	ds_bpermute_b32 v225, v245, v224
	s_waitcnt lgkmcnt(0)
	v_add_f32_e32 v224, v224, v225
	ds_bpermute_b32 v225, v246, v224
	s_waitcnt lgkmcnt(0)
	v_add_f32_e32 v224, v224, v225
	ds_bpermute_b32 v225, v247, v224
	s_waitcnt lgkmcnt(0)
	v_add_f32_e32 v224, v224, v225
	v_fmamk_f32 v224, v224, 0x3a800000, v248
	v_rsq_f32_e32 v224, v224
	s_nop 1
	v_pk_mul_f32 v[226:227], v[128:129], v[224:225] op_sel_hi:[1,0]
	v_pk_mul_f32 v[0:1], v[0:1], v[226:227]
	v_pk_mul_f32 v[228:229], v[130:131], v[224:225] op_sel_hi:[1,0]
	v_pk_mul_f32 v[2:3], v[2:3], v[228:229]
	v_pk_mul_f32 v[230:231], v[132:133], v[224:225] op_sel_hi:[1,0]
	v_pk_mul_f32 v[4:5], v[4:5], v[230:231]
	v_pk_mul_f32 v[232:233], v[134:135], v[224:225] op_sel_hi:[1,0]
	v_pk_mul_f32 v[6:7], v[6:7], v[232:233]
	v_pk_mul_f32 v[226:227], v[136:137], v[224:225] op_sel_hi:[1,0]
	v_pk_mul_f32 v[8:9], v[8:9], v[226:227]
	v_pk_mul_f32 v[228:229], v[138:139], v[224:225] op_sel_hi:[1,0]
	v_pk_mul_f32 v[10:11], v[10:11], v[228:229]
	v_pk_mul_f32 v[230:231], v[140:141], v[224:225] op_sel_hi:[1,0]
	v_pk_mul_f32 v[12:13], v[12:13], v[230:231]
	v_pk_mul_f32 v[232:233], v[142:143], v[224:225] op_sel_hi:[1,0]
	v_pk_mul_f32 v[14:15], v[14:15], v[232:233]
	v_pk_add_f32 v[16:17], v[16:17], v[80:81]
	v_pk_add_f32 v[18:19], v[18:19], v[82:83]
	v_pk_add_f32 v[20:21], v[20:21], v[84:85]
	v_pk_add_f32 v[22:23], v[22:23], v[86:87]
	v_pk_add_f32 v[24:25], v[24:25], v[88:89]
	v_pk_add_f32 v[26:27], v[26:27], v[90:91]
	v_pk_add_f32 v[28:29], v[28:29], v[92:93]
	v_pk_add_f32 v[30:31], v[30:31], v[94:95]
	v_pk_mul_f32 v[224:225], v[16:17], v[16:17]
	v_pk_mul_f32 v[226:227], v[18:19], v[18:19]
	v_pk_fma_f32 v[224:225], v[20:21], v[20:21], v[224:225]
	v_pk_fma_f32 v[226:227], v[22:23], v[22:23], v[226:227]
	v_pk_fma_f32 v[224:225], v[24:25], v[24:25], v[224:225]
	v_pk_fma_f32 v[226:227], v[26:27], v[26:27], v[226:227]
	v_pk_fma_f32 v[224:225], v[28:29], v[28:29], v[224:225]
	v_pk_fma_f32 v[226:227], v[30:31], v[30:31], v[226:227]
	v_pk_add_f32 v[224:225], v[224:225], v[226:227]
	s_nop 0
	v_add_f32_e32 v224, v224, v225
	ds_bpermute_b32 v225, v242, v224
	s_waitcnt lgkmcnt(0)
	v_add_f32_e32 v224, v224, v225
	ds_bpermute_b32 v225, v243, v224
	s_waitcnt lgkmcnt(0)
	v_add_f32_e32 v224, v224, v225
	ds_bpermute_b32 v225, v244, v224
	s_waitcnt lgkmcnt(0)
	v_add_f32_e32 v224, v224, v225
	ds_bpermute_b32 v225, v245, v224
	s_waitcnt lgkmcnt(0)
	v_add_f32_e32 v224, v224, v225
	ds_bpermute_b32 v225, v246, v224
	s_waitcnt lgkmcnt(0)
	v_add_f32_e32 v224, v224, v225
	ds_bpermute_b32 v225, v247, v224
	s_waitcnt lgkmcnt(0)
; DI int vb_id() { return (int)blockIdx.x + half_id() * (int)gridDim.x; }
; DI int vb_n() { return (int)gridDim.x * 2; }
; DI void peer_item_v(const Params& p, int item) {
;     ...
;     ss = wave_sum(ss);
;     const float r = rsqrtf(ss * (1.f / 1024.f) + 1e-6f);
; #pragma unroll
;     for (int i = 0; i < 4; ++i) {
;       float4 g = *(const float4*)(p.g_final + 256 * i + lane * 4);
;       y[i].x *= r * g.x; y[i].y *= r * g.y; y[i].z *= r * g.z; y[i].w *= r * g.w;
;       *(float4*)(orow + 256 * i) = y[i];
;     }
;   }
; }
; template <bool STORE>
; DI void phase_peer(const Params& p, char* smem) {
;   for (int it = vb_id(); it < 512; it += vb_n()) peer_item<STORE>(p, it, smem);
; }
; DI void phase_peer_v(const Params& p) {
;   for (int it = vb_id(); it < 512; it += vb_n()) peer_item_v(p, it);
	v_add_f32_e32 v224, v224, v225
	v_fmamk_f32 v224, v224, 0x3a800000, v248
	v_rsq_f32_e32 v224, v224
	s_nop 1
	v_pk_mul_f32 v[226:227], v[128:129], v[224:225] op_sel_hi:[1,0]
	v_pk_mul_f32 v[16:17], v[16:17], v[226:227]
	v_pk_mul_f32 v[228:229], v[130:131], v[224:225] op_sel_hi:[1,0]
	v_pk_mul_f32 v[18:19], v[18:19], v[228:229]
	v_pk_mul_f32 v[230:231], v[132:133], v[224:225] op_sel_hi:[1,0]
	v_pk_mul_f32 v[20:21], v[20:21], v[230:231]
	v_pk_mul_f32 v[232:233], v[134:135], v[224:225] op_sel_hi:[1,0]
	v_pk_mul_f32 v[22:23], v[22:23], v[232:233]
	v_pk_mul_f32 v[226:227], v[136:137], v[224:225] op_sel_hi:[1,0]
	v_pk_mul_f32 v[24:25], v[24:25], v[226:227]
	v_pk_mul_f32 v[228:229], v[138:139], v[224:225] op_sel_hi:[1,0]
	v_pk_mul_f32 v[26:27], v[26:27], v[228:229]
	v_pk_mul_f32 v[230:231], v[140:141], v[224:225] op_sel_hi:[1,0]
	v_pk_mul_f32 v[28:29], v[28:29], v[230:231]
	v_pk_mul_f32 v[232:233], v[142:143], v[224:225] op_sel_hi:[1,0]
	v_pk_mul_f32 v[30:31], v[30:31], v[232:233]
	v_pk_add_f32 v[32:33], v[32:33], v[96:97]
	v_pk_add_f32 v[34:35], v[34:35], v[98:99]
	v_pk_add_f32 v[36:37], v[36:37], v[100:101]
	v_pk_add_f32 v[38:39], v[38:39], v[102:103]
	v_pk_add_f32 v[40:41], v[40:41], v[104:105]
	v_pk_add_f32 v[42:43], v[42:43], v[106:107]
	v_pk_add_f32 v[44:45], v[44:45], v[108:109]
	v_pk_add_f32 v[46:47], v[46:47], v[110:111]
	v_pk_mul_f32 v[224:225], v[32:33], v[32:33]
	v_pk_mul_f32 v[226:227], v[34:35], v[34:35]
	v_pk_fma_f32 v[224:225], v[36:37], v[36:37], v[224:225]
	v_pk_fma_f32 v[226:227], v[38:39], v[38:39], v[226:227]
	v_pk_fma_f32 v[224:225], v[40:41], v[40:41], v[224:225]
	v_pk_fma_f32 v[226:227], v[42:43], v[42:43], v[226:227]
	v_pk_fma_f32 v[224:225], v[44:45], v[44:45], v[224:225]
	v_pk_fma_f32 v[226:227], v[46:47], v[46:47], v[226:227]
	v_pk_add_f32 v[224:225], v[224:225], v[226:227]
	s_nop 0
	v_add_f32_e32 v224, v224, v225
	ds_bpermute_b32 v225, v242, v224
	s_waitcnt lgkmcnt(0)
	v_add_f32_e32 v224, v224, v225
	ds_bpermute_b32 v225, v243, v224
	s_waitcnt lgkmcnt(0)
	v_add_f32_e32 v224, v224, v225
	ds_bpermute_b32 v225, v244, v224
	s_waitcnt lgkmcnt(0)
	v_add_f32_e32 v224, v224, v225
	ds_bpermute_b32 v225, v245, v224
	s_waitcnt lgkmcnt(0)
	v_add_f32_e32 v224, v224, v225
	ds_bpermute_b32 v225, v246, v224
	s_waitcnt lgkmcnt(0)
	v_add_f32_e32 v224, v224, v225
	ds_bpermute_b32 v225, v247, v224
	s_waitcnt lgkmcnt(0)
	v_add_f32_e32 v224, v224, v225
	v_fmamk_f32 v224, v224, 0x3a800000, v248
	v_rsq_f32_e32 v224, v224
	s_nop 1
	v_pk_mul_f32 v[226:227], v[128:129], v[224:225] op_sel_hi:[1,0]
	v_pk_mul_f32 v[32:33], v[32:33], v[226:227]
	v_pk_mul_f32 v[228:229], v[130:131], v[224:225] op_sel_hi:[1,0]
	v_pk_mul_f32 v[34:35], v[34:35], v[228:229]
	v_pk_mul_f32 v[230:231], v[132:133], v[224:225] op_sel_hi:[1,0]
	v_pk_mul_f32 v[36:37], v[36:37], v[230:231]
	v_pk_mul_f32 v[232:233], v[134:135], v[224:225] op_sel_hi:[1,0]
	v_pk_mul_f32 v[38:39], v[38:39], v[232:233]
	v_pk_mul_f32 v[226:227], v[136:137], v[224:225] op_sel_hi:[1,0]
	v_pk_mul_f32 v[40:41], v[40:41], v[226:227]
	v_pk_mul_f32 v[228:229], v[138:139], v[224:225] op_sel_hi:[1,0]
	v_pk_mul_f32 v[42:43], v[42:43], v[228:229]
	v_pk_mul_f32 v[230:231], v[140:141], v[224:225] op_sel_hi:[1,0]
	v_pk_mul_f32 v[44:45], v[44:45], v[230:231]
	v_pk_mul_f32 v[232:233], v[142:143], v[224:225] op_sel_hi:[1,0]
	v_pk_mul_f32 v[46:47], v[46:47], v[232:233]
	v_pk_add_f32 v[48:49], v[48:49], v[112:113]
	v_pk_add_f32 v[50:51], v[50:51], v[114:115]
	v_pk_add_f32 v[52:53], v[52:53], v[116:117]
	v_pk_add_f32 v[54:55], v[54:55], v[118:119]
	v_pk_add_f32 v[56:57], v[56:57], v[120:121]
	v_pk_add_f32 v[58:59], v[58:59], v[122:123]
	v_pk_add_f32 v[60:61], v[60:61], v[124:125]
	v_pk_add_f32 v[62:63], v[62:63], v[126:127]
	v_pk_mul_f32 v[224:225], v[48:49], v[48:49]
	v_pk_mul_f32 v[226:227], v[50:51], v[50:51]
	v_pk_fma_f32 v[224:225], v[52:53], v[52:53], v[224:225]
	v_pk_fma_f32 v[226:227], v[54:55], v[54:55], v[226:227]
	v_pk_fma_f32 v[224:225], v[56:57], v[56:57], v[224:225]
	v_pk_fma_f32 v[226:227], v[58:59], v[58:59], v[226:227]
	v_pk_fma_f32 v[224:225], v[60:61], v[60:61], v[224:225]
	v_pk_fma_f32 v[226:227], v[62:63], v[62:63], v[226:227]
	v_pk_add_f32 v[224:225], v[224:225], v[226:227]
	s_nop 0
	v_add_f32_e32 v224, v224, v225
	ds_bpermute_b32 v225, v242, v224
	s_waitcnt lgkmcnt(0)
	v_add_f32_e32 v224, v224, v225
	ds_bpermute_b32 v225, v243, v224
	s_waitcnt lgkmcnt(0)
	v_add_f32_e32 v224, v224, v225
	ds_bpermute_b32 v225, v244, v224
	s_waitcnt lgkmcnt(0)
	v_add_f32_e32 v224, v224, v225
	ds_bpermute_b32 v225, v245, v224
	s_waitcnt lgkmcnt(0)
	v_add_f32_e32 v224, v224, v225
	ds_bpermute_b32 v225, v246, v224
	s_waitcnt lgkmcnt(0)
	v_add_f32_e32 v224, v224, v225
	ds_bpermute_b32 v225, v247, v224
	s_waitcnt lgkmcnt(0)
	v_add_f32_e32 v224, v224, v225
	v_fmamk_f32 v224, v224, 0x3a800000, v248
	v_rsq_f32_e32 v224, v224
	s_nop 1
	v_pk_mul_f32 v[226:227], v[128:129], v[224:225] op_sel_hi:[1,0]
	v_pk_mul_f32 v[48:49], v[48:49], v[226:227]
	v_pk_mul_f32 v[228:229], v[130:131], v[224:225] op_sel_hi:[1,0]
	v_pk_mul_f32 v[50:51], v[50:51], v[228:229]
	v_pk_mul_f32 v[230:231], v[132:133], v[224:225] op_sel_hi:[1,0]
	v_pk_mul_f32 v[52:53], v[52:53], v[230:231]
	v_pk_mul_f32 v[232:233], v[134:135], v[224:225] op_sel_hi:[1,0]
	v_pk_mul_f32 v[54:55], v[54:55], v[232:233]
	v_pk_mul_f32 v[226:227], v[136:137], v[224:225] op_sel_hi:[1,0]
	v_pk_mul_f32 v[56:57], v[56:57], v[226:227]
	v_pk_mul_f32 v[228:229], v[138:139], v[224:225] op_sel_hi:[1,0]
	v_pk_mul_f32 v[58:59], v[58:59], v[228:229]
	v_pk_mul_f32 v[230:231], v[140:141], v[224:225] op_sel_hi:[1,0]
	v_pk_mul_f32 v[60:61], v[60:61], v[230:231]
	v_pk_mul_f32 v[232:233], v[142:143], v[224:225] op_sel_hi:[1,0]
	v_pk_mul_f32 v[62:63], v[62:63], v[232:233]
	global_store_dwordx4 v240, v[0:3], s[32:33]
	global_store_dwordx4 v240, v[4:7], s[32:33] offset:1024
	global_store_dwordx4 v240, v[8:11], s[32:33] offset:2048
	global_store_dwordx4 v240, v[12:15], s[32:33] offset:3072
	global_store_dwordx4 v240, v[16:19], s[34:35]
	global_store_dwordx4 v240, v[20:23], s[34:35] offset:1024
	global_store_dwordx4 v240, v[24:27], s[34:35] offset:2048
	global_store_dwordx4 v240, v[28:31], s[34:35] offset:3072
	global_store_dwordx4 v240, v[32:35], s[36:37]
	global_store_dwordx4 v240, v[36:39], s[36:37] offset:1024
	global_store_dwordx4 v240, v[40:43], s[36:37] offset:2048
	global_store_dwordx4 v240, v[44:47], s[36:37] offset:3072
	global_store_dwordx4 v240, v[48:51], s[38:39]
	global_store_dwordx4 v240, v[52:55], s[38:39] offset:1024
	global_store_dwordx4 v240, v[56:59], s[38:39] offset:2048
	global_store_dwordx4 v240, v[60:63], s[38:39] offset:3072
	s_nop 1
	s_add_i32 s10, s10, s11
	s_cmpk_lt_i32 s10, 0x200
	s_cbranch_scc1 .Lvq_item
